# GEMM K-loops: per-phase s_setprio 1/0 flips removed (all six mainloops)
# speedup vs baseline: 1.0401x; 1.0133x over previous
; #define PG8_STAGE(bufoff, gbase, voff) do { _Pragma("unroll") for (int _i = 0; _i < 2; ++_i) \
;         __builtin_amdgcn_global_load_lds((const unsigned*)((const char*)(gbase) + (voff)[_i]), (LAS unsigned*)(lds + (bufoff) + ldsw + _i * 8192), 16, 0, 0); } while (0)
; #define PG8_LDA(dst, b, h) do { _Pragma("unroll") for (int m = 0; m < 4; ++m) _Pragma("unroll") for (int k = 0; k < 2; ++k) dst[m][k] = *(const LAS bf16x8*)(lds + PG8_SA(b, h) + aoff + m * 2048 + k * 1024); } while (0)
; #define PG8_LDB(dst, b, h) do { _Pragma("unroll") for (int n = 0; n < 2; ++n) _Pragma("unroll") for (int k = 0; k < 2; ++k) dst[n][k] = *(const LAS bf16x8*)(lds + PG8_SB(b, h) + boff + n * 2048 + k * 1024); } while (0)
; #define PG8_MMA(ai, bj, At, Bt) do { __builtin_amdgcn_s_setprio(1); _Pragma("unroll") for (int m = 0; m < 4; ++m) _Pragma("unroll") for (int n = 0; n < 2; ++n) _Pragma("unroll") for (int k = 0; k < 2; ++k) \
;         acc[ai][bj][m][n] = __builtin_amdgcn_mfma_f32_16x16x32_bf16(Bt[n][k], At[m][k], acc[ai][bj][m][n], 0, 0, 0); __builtin_amdgcn_s_setprio(0); } while (0)
; #define PG8_WAIT_L(n) asm volatile("s_waitcnt lgkmcnt(" #n ")" ::: "memory")
; #define PG8_BAR __builtin_amdgcn_s_barrier()
; #define PG8_SCHED __builtin_amdgcn_sched_barrier(0)
; template <class Epi, bool KS0 = false>
; __device__ __forceinline__ void gemm_phase(const int WID, LAS unsigned char* lds, const Gemm g, const StaticOrder& S, const Epi& E) {
;     ...
;         for (int t = 0; t < nt; t += 2) {
;             const bool last = (t == nt - 2);
;             const char* a1 = cA + (size_t)(t + 1) * kstep;
;             const char* a2 = last ? nA : cA + (size_t)(t + 2) * kstep; const char* b2 = last ? nB : cB + (size_t)(t + 2) * kstep;
;             const char* a3 = a2 + kstep; const char* b3 = b2 + kstep;
;             PG8_LDB(B0, 0, 0); PG8_SCHED; PG8_LDA(At, 0, 0); PG8_STAGE(PG8_SA(1, 1), a1 + hstep, voffA);
;             PG8_WAIT_L(8); PG8_BAR; PG8_WAIT_L(0); PG8_MMA(0, 0, At, B0); PG8_BAR; PG8_SCHED;
;             PG8_LDB(B1, 0, 1); PG8_STAGE(PG8_SB(0, 0), b2, voffB);
;             PG8_BAR; PG8_WAIT_L(0); PG8_MMA(0, 1, At, B1); PG8_BAR;
;             PG8_LDA(At, 0, 1); PG8_STAGE(PG8_SA(0, 0), a2, voffA);
;             PG8_BAR; PG8_WAIT_L(0); PG8_MMA(1, 0, At, B0); PG8_BAR; PG8_SCHED;
.LBB0_86:
	ds_read_b128 v[152:155], v148
	ds_read_b128 v[156:159], v148 offset:1024
	ds_read_b128 v[160:163], v148 offset:2048
	ds_read_b128 v[164:167], v148 offset:3072
	s_add_u32 s22, s20, 0xfff80080
	s_addc_u32 s23, s21, -1
	s_cmp_eq_u32 s50, 28
	s_cselect_b32 s25, s15, s23
	s_cselect_b32 s24, s46, s22
	s_cselect_b32 s23, s13, s49
	s_cselect_b32 s22, s47, s48
	v_lshl_add_u64 v[144:145], s[20:21], 0, v[136:137]
	s_add_i32 m0, s34, 0xc000
	ds_read_b128 v[168:171], v149
	ds_read_b128 v[172:175], v149 offset:1024
	ds_read_b128 v[176:179], v149 offset:2048
	ds_read_b128 v[180:183], v149 offset:3072
	ds_read_b128 v[184:187], v149 offset:4096
	ds_read_b128 v[188:191], v149 offset:5120
	ds_read_b128 v[192:195], v149 offset:6144
	ds_read_b128 v[196:199], v149 offset:7168
	global_load_lds_dwordx4 v[144:145], off
	v_lshl_add_u64 v[144:145], s[20:21], 0, v[138:139]
	s_add_i32 m0, s34, 0xe000
	s_nop 0
	global_load_lds_dwordx4 v[144:145], off
	s_waitcnt lgkmcnt(8)
	s_barrier
	s_waitcnt lgkmcnt(0)
	s_waitcnt lgkmcnt(0)
	v_mfma_f32_16x16x32_bf16 v[124:127], v[152:155], v[168:171], v[124:127]
	v_mfma_f32_16x16x32_bf16 v[120:123], v[160:163], v[168:171], v[120:123]
	v_mfma_f32_16x16x32_bf16 v[112:115], v[152:155], v[176:179], v[112:115]
	v_mfma_f32_16x16x32_bf16 v[104:107], v[160:163], v[176:179], v[104:107]
	v_mfma_f32_16x16x32_bf16 v[100:103], v[152:155], v[184:187], v[100:103]
	v_mfma_f32_16x16x32_bf16 v[92:95], v[160:163], v[184:187], v[92:95]
	v_mfma_f32_16x16x32_bf16 v[84:87], v[152:155], v[192:195], v[84:87]
	v_mfma_f32_16x16x32_bf16 v[76:79], v[160:163], v[192:195], v[76:79]
	v_mfma_f32_16x16x32_bf16 v[124:127], v[156:159], v[172:175], v[124:127]
	v_mfma_f32_16x16x32_bf16 v[120:123], v[164:167], v[172:175], v[120:123]
	v_mfma_f32_16x16x32_bf16 v[112:115], v[156:159], v[180:183], v[112:115]
	v_mfma_f32_16x16x32_bf16 v[104:107], v[164:167], v[180:183], v[104:107]
	v_mfma_f32_16x16x32_bf16 v[100:103], v[156:159], v[188:191], v[100:103]
	v_mfma_f32_16x16x32_bf16 v[92:95], v[164:167], v[188:191], v[92:95]
	v_mfma_f32_16x16x32_bf16 v[84:87], v[156:159], v[196:199], v[84:87]
	v_mfma_f32_16x16x32_bf16 v[76:79], v[164:167], v[196:199], v[76:79]
	s_barrier
	s_add_i32 s51, s42, s26
	v_lshl_add_u64 v[144:145], s[22:23], 0, v[132:133]
	s_mov_b32 m0, s51
	ds_read_b128 v[200:203], v150
	ds_read_b128 v[204:207], v150 offset:1024
	ds_read_b128 v[208:211], v150 offset:2048
	ds_read_b128 v[212:215], v150 offset:3072
	global_load_lds_dwordx4 v[144:145], off
	v_lshl_add_u64 v[216:217], s[22:23], 0, v[128:129]
	s_add_i32 m0, s51, 0x2000
	s_nop 0
	global_load_lds_dwordx4 v[216:217], off
	s_barrier
	s_waitcnt lgkmcnt(0)
	s_waitcnt lgkmcnt(0)
	v_mfma_f32_16x16x32_bf16 v[116:119], v[200:203], v[168:171], v[116:119]
	v_mfma_f32_16x16x32_bf16 v[108:111], v[208:211], v[168:171], v[108:111]
	v_mfma_f32_16x16x32_bf16 v[96:99], v[200:203], v[176:179], v[96:99]
	v_mfma_f32_16x16x32_bf16 v[88:91], v[208:211], v[176:179], v[88:91]
	v_mfma_f32_16x16x32_bf16 v[80:83], v[200:203], v[184:187], v[80:83]
	v_mfma_f32_16x16x32_bf16 v[72:75], v[208:211], v[184:187], v[72:75]
	v_mfma_f32_16x16x32_bf16 v[68:71], v[200:203], v[192:195], v[68:71]
	v_mfma_f32_16x16x32_bf16 v[64:67], v[208:211], v[192:195], v[64:67]
	v_mfma_f32_16x16x32_bf16 v[116:119], v[204:207], v[172:175], v[116:119]
	v_mfma_f32_16x16x32_bf16 v[108:111], v[212:215], v[172:175], v[108:111]
	v_mfma_f32_16x16x32_bf16 v[96:99], v[204:207], v[180:183], v[96:99]
	v_mfma_f32_16x16x32_bf16 v[88:91], v[212:215], v[180:183], v[88:91]
	v_mfma_f32_16x16x32_bf16 v[80:83], v[204:207], v[188:191], v[80:83]
	v_mfma_f32_16x16x32_bf16 v[72:75], v[212:215], v[188:191], v[72:75]
	v_mfma_f32_16x16x32_bf16 v[68:71], v[204:207], v[196:199], v[68:71]
	v_mfma_f32_16x16x32_bf16 v[64:67], v[212:215], v[196:199], v[64:67]
	s_mov_b32 m0, s34
	v_lshl_add_u64 v[218:219], s[24:25], 0, v[134:135]
	s_barrier
	ds_read_b128 v[168:171], v149 offset:16384
	ds_read_b128 v[172:175], v149 offset:17408
	ds_read_b128 v[176:179], v149 offset:18432
	ds_read_b128 v[180:183], v149 offset:19456
	ds_read_b128 v[184:187], v149 offset:20480
	ds_read_b128 v[188:191], v149 offset:21504
	ds_read_b128 v[192:195], v149 offset:22528
	ds_read_b128 v[196:199], v149 offset:23552
	global_load_lds_dwordx4 v[218:219], off
	v_lshl_add_u64 v[220:221], s[24:25], 0, v[130:131]
	s_mov_b32 m0, s35
	s_nop 0
	global_load_lds_dwordx4 v[220:221], off
	s_barrier
	s_waitcnt lgkmcnt(0)
	s_waitcnt lgkmcnt(0)
	v_mfma_f32_16x16x32_bf16 v[60:63], v[152:155], v[168:171], v[60:63]
	v_mfma_f32_16x16x32_bf16 v[56:59], v[160:163], v[168:171], v[56:59]
	v_mfma_f32_16x16x32_bf16 v[52:55], v[152:155], v[176:179], v[52:55]
	v_mfma_f32_16x16x32_bf16 v[44:47], v[160:163], v[176:179], v[44:47]
	v_mfma_f32_16x16x32_bf16 v[36:39], v[152:155], v[184:187], v[36:39]
	v_mfma_f32_16x16x32_bf16 v[28:31], v[160:163], v[184:187], v[28:31]
	v_mfma_f32_16x16x32_bf16 v[20:23], v[152:155], v[192:195], v[20:23]
	v_mfma_f32_16x16x32_bf16 v[12:15], v[160:163], v[192:195], v[12:15]
	v_mfma_f32_16x16x32_bf16 v[60:63], v[156:159], v[172:175], v[60:63]
	v_mfma_f32_16x16x32_bf16 v[56:59], v[164:167], v[172:175], v[56:59]
	v_mfma_f32_16x16x32_bf16 v[52:55], v[156:159], v[180:183], v[52:55]
	v_mfma_f32_16x16x32_bf16 v[44:47], v[164:167], v[180:183], v[44:47]
	v_mfma_f32_16x16x32_bf16 v[36:39], v[156:159], v[188:191], v[36:39]
	v_mfma_f32_16x16x32_bf16 v[28:31], v[164:167], v[188:191], v[28:31]
	v_mfma_f32_16x16x32_bf16 v[20:23], v[156:159], v[196:199], v[20:23]
	v_mfma_f32_16x16x32_bf16 v[12:15], v[164:167], v[196:199], v[12:15]
	s_barrier
; #define PG8_STAGE(bufoff, gbase, voff) do { _Pragma("unroll") for (int _i = 0; _i < 2; ++_i) \
;         __builtin_amdgcn_global_load_lds((const unsigned*)((const char*)(gbase) + (voff)[_i]), (LAS unsigned*)(lds + (bufoff) + ldsw + _i * 8192), 16, 0, 0); } while (0)
; #define PG8_LDA(dst, b, h) do { _Pragma("unroll") for (int m = 0; m < 4; ++m) _Pragma("unroll") for (int k = 0; k < 2; ++k) dst[m][k] = *(const LAS bf16x8*)(lds + PG8_SA(b, h) + aoff + m * 2048 + k * 1024); } while (0)
; #define PG8_LDB(dst, b, h) do { _Pragma("unroll") for (int n = 0; n < 2; ++n) _Pragma("unroll") for (int k = 0; k < 2; ++k) dst[n][k] = *(const LAS bf16x8*)(lds + PG8_SB(b, h) + boff + n * 2048 + k * 1024); } while (0)
; #define PG8_MMA(ai, bj, At, Bt) do { __builtin_amdgcn_s_setprio(1); _Pragma("unroll") for (int m = 0; m < 4; ++m) _Pragma("unroll") for (int n = 0; n < 2; ++n) _Pragma("unroll") for (int k = 0; k < 2; ++k) \
;         acc[ai][bj][m][n] = __builtin_amdgcn_mfma_f32_16x16x32_bf16(Bt[n][k], At[m][k], acc[ai][bj][m][n], 0, 0, 0); __builtin_amdgcn_s_setprio(0); } while (0)
; #define PG8_WAIT_V(n) asm volatile("s_waitcnt vmcnt(" #n ")" ::: "memory")
; #define PG8_WAIT_L(n) asm volatile("s_waitcnt lgkmcnt(" #n ")" ::: "memory")
; #define PG8_BAR __builtin_amdgcn_s_barrier()
; #define PG8_SCHED __builtin_amdgcn_sched_barrier(0)
; template <class Epi, bool KS0 = false>
; __device__ __forceinline__ void gemm_phase(const int WID, LAS unsigned char* lds, const Gemm g, const StaticOrder& S, const Epi& E) {
;     ...
;             PG8_STAGE(PG8_SB(0, 1), b2 + hstep, voffB);
;             PG8_WAIT_V(6); PG8_BAR; PG8_MMA(1, 1, At, B1); PG8_BAR;
;             PG8_LDB(B0, 1, 0); PG8_SCHED; PG8_LDA(At, 1, 0); PG8_STAGE(PG8_SA(0, 1), a2 + hstep, voffA);
;             PG8_WAIT_L(8); PG8_BAR; PG8_WAIT_L(0); PG8_MMA(0, 0, At, B0); PG8_BAR; PG8_SCHED;
;             PG8_LDB(B1, 1, 1); PG8_STAGE(PG8_SB(1, 0), b3, voffB);
;             PG8_BAR; PG8_WAIT_L(0); PG8_MMA(0, 1, At, B1); PG8_BAR;
	s_add_u32 s52, s22, 0x80000
	s_addc_u32 s53, s23, 0
	s_add_i32 s51, s43, s26
	v_lshl_add_u64 v[152:153], s[52:53], 0, v[132:133]
	s_mov_b32 m0, s51
	s_nop 0
	global_load_lds_dwordx4 v[152:153], off
	v_lshl_add_u64 v[152:153], s[52:53], 0, v[128:129]
	s_add_i32 m0, s51, 0x2000
	s_nop 0
	global_load_lds_dwordx4 v[152:153], off
	s_waitcnt vmcnt(6)
	s_barrier
	v_mfma_f32_16x16x32_bf16 v[48:51], v[200:203], v[168:171], v[48:51]
	v_mfma_f32_16x16x32_bf16 v[40:43], v[208:211], v[168:171], v[40:43]
	v_mfma_f32_16x16x32_bf16 v[32:35], v[200:203], v[176:179], v[32:35]
	v_mfma_f32_16x16x32_bf16 v[24:27], v[208:211], v[176:179], v[24:27]
	v_mfma_f32_16x16x32_bf16 v[16:19], v[200:203], v[184:187], v[16:19]
	v_mfma_f32_16x16x32_bf16 v[8:11], v[208:211], v[184:187], v[8:11]
	v_mfma_f32_16x16x32_bf16 v[4:7], v[200:203], v[192:195], v[4:7]
	v_mfma_f32_16x16x32_bf16 v[0:3], v[208:211], v[192:195], v[0:3]
	v_mfma_f32_16x16x32_bf16 v[48:51], v[204:207], v[172:175], v[48:51]
	v_mfma_f32_16x16x32_bf16 v[40:43], v[212:215], v[172:175], v[40:43]
	v_mfma_f32_16x16x32_bf16 v[32:35], v[204:207], v[180:183], v[32:35]
	v_mfma_f32_16x16x32_bf16 v[24:27], v[212:215], v[180:183], v[24:27]
	v_mfma_f32_16x16x32_bf16 v[16:19], v[204:207], v[188:191], v[16:19]
	v_mfma_f32_16x16x32_bf16 v[8:11], v[212:215], v[188:191], v[8:11]
	v_mfma_f32_16x16x32_bf16 v[4:7], v[204:207], v[196:199], v[4:7]
	v_mfma_f32_16x16x32_bf16 v[0:3], v[212:215], v[196:199], v[0:3]
	s_add_i32 s51, 0, 0x18000
	v_add_u32_e32 v151, s51, v147
	s_barrier
	ds_read_b128 v[152:155], v151
	ds_read_b128 v[156:159], v151 offset:1024
	ds_read_b128 v[160:163], v151 offset:2048
	ds_read_b128 v[164:167], v151 offset:3072
	s_add_u32 s24, s24, 0x80000
	s_addc_u32 s25, s25, 0
	s_mov_b32 m0, s38
	v_lshl_add_u64 v[200:201], s[24:25], 0, v[134:135]
	ds_read_b128 v[168:171], v149 offset:32768
	ds_read_b128 v[172:175], v149 offset:33792
	ds_read_b128 v[176:179], v149 offset:34816
	ds_read_b128 v[180:183], v149 offset:35840
	ds_read_b128 v[184:187], v149 offset:36864
	ds_read_b128 v[188:191], v149 offset:37888
	ds_read_b128 v[192:195], v149 offset:38912
	ds_read_b128 v[196:199], v149 offset:39936
	global_load_lds_dwordx4 v[200:201], off
	v_lshl_add_u64 v[200:201], s[24:25], 0, v[130:131]
	s_mov_b32 m0, s39
	s_nop 0
	global_load_lds_dwordx4 v[200:201], off
	s_waitcnt lgkmcnt(8)
	s_barrier
	s_waitcnt lgkmcnt(0)
	s_waitcnt lgkmcnt(0)
	v_mfma_f32_16x16x32_bf16 v[124:127], v[152:155], v[168:171], v[124:127]
	v_mfma_f32_16x16x32_bf16 v[120:123], v[160:163], v[168:171], v[120:123]
	v_mfma_f32_16x16x32_bf16 v[112:115], v[152:155], v[176:179], v[112:115]
	v_mfma_f32_16x16x32_bf16 v[104:107], v[160:163], v[176:179], v[104:107]
	v_mfma_f32_16x16x32_bf16 v[100:103], v[152:155], v[184:187], v[100:103]
	v_mfma_f32_16x16x32_bf16 v[92:95], v[160:163], v[184:187], v[92:95]
	v_mfma_f32_16x16x32_bf16 v[84:87], v[152:155], v[192:195], v[84:87]
	v_mfma_f32_16x16x32_bf16 v[76:79], v[160:163], v[192:195], v[76:79]
	v_mfma_f32_16x16x32_bf16 v[124:127], v[156:159], v[172:175], v[124:127]
	v_mfma_f32_16x16x32_bf16 v[120:123], v[164:167], v[172:175], v[120:123]
	v_mfma_f32_16x16x32_bf16 v[112:115], v[156:159], v[180:183], v[112:115]
	v_mfma_f32_16x16x32_bf16 v[104:107], v[164:167], v[180:183], v[104:107]
	v_mfma_f32_16x16x32_bf16 v[100:103], v[156:159], v[188:191], v[100:103]
	v_mfma_f32_16x16x32_bf16 v[92:95], v[164:167], v[188:191], v[92:95]
	v_mfma_f32_16x16x32_bf16 v[84:87], v[156:159], v[196:199], v[84:87]
	v_mfma_f32_16x16x32_bf16 v[76:79], v[164:167], v[196:199], v[76:79]
	s_barrier
	s_add_i32 s24, 0, 0x1c000
	s_add_i32 s25, s51, s26
	v_add_u32_e32 v151, s24, v147
	v_lshl_add_u64 v[144:145], v[144:145], 0, s[8:9]
	s_mov_b32 m0, s25
	ds_read_b128 v[200:203], v151
	ds_read_b128 v[204:207], v151 offset:1024
	ds_read_b128 v[208:211], v151 offset:2048
	ds_read_b128 v[212:215], v151 offset:3072
	global_load_lds_dwordx4 v[144:145], off
	v_lshl_add_u64 v[144:145], v[216:217], 0, s[8:9]
	s_add_i32 m0, s25, 0x2000
	s_nop 0
	global_load_lds_dwordx4 v[144:145], off
	s_barrier
; __device__ __forceinline__ int lane_id_() { int l; asm volatile("v_mbcnt_lo_u32_b32 %0, -1, 0\n\tv_mbcnt_hi_u32_b32 %0, -1, %0" : "=v"(l)); return l; }
; #define PG8_STAGE(bufoff, gbase, voff) do { _Pragma("unroll") for (int _i = 0; _i < 2; ++_i) \
;         __builtin_amdgcn_global_load_lds((const unsigned*)((const char*)(gbase) + (voff)[_i]), (LAS unsigned*)(lds + (bufoff) + ldsw + _i * 8192), 16, 0, 0); } while (0)
; #define PG8_LDA(dst, b, h) do { _Pragma("unroll") for (int m = 0; m < 4; ++m) _Pragma("unroll") for (int k = 0; k < 2; ++k) dst[m][k] = *(const LAS bf16x8*)(lds + PG8_SA(b, h) + aoff + m * 2048 + k * 1024); } while (0)
; #define PG8_MMA(ai, bj, At, Bt) do { __builtin_amdgcn_s_setprio(1); _Pragma("unroll") for (int m = 0; m < 4; ++m) _Pragma("unroll") for (int n = 0; n < 2; ++n) _Pragma("unroll") for (int k = 0; k < 2; ++k) \
;         acc[ai][bj][m][n] = __builtin_amdgcn_mfma_f32_16x16x32_bf16(Bt[n][k], At[m][k], acc[ai][bj][m][n], 0, 0, 0); __builtin_amdgcn_s_setprio(0); } while (0)
; template <class Epi, bool KS0 = false>
; __device__ __forceinline__ void gemm_phase(const int WID, LAS unsigned char* lds, const Gemm g, const StaticOrder& S, const Epi& E) {
;     ...
;             PG8_BAR; PG8_WAIT_L(0); PG8_MMA(0, 1, At, B1); PG8_BAR;
;             PG8_LDA(At, 1, 1); PG8_STAGE(PG8_SA(1, 0), a3, voffA);
;             PG8_BAR; PG8_WAIT_L(0); PG8_MMA(1, 0, At, B0); PG8_BAR; PG8_SCHED;
;             PG8_STAGE(PG8_SB(1, 1), b3 + hstep, voffB);
;             PG8_WAIT_V(6); PG8_BAR; PG8_MMA(1, 1, At, B1); PG8_BAR;
;         }
;         { int fr2 = lane_id_(), fq2; fq2 = fr2 >> 4; fr2 &= 15; asm volatile("" : "+v"(fr2), "+v"(fq2)); E(acc, cur, wr, wc, fr2, fq2); }
;         if (!has_next) break;
;     __device__ __forceinline__ void operator()(f32x4 (&acc)[2][2][4][2], const Unit& u, int wr, int wc, int fr, int fq) const {
;     ...
;         if (frag && u.pn >= fmin) { base = O + ((size_t)(u.pm * frag + u.pn) << 16) + (size_t)((((wr * 4 + wc) * 16) * 64 + fq * 16 + fr) << 3); s_ai = 4096; s_m = 1024; s_bj = 512; }
;         else if (frag) { base = O + ((size_t)(u.pm * frag + u.pn) << 16) + (size_t)(((wr * 64 + fr) << 8) + wc * 32 + 8 * fq); s_ai = (size_t)HALF * 256; s_m = 16 * 256; s_bj = HALF; }
;         else { base = O + (size_t)(u.pm * BM + wr * 64 + fr) * ldc + u.pn * BM + wc * 32 + 8 * fq; s_ai = (size_t)HALF * ldc; s_m = (size_t)16 * ldc; s_bj = HALF; }
	s_waitcnt lgkmcnt(0)
	s_waitcnt lgkmcnt(0)
	v_mfma_f32_16x16x32_bf16 v[116:119], v[200:203], v[168:171], v[116:119]
	v_mfma_f32_16x16x32_bf16 v[108:111], v[208:211], v[168:171], v[108:111]
	v_mfma_f32_16x16x32_bf16 v[96:99], v[200:203], v[176:179], v[96:99]
	v_mfma_f32_16x16x32_bf16 v[88:91], v[208:211], v[176:179], v[88:91]
	v_mfma_f32_16x16x32_bf16 v[80:83], v[200:203], v[184:187], v[80:83]
	v_mfma_f32_16x16x32_bf16 v[72:75], v[208:211], v[184:187], v[72:75]
	v_mfma_f32_16x16x32_bf16 v[68:71], v[200:203], v[192:195], v[68:71]
	v_mfma_f32_16x16x32_bf16 v[64:67], v[208:211], v[192:195], v[64:67]
	v_mfma_f32_16x16x32_bf16 v[116:119], v[204:207], v[172:175], v[116:119]
	v_mfma_f32_16x16x32_bf16 v[108:111], v[212:215], v[172:175], v[108:111]
	v_mfma_f32_16x16x32_bf16 v[96:99], v[204:207], v[180:183], v[96:99]
	v_mfma_f32_16x16x32_bf16 v[88:91], v[212:215], v[180:183], v[88:91]
	v_mfma_f32_16x16x32_bf16 v[80:83], v[204:207], v[188:191], v[80:83]
	v_mfma_f32_16x16x32_bf16 v[72:75], v[212:215], v[188:191], v[72:75]
	v_mfma_f32_16x16x32_bf16 v[68:71], v[204:207], v[196:199], v[68:71]
	v_mfma_f32_16x16x32_bf16 v[64:67], v[212:215], v[196:199], v[64:67]
	s_mov_b32 m0, s40
	v_lshl_add_u64 v[144:145], v[218:219], 0, s[8:9]
	s_barrier
	ds_read_b128 v[168:171], v149 offset:49152
	ds_read_b128 v[172:175], v149 offset:50176
	ds_read_b128 v[176:179], v149 offset:51200
	ds_read_b128 v[180:183], v149 offset:52224
	ds_read_b128 v[184:187], v149 offset:53248
	ds_read_b128 v[188:191], v149 offset:54272
	ds_read_b128 v[192:195], v149 offset:55296
	ds_read_b128 v[196:199], v149 offset:56320
	global_load_lds_dwordx4 v[144:145], off
	v_lshl_add_u64 v[144:145], v[220:221], 0, s[8:9]
	s_mov_b32 m0, s41
	s_nop 0
	global_load_lds_dwordx4 v[144:145], off
	s_barrier
	s_waitcnt lgkmcnt(0)
	s_waitcnt lgkmcnt(0)
	v_mfma_f32_16x16x32_bf16 v[60:63], v[152:155], v[168:171], v[60:63]
	v_mfma_f32_16x16x32_bf16 v[56:59], v[160:163], v[168:171], v[56:59]
	v_mfma_f32_16x16x32_bf16 v[52:55], v[152:155], v[176:179], v[52:55]
	v_mfma_f32_16x16x32_bf16 v[44:47], v[160:163], v[176:179], v[44:47]
	v_mfma_f32_16x16x32_bf16 v[36:39], v[152:155], v[184:187], v[36:39]
	v_mfma_f32_16x16x32_bf16 v[28:31], v[160:163], v[184:187], v[28:31]
	v_mfma_f32_16x16x32_bf16 v[20:23], v[152:155], v[192:195], v[20:23]
	v_mfma_f32_16x16x32_bf16 v[12:15], v[160:163], v[192:195], v[12:15]
	v_mfma_f32_16x16x32_bf16 v[60:63], v[156:159], v[172:175], v[60:63]
	v_mfma_f32_16x16x32_bf16 v[56:59], v[164:167], v[172:175], v[56:59]
	v_mfma_f32_16x16x32_bf16 v[52:55], v[156:159], v[180:183], v[52:55]
	v_mfma_f32_16x16x32_bf16 v[44:47], v[164:167], v[180:183], v[44:47]
	v_mfma_f32_16x16x32_bf16 v[36:39], v[156:159], v[188:191], v[36:39]
	v_mfma_f32_16x16x32_bf16 v[28:31], v[164:167], v[188:191], v[28:31]
	v_mfma_f32_16x16x32_bf16 v[20:23], v[156:159], v[196:199], v[20:23]
	v_mfma_f32_16x16x32_bf16 v[12:15], v[164:167], v[196:199], v[12:15]
	s_barrier
	s_add_u32 s22, s22, 0x80080
	s_addc_u32 s23, s23, 0
	s_add_i32 s24, s24, s26
	v_lshl_add_u64 v[144:145], s[22:23], 0, v[132:133]
	s_mov_b32 m0, s24
	s_nop 0
	global_load_lds_dwordx4 v[144:145], off
	v_lshl_add_u64 v[144:145], s[22:23], 0, v[128:129]
	s_add_i32 m0, s24, 0x2000
	s_nop 0
	global_load_lds_dwordx4 v[144:145], off
	s_waitcnt vmcnt(6)
	s_barrier
	v_mfma_f32_16x16x32_bf16 v[48:51], v[200:203], v[168:171], v[48:51]
	v_mfma_f32_16x16x32_bf16 v[40:43], v[208:211], v[168:171], v[40:43]
	v_mfma_f32_16x16x32_bf16 v[32:35], v[200:203], v[176:179], v[32:35]
	v_mfma_f32_16x16x32_bf16 v[24:27], v[208:211], v[176:179], v[24:27]
	v_mfma_f32_16x16x32_bf16 v[16:19], v[200:203], v[184:187], v[16:19]
	v_mfma_f32_16x16x32_bf16 v[8:11], v[208:211], v[184:187], v[8:11]
	v_mfma_f32_16x16x32_bf16 v[4:7], v[200:203], v[192:195], v[4:7]
	v_mfma_f32_16x16x32_bf16 v[0:3], v[208:211], v[192:195], v[0:3]
	v_mfma_f32_16x16x32_bf16 v[48:51], v[204:207], v[172:175], v[48:51]
	v_mfma_f32_16x16x32_bf16 v[40:43], v[212:215], v[172:175], v[40:43]
	v_mfma_f32_16x16x32_bf16 v[32:35], v[204:207], v[180:183], v[32:35]
	v_mfma_f32_16x16x32_bf16 v[24:27], v[212:215], v[180:183], v[24:27]
	v_mfma_f32_16x16x32_bf16 v[16:19], v[204:207], v[188:191], v[16:19]
	v_mfma_f32_16x16x32_bf16 v[8:11], v[212:215], v[188:191], v[8:11]
	v_mfma_f32_16x16x32_bf16 v[4:7], v[204:207], v[196:199], v[4:7]
	v_mfma_f32_16x16x32_bf16 v[0:3], v[212:215], v[196:199], v[0:3]
	s_add_i32 s50, s50, 2
	s_add_u32 s20, s20, 0x100
	s_addc_u32 s21, s21, 0
	s_add_u32 s48, s48, 0x100
	s_addc_u32 s49, s49, 0
	s_cmp_gt_u32 s50, 29
	s_barrier
	s_cbranch_scc0 .LBB0_86
	v_mbcnt_lo_u32_b32 v144, -1, 0
	v_mbcnt_hi_u32_b32 v144, -1, v144
	s_cmp_lt_i32 s45, 8
	v_ashrrev_i32_e32 v145, 4, v144
	v_and_b32_e32 v151, 15, v144
	s_mov_b64 s[20:21], -1
	s_cbranch_scc1 .LBB0_89
	v_add_u32_e32 v144, s55, v151
	v_lshlrev_b32_e32 v152, 7, v145
	v_lshl_add_u32 v144, v144, 3, v152
	s_mov_b64 s[20:21], 0

; #define PG8_STAGE(bufoff, gbase, voff) do { _Pragma("unroll") for (int _i = 0; _i < 2; ++_i) \
;         __builtin_amdgcn_global_load_lds((const unsigned*)((const char*)(gbase) + (voff)[_i]), (LAS unsigned*)(lds + (bufoff) + ldsw + _i * 8192), 16, 0, 0); } while (0)
; #define PG8_LDA(dst, b, h) do { _Pragma("unroll") for (int m = 0; m < 4; ++m) _Pragma("unroll") for (int k = 0; k < 2; ++k) dst[m][k] = *(const LAS bf16x8*)(lds + PG8_SA(b, h) + aoff + m * 2048 + k * 1024); } while (0)
; #define PG8_LDB(dst, b, h) do { _Pragma("unroll") for (int n = 0; n < 2; ++n) _Pragma("unroll") for (int k = 0; k < 2; ++k) dst[n][k] = *(const LAS bf16x8*)(lds + PG8_SB(b, h) + boff + n * 2048 + k * 1024); } while (0)
; #define PG8_MMA(ai, bj, At, Bt) do { __builtin_amdgcn_s_setprio(1); _Pragma("unroll") for (int m = 0; m < 4; ++m) _Pragma("unroll") for (int n = 0; n < 2; ++n) _Pragma("unroll") for (int k = 0; k < 2; ++k) \
;         acc[ai][bj][m][n] = __builtin_amdgcn_mfma_f32_16x16x32_bf16(Bt[n][k], At[m][k], acc[ai][bj][m][n], 0, 0, 0); __builtin_amdgcn_s_setprio(0); } while (0)
; #define PG8_WAIT_L(n) asm volatile("s_waitcnt lgkmcnt(" #n ")" ::: "memory")
; #define PG8_BAR __builtin_amdgcn_s_barrier()
; #define PG8_SCHED __builtin_amdgcn_sched_barrier(0)
; template <class Epi, bool KS0 = false>
; __device__ __forceinline__ void gemm_phase(const int WID, LAS unsigned char* lds, const Gemm g, const StaticOrder& S, const Epi& E) {
;     ...
;         for (int t = 0; t < nt; t += 2) {
;             const bool last = (t == nt - 2);
;             const char* a1 = cA + (size_t)(t + 1) * kstep;
;             const char* a2 = last ? nA : cA + (size_t)(t + 2) * kstep; const char* b2 = last ? nB : cB + (size_t)(t + 2) * kstep;
;             const char* a3 = a2 + kstep; const char* b3 = b2 + kstep;
;             PG8_LDB(B0, 0, 0); PG8_SCHED; PG8_LDA(At, 0, 0); PG8_STAGE(PG8_SA(1, 1), a1 + hstep, voffA);
;             PG8_WAIT_L(8); PG8_BAR; PG8_WAIT_L(0); PG8_MMA(0, 0, At, B0); PG8_BAR; PG8_SCHED;
;             PG8_LDB(B1, 0, 1); PG8_STAGE(PG8_SB(0, 0), b2, voffB);
;             PG8_BAR; PG8_WAIT_L(0); PG8_MMA(0, 1, At, B1); PG8_BAR;
;             PG8_LDA(At, 0, 1); PG8_STAGE(PG8_SA(0, 0), a2, voffA);
;             PG8_BAR; PG8_WAIT_L(0); PG8_MMA(1, 0, At, B0); PG8_BAR; PG8_SCHED;
.LBB0_670:
	ds_read_b128 v[128:131], v206
	ds_read_b128 v[132:135], v206 offset:1024
	ds_read_b128 v[136:139], v206 offset:2048
	ds_read_b128 v[140:143], v206 offset:3072
	s_add_u32 s42, s20, 0xfff80080
	s_addc_u32 s43, s21, -1
	s_cmp_eq_u32 s53, 28
	s_cselect_b32 s45, s11, s43
	s_cselect_b32 s44, s19, s42
	s_cselect_b32 s43, s9, s52
	s_cselect_b32 s42, s50, s51
	v_lshl_add_u64 v[192:193], s[20:21], 0, v[184:185]
	s_add_i32 m0, s23, 0xc000
	ds_read_b128 v[144:147], v207
	ds_read_b128 v[148:151], v207 offset:1024
	ds_read_b128 v[152:155], v207 offset:2048
	ds_read_b128 v[156:159], v207 offset:3072
	ds_read_b128 v[160:163], v207 offset:4096
	ds_read_b128 v[164:167], v207 offset:5120
	ds_read_b128 v[168:171], v207 offset:6144
	ds_read_b128 v[172:175], v207 offset:7168
	global_load_lds_dwordx4 v[192:193], off
	v_lshl_add_u64 v[192:193], s[20:21], 0, v[186:187]
	s_add_i32 m0, s23, 0xe000
	s_nop 0
	global_load_lds_dwordx4 v[192:193], off
	s_waitcnt lgkmcnt(8)
	s_barrier
	s_waitcnt lgkmcnt(0)
	s_waitcnt lgkmcnt(0)
	v_mfma_f32_16x16x32_bf16 v[124:127], v[128:131], v[144:147], v[124:127]
	v_mfma_f32_16x16x32_bf16 v[120:123], v[136:139], v[144:147], v[120:123]
	v_mfma_f32_16x16x32_bf16 v[108:111], v[128:131], v[152:155], v[108:111]
	v_mfma_f32_16x16x32_bf16 v[104:107], v[136:139], v[152:155], v[104:107]
	v_mfma_f32_16x16x32_bf16 v[92:95], v[128:131], v[160:163], v[92:95]
	v_mfma_f32_16x16x32_bf16 v[88:91], v[136:139], v[160:163], v[88:91]
	v_mfma_f32_16x16x32_bf16 v[76:79], v[128:131], v[168:171], v[76:79]
	v_mfma_f32_16x16x32_bf16 v[72:75], v[136:139], v[168:171], v[72:75]
	v_mfma_f32_16x16x32_bf16 v[124:127], v[132:135], v[148:151], v[124:127]
	v_mfma_f32_16x16x32_bf16 v[120:123], v[140:143], v[148:151], v[120:123]
	v_mfma_f32_16x16x32_bf16 v[108:111], v[132:135], v[156:159], v[108:111]
	v_mfma_f32_16x16x32_bf16 v[104:107], v[140:143], v[156:159], v[104:107]
	v_mfma_f32_16x16x32_bf16 v[92:95], v[132:135], v[164:167], v[92:95]
	v_mfma_f32_16x16x32_bf16 v[88:91], v[140:143], v[164:167], v[88:91]
	v_mfma_f32_16x16x32_bf16 v[76:79], v[132:135], v[172:175], v[76:79]
	v_mfma_f32_16x16x32_bf16 v[72:75], v[140:143], v[172:175], v[72:75]
	s_barrier
	s_add_i32 s54, s35, s26
	v_lshl_add_u64 v[214:215], s[42:43], 0, v[178:179]
	s_mov_b32 m0, s54
	ds_read_b128 v[192:195], v208
	ds_read_b128 v[196:199], v208 offset:1024
	ds_read_b128 v[200:203], v208 offset:2048
	ds_read_b128 v[210:213], v208 offset:3072
	global_load_lds_dwordx4 v[214:215], off
	v_lshl_add_u64 v[216:217], s[42:43], 0, v[182:183]
	s_add_i32 m0, s54, 0x2000
	s_nop 0
	global_load_lds_dwordx4 v[216:217], off
	s_barrier
	s_waitcnt lgkmcnt(0)
	s_waitcnt lgkmcnt(0)
	v_mfma_f32_16x16x32_bf16 v[116:119], v[192:195], v[144:147], v[116:119]
	v_mfma_f32_16x16x32_bf16 v[112:115], v[200:203], v[144:147], v[112:115]
	v_mfma_f32_16x16x32_bf16 v[100:103], v[192:195], v[152:155], v[100:103]
	v_mfma_f32_16x16x32_bf16 v[96:99], v[200:203], v[152:155], v[96:99]
	v_mfma_f32_16x16x32_bf16 v[84:87], v[192:195], v[160:163], v[84:87]
	v_mfma_f32_16x16x32_bf16 v[80:83], v[200:203], v[160:163], v[80:83]
	v_mfma_f32_16x16x32_bf16 v[68:71], v[192:195], v[168:171], v[68:71]
	v_mfma_f32_16x16x32_bf16 v[64:67], v[200:203], v[168:171], v[64:67]
	v_mfma_f32_16x16x32_bf16 v[116:119], v[196:199], v[148:151], v[116:119]
	v_mfma_f32_16x16x32_bf16 v[112:115], v[210:213], v[148:151], v[112:115]
	v_mfma_f32_16x16x32_bf16 v[100:103], v[196:199], v[156:159], v[100:103]
	v_mfma_f32_16x16x32_bf16 v[96:99], v[210:213], v[156:159], v[96:99]
	v_mfma_f32_16x16x32_bf16 v[84:87], v[196:199], v[164:167], v[84:87]
	v_mfma_f32_16x16x32_bf16 v[80:83], v[210:213], v[164:167], v[80:83]
	v_mfma_f32_16x16x32_bf16 v[68:71], v[196:199], v[172:175], v[68:71]
	v_mfma_f32_16x16x32_bf16 v[64:67], v[210:213], v[172:175], v[64:67]
	s_mov_b32 m0, s23
	v_lshl_add_u64 v[218:219], s[44:45], 0, v[176:177]
	s_barrier
	ds_read_b128 v[144:147], v207 offset:16384
	ds_read_b128 v[148:151], v207 offset:17408
	ds_read_b128 v[152:155], v207 offset:18432
	ds_read_b128 v[156:159], v207 offset:19456
	ds_read_b128 v[160:163], v207 offset:20480
	ds_read_b128 v[164:167], v207 offset:21504
	ds_read_b128 v[168:171], v207 offset:22528
	ds_read_b128 v[172:175], v207 offset:23552
	global_load_lds_dwordx4 v[218:219], off
	v_lshl_add_u64 v[220:221], s[44:45], 0, v[180:181]
	s_mov_b32 m0, s24
	s_nop 0
	global_load_lds_dwordx4 v[220:221], off
	s_barrier
	s_waitcnt lgkmcnt(0)
	s_waitcnt lgkmcnt(0)
	v_mfma_f32_16x16x32_bf16 v[60:63], v[128:131], v[144:147], v[60:63]
	v_mfma_f32_16x16x32_bf16 v[56:59], v[136:139], v[144:147], v[56:59]
	v_mfma_f32_16x16x32_bf16 v[44:47], v[128:131], v[152:155], v[44:47]
	v_mfma_f32_16x16x32_bf16 v[40:43], v[136:139], v[152:155], v[40:43]
	v_mfma_f32_16x16x32_bf16 v[28:31], v[128:131], v[160:163], v[28:31]
	v_mfma_f32_16x16x32_bf16 v[24:27], v[136:139], v[160:163], v[24:27]
	v_mfma_f32_16x16x32_bf16 v[12:15], v[128:131], v[168:171], v[12:15]
	v_mfma_f32_16x16x32_bf16 v[8:11], v[136:139], v[168:171], v[8:11]
	v_mfma_f32_16x16x32_bf16 v[60:63], v[132:135], v[148:151], v[60:63]
	v_mfma_f32_16x16x32_bf16 v[56:59], v[140:143], v[148:151], v[56:59]
	v_mfma_f32_16x16x32_bf16 v[44:47], v[132:135], v[156:159], v[44:47]
	v_mfma_f32_16x16x32_bf16 v[40:43], v[140:143], v[156:159], v[40:43]
	v_mfma_f32_16x16x32_bf16 v[28:31], v[132:135], v[164:167], v[28:31]
	v_mfma_f32_16x16x32_bf16 v[24:27], v[140:143], v[164:167], v[24:27]
	v_mfma_f32_16x16x32_bf16 v[12:15], v[132:135], v[172:175], v[12:15]
	v_mfma_f32_16x16x32_bf16 v[8:11], v[140:143], v[172:175], v[8:11]
	s_barrier
; #define PG8_STAGE(bufoff, gbase, voff) do { _Pragma("unroll") for (int _i = 0; _i < 2; ++_i) \
;         __builtin_amdgcn_global_load_lds((const unsigned*)((const char*)(gbase) + (voff)[_i]), (LAS unsigned*)(lds + (bufoff) + ldsw + _i * 8192), 16, 0, 0); } while (0)
; #define PG8_LDA(dst, b, h) do { _Pragma("unroll") for (int m = 0; m < 4; ++m) _Pragma("unroll") for (int k = 0; k < 2; ++k) dst[m][k] = *(const LAS bf16x8*)(lds + PG8_SA(b, h) + aoff + m * 2048 + k * 1024); } while (0)
; #define PG8_LDB(dst, b, h) do { _Pragma("unroll") for (int n = 0; n < 2; ++n) _Pragma("unroll") for (int k = 0; k < 2; ++k) dst[n][k] = *(const LAS bf16x8*)(lds + PG8_SB(b, h) + boff + n * 2048 + k * 1024); } while (0)
; #define PG8_MMA(ai, bj, At, Bt) do { __builtin_amdgcn_s_setprio(1); _Pragma("unroll") for (int m = 0; m < 4; ++m) _Pragma("unroll") for (int n = 0; n < 2; ++n) _Pragma("unroll") for (int k = 0; k < 2; ++k) \
;         acc[ai][bj][m][n] = __builtin_amdgcn_mfma_f32_16x16x32_bf16(Bt[n][k], At[m][k], acc[ai][bj][m][n], 0, 0, 0); __builtin_amdgcn_s_setprio(0); } while (0)
; #define PG8_WAIT_V(n) asm volatile("s_waitcnt vmcnt(" #n ")" ::: "memory")
; #define PG8_WAIT_L(n) asm volatile("s_waitcnt lgkmcnt(" #n ")" ::: "memory")
; #define PG8_BAR __builtin_amdgcn_s_barrier()
; #define PG8_SCHED __builtin_amdgcn_sched_barrier(0)
; template <class Epi, bool KS0 = false>
; __device__ __forceinline__ void gemm_phase(const int WID, LAS unsigned char* lds, const Gemm g, const StaticOrder& S, const Epi& E) {
;     ...
;             PG8_STAGE(PG8_SB(0, 1), b2 + hstep, voffB);
;             PG8_WAIT_V(6); PG8_BAR; PG8_MMA(1, 1, At, B1); PG8_BAR;
;             PG8_LDB(B0, 1, 0); PG8_SCHED; PG8_LDA(At, 1, 0); PG8_STAGE(PG8_SA(0, 1), a2 + hstep, voffA);
;             PG8_WAIT_L(8); PG8_BAR; PG8_WAIT_L(0); PG8_MMA(0, 0, At, B0); PG8_BAR; PG8_SCHED;
;             PG8_LDB(B1, 1, 1); PG8_STAGE(PG8_SB(1, 0), b3, voffB);
;             PG8_BAR; PG8_WAIT_L(0); PG8_MMA(0, 1, At, B1); PG8_BAR;
;             PG8_LDA(At, 1, 1); PG8_STAGE(PG8_SA(1, 0), a3, voffA);
;             PG8_BAR; PG8_WAIT_L(0); PG8_MMA(1, 0, At, B0); PG8_BAR; PG8_SCHED;
	s_add_u32 s54, s42, 0x80000
	s_addc_u32 s55, s43, 0
	s_add_i32 s58, s48, s26
	v_lshl_add_u64 v[128:129], s[54:55], 0, v[178:179]
	s_mov_b32 m0, s58
	s_nop 0
	global_load_lds_dwordx4 v[128:129], off
	v_lshl_add_u64 v[128:129], s[54:55], 0, v[182:183]
	s_add_i32 m0, s58, 0x2000
	s_nop 0
	global_load_lds_dwordx4 v[128:129], off
	s_waitcnt vmcnt(6)
	s_barrier
	v_mfma_f32_16x16x32_bf16 v[52:55], v[192:195], v[144:147], v[52:55]
	v_mfma_f32_16x16x32_bf16 v[48:51], v[200:203], v[144:147], v[48:51]
	v_mfma_f32_16x16x32_bf16 v[36:39], v[192:195], v[152:155], v[36:39]
	v_mfma_f32_16x16x32_bf16 v[32:35], v[200:203], v[152:155], v[32:35]
	v_mfma_f32_16x16x32_bf16 v[20:23], v[192:195], v[160:163], v[20:23]
	v_mfma_f32_16x16x32_bf16 v[16:19], v[200:203], v[160:163], v[16:19]
	v_mfma_f32_16x16x32_bf16 v[4:7], v[192:195], v[168:171], v[4:7]
	v_mfma_f32_16x16x32_bf16 v[0:3], v[200:203], v[168:171], v[0:3]
	v_mfma_f32_16x16x32_bf16 v[52:55], v[196:199], v[148:151], v[52:55]
	v_mfma_f32_16x16x32_bf16 v[48:51], v[210:213], v[148:151], v[48:51]
	v_mfma_f32_16x16x32_bf16 v[36:39], v[196:199], v[156:159], v[36:39]
	v_mfma_f32_16x16x32_bf16 v[32:35], v[210:213], v[156:159], v[32:35]
	v_mfma_f32_16x16x32_bf16 v[20:23], v[196:199], v[164:167], v[20:23]
	v_mfma_f32_16x16x32_bf16 v[16:19], v[210:213], v[164:167], v[16:19]
	v_mfma_f32_16x16x32_bf16 v[4:7], v[196:199], v[172:175], v[4:7]
	v_mfma_f32_16x16x32_bf16 v[0:3], v[210:213], v[172:175], v[0:3]
	s_add_i32 s54, 0, 0x18000
	v_add_u32_e32 v140, s54, v205
	s_barrier
	ds_read_b128 v[128:131], v140
	ds_read_b128 v[132:135], v140 offset:1024
	ds_read_b128 v[136:139], v140 offset:2048
	ds_read_b128 v[140:143], v140 offset:3072
	s_add_u32 s44, s44, 0x80000
	s_addc_u32 s45, s45, 0
	s_mov_b32 m0, s25
	v_lshl_add_u64 v[192:193], s[44:45], 0, v[176:177]
	ds_read_b128 v[144:147], v207 offset:32768
	ds_read_b128 v[148:151], v207 offset:33792
	ds_read_b128 v[152:155], v207 offset:34816
	ds_read_b128 v[156:159], v207 offset:35840
	ds_read_b128 v[160:163], v207 offset:36864
	ds_read_b128 v[164:167], v207 offset:37888
	ds_read_b128 v[168:171], v207 offset:38912
	ds_read_b128 v[172:175], v207 offset:39936
	global_load_lds_dwordx4 v[192:193], off
	v_lshl_add_u64 v[192:193], s[44:45], 0, v[180:181]
	s_mov_b32 m0, s28
	s_nop 0
	global_load_lds_dwordx4 v[192:193], off
	s_waitcnt lgkmcnt(8)
	s_barrier
	s_waitcnt lgkmcnt(0)
	s_waitcnt lgkmcnt(0)
	v_mfma_f32_16x16x32_bf16 v[124:127], v[128:131], v[144:147], v[124:127]
	v_mfma_f32_16x16x32_bf16 v[120:123], v[136:139], v[144:147], v[120:123]
	v_mfma_f32_16x16x32_bf16 v[108:111], v[128:131], v[152:155], v[108:111]
	v_mfma_f32_16x16x32_bf16 v[104:107], v[136:139], v[152:155], v[104:107]
	v_mfma_f32_16x16x32_bf16 v[92:95], v[128:131], v[160:163], v[92:95]
	v_mfma_f32_16x16x32_bf16 v[88:91], v[136:139], v[160:163], v[88:91]
	v_mfma_f32_16x16x32_bf16 v[76:79], v[128:131], v[168:171], v[76:79]
	v_mfma_f32_16x16x32_bf16 v[72:75], v[136:139], v[168:171], v[72:75]
	v_mfma_f32_16x16x32_bf16 v[124:127], v[132:135], v[148:151], v[124:127]
	v_mfma_f32_16x16x32_bf16 v[120:123], v[140:143], v[148:151], v[120:123]
	v_mfma_f32_16x16x32_bf16 v[108:111], v[132:135], v[156:159], v[108:111]
	v_mfma_f32_16x16x32_bf16 v[104:107], v[140:143], v[156:159], v[104:107]
	v_mfma_f32_16x16x32_bf16 v[92:95], v[132:135], v[164:167], v[92:95]
	v_mfma_f32_16x16x32_bf16 v[88:91], v[140:143], v[164:167], v[88:91]
	v_mfma_f32_16x16x32_bf16 v[76:79], v[132:135], v[172:175], v[76:79]
	v_mfma_f32_16x16x32_bf16 v[72:75], v[140:143], v[172:175], v[72:75]
	s_barrier
	s_add_i32 s44, 0, 0x1c000
	s_add_i32 s45, s54, s26
	v_add_u32_e32 v210, s44, v205
	v_lshl_add_u64 v[214:215], v[214:215], 0, s[0:1]
	s_mov_b32 m0, s45
	ds_read_b128 v[192:195], v210
	ds_read_b128 v[196:199], v210 offset:1024
	ds_read_b128 v[200:203], v210 offset:2048
	ds_read_b128 v[210:213], v210 offset:3072
	global_load_lds_dwordx4 v[214:215], off
	v_lshl_add_u64 v[214:215], v[216:217], 0, s[0:1]
	s_add_i32 m0, s45, 0x2000
	s_nop 0
	global_load_lds_dwordx4 v[214:215], off
	s_barrier
	s_waitcnt lgkmcnt(0)
	s_waitcnt lgkmcnt(0)
	v_mfma_f32_16x16x32_bf16 v[116:119], v[192:195], v[144:147], v[116:119]
	v_mfma_f32_16x16x32_bf16 v[112:115], v[200:203], v[144:147], v[112:115]
	v_mfma_f32_16x16x32_bf16 v[100:103], v[192:195], v[152:155], v[100:103]
	v_mfma_f32_16x16x32_bf16 v[96:99], v[200:203], v[152:155], v[96:99]
	v_mfma_f32_16x16x32_bf16 v[84:87], v[192:195], v[160:163], v[84:87]
	v_mfma_f32_16x16x32_bf16 v[80:83], v[200:203], v[160:163], v[80:83]
	v_mfma_f32_16x16x32_bf16 v[68:71], v[192:195], v[168:171], v[68:71]
	v_mfma_f32_16x16x32_bf16 v[64:67], v[200:203], v[168:171], v[64:67]
	v_mfma_f32_16x16x32_bf16 v[116:119], v[196:199], v[148:151], v[116:119]
	v_mfma_f32_16x16x32_bf16 v[112:115], v[210:213], v[148:151], v[112:115]
	v_mfma_f32_16x16x32_bf16 v[100:103], v[196:199], v[156:159], v[100:103]
	v_mfma_f32_16x16x32_bf16 v[96:99], v[210:213], v[156:159], v[96:99]
	v_mfma_f32_16x16x32_bf16 v[84:87], v[196:199], v[164:167], v[84:87]
	v_mfma_f32_16x16x32_bf16 v[80:83], v[210:213], v[164:167], v[80:83]
	v_mfma_f32_16x16x32_bf16 v[68:71], v[196:199], v[172:175], v[68:71]
	v_mfma_f32_16x16x32_bf16 v[64:67], v[210:213], v[172:175], v[64:67]
	s_mov_b32 m0, s29
	v_lshl_add_u64 v[214:215], v[218:219], 0, s[0:1]
	s_barrier
	ds_read_b128 v[144:147], v207 offset:49152
	ds_read_b128 v[148:151], v207 offset:50176
	ds_read_b128 v[152:155], v207 offset:51200
	ds_read_b128 v[156:159], v207 offset:52224
	ds_read_b128 v[160:163], v207 offset:53248
	ds_read_b128 v[164:167], v207 offset:54272
	ds_read_b128 v[168:171], v207 offset:55296
	ds_read_b128 v[172:175], v207 offset:56320
	global_load_lds_dwordx4 v[214:215], off
	v_lshl_add_u64 v[214:215], v[220:221], 0, s[0:1]
	s_mov_b32 m0, s34
	s_nop 0
	global_load_lds_dwordx4 v[214:215], off
	s_barrier
; #define PG8_STAGE(bufoff, gbase, voff) do { _Pragma("unroll") for (int _i = 0; _i < 2; ++_i) \
;         __builtin_amdgcn_global_load_lds((const unsigned*)((const char*)(gbase) + (voff)[_i]), (LAS unsigned*)(lds + (bufoff) + ldsw + _i * 8192), 16, 0, 0); } while (0)
; #define PG8_MMA(ai, bj, At, Bt) do { __builtin_amdgcn_s_setprio(1); _Pragma("unroll") for (int m = 0; m < 4; ++m) _Pragma("unroll") for (int n = 0; n < 2; ++n) _Pragma("unroll") for (int k = 0; k < 2; ++k) \
;         acc[ai][bj][m][n] = __builtin_amdgcn_mfma_f32_16x16x32_bf16(Bt[n][k], At[m][k], acc[ai][bj][m][n], 0, 0, 0); __builtin_amdgcn_s_setprio(0); } while (0)
; #define PG8_WAIT_V(n) asm volatile("s_waitcnt vmcnt(" #n ")" ::: "memory")
; #define PG8_WAIT_L(n) asm volatile("s_waitcnt lgkmcnt(" #n ")" ::: "memory")
; #define PG8_BAR __builtin_amdgcn_s_barrier()
; #define PG8_SCHED __builtin_amdgcn_sched_barrier(0)
; template <class Epi, bool KS0 = false>
; __device__ __forceinline__ void gemm_phase(const int WID, LAS unsigned char* lds, const Gemm g, const StaticOrder& S, const Epi& E) {
;     ...
;             PG8_BAR; PG8_WAIT_L(0); PG8_MMA(1, 0, At, B0); PG8_BAR; PG8_SCHED;
;             PG8_STAGE(PG8_SB(1, 1), b3 + hstep, voffB);
;             PG8_WAIT_V(6); PG8_BAR; PG8_MMA(1, 1, At, B1); PG8_BAR;
;         }
	s_waitcnt lgkmcnt(0)
	s_waitcnt lgkmcnt(0)
	v_mfma_f32_16x16x32_bf16 v[60:63], v[128:131], v[144:147], v[60:63]
	v_mfma_f32_16x16x32_bf16 v[56:59], v[136:139], v[144:147], v[56:59]
	v_mfma_f32_16x16x32_bf16 v[44:47], v[128:131], v[152:155], v[44:47]
	v_mfma_f32_16x16x32_bf16 v[40:43], v[136:139], v[152:155], v[40:43]
	v_mfma_f32_16x16x32_bf16 v[28:31], v[128:131], v[160:163], v[28:31]
	v_mfma_f32_16x16x32_bf16 v[24:27], v[136:139], v[160:163], v[24:27]
	v_mfma_f32_16x16x32_bf16 v[12:15], v[128:131], v[168:171], v[12:15]
	v_mfma_f32_16x16x32_bf16 v[8:11], v[136:139], v[168:171], v[8:11]
	v_mfma_f32_16x16x32_bf16 v[60:63], v[132:135], v[148:151], v[60:63]
	v_mfma_f32_16x16x32_bf16 v[56:59], v[140:143], v[148:151], v[56:59]
	v_mfma_f32_16x16x32_bf16 v[44:47], v[132:135], v[156:159], v[44:47]
	v_mfma_f32_16x16x32_bf16 v[40:43], v[140:143], v[156:159], v[40:43]
	v_mfma_f32_16x16x32_bf16 v[28:31], v[132:135], v[164:167], v[28:31]
	v_mfma_f32_16x16x32_bf16 v[24:27], v[140:143], v[164:167], v[24:27]
	v_mfma_f32_16x16x32_bf16 v[12:15], v[132:135], v[172:175], v[12:15]
	v_mfma_f32_16x16x32_bf16 v[8:11], v[140:143], v[172:175], v[8:11]
	s_barrier
	s_add_u32 s42, s42, 0x80080
	s_addc_u32 s43, s43, 0
	s_add_i32 s44, s44, s26
	v_lshl_add_u64 v[128:129], s[42:43], 0, v[178:179]
	s_mov_b32 m0, s44
	s_nop 0
	global_load_lds_dwordx4 v[128:129], off
	v_lshl_add_u64 v[128:129], s[42:43], 0, v[182:183]
	s_add_i32 m0, s44, 0x2000
	s_nop 0
	global_load_lds_dwordx4 v[128:129], off
	s_waitcnt vmcnt(6)
	s_barrier
	v_mfma_f32_16x16x32_bf16 v[52:55], v[192:195], v[144:147], v[52:55]
	v_mfma_f32_16x16x32_bf16 v[48:51], v[200:203], v[144:147], v[48:51]
	v_mfma_f32_16x16x32_bf16 v[36:39], v[192:195], v[152:155], v[36:39]
	v_mfma_f32_16x16x32_bf16 v[32:35], v[200:203], v[152:155], v[32:35]
	v_mfma_f32_16x16x32_bf16 v[20:23], v[192:195], v[160:163], v[20:23]
	v_mfma_f32_16x16x32_bf16 v[16:19], v[200:203], v[160:163], v[16:19]
	v_mfma_f32_16x16x32_bf16 v[4:7], v[192:195], v[168:171], v[4:7]
	v_mfma_f32_16x16x32_bf16 v[0:3], v[200:203], v[168:171], v[0:3]
	v_mfma_f32_16x16x32_bf16 v[52:55], v[196:199], v[148:151], v[52:55]
	v_mfma_f32_16x16x32_bf16 v[48:51], v[210:213], v[148:151], v[48:51]
	v_mfma_f32_16x16x32_bf16 v[36:39], v[196:199], v[156:159], v[36:39]
	v_mfma_f32_16x16x32_bf16 v[32:35], v[210:213], v[156:159], v[32:35]
	v_mfma_f32_16x16x32_bf16 v[20:23], v[196:199], v[164:167], v[20:23]
	v_mfma_f32_16x16x32_bf16 v[16:19], v[210:213], v[164:167], v[16:19]
	v_mfma_f32_16x16x32_bf16 v[4:7], v[196:199], v[172:175], v[4:7]
	v_mfma_f32_16x16x32_bf16 v[0:3], v[210:213], v[172:175], v[0:3]
	s_add_i32 s53, s53, 2
	s_add_u32 s20, s20, 0x100
	s_addc_u32 s21, s21, 0
	s_add_u32 s51, s51, 0x100
	s_addc_u32 s52, s52, 0
	s_cmp_gt_u32 s53, 29
	s_barrier
	s_cbranch_scc0 .LBB0_670
; __device__ __forceinline__ unsigned cvt_pk_bf16(float lo, float hi) { unsigned r; asm volatile("v_cvt_pk_bf16_f32 %0, %1, %2" : "=v"(r) : "v"(lo), "v"(hi)); return r; }
; __device__ __forceinline__ float bflo(unsigned w) { return __uint_as_float(w << 16); }
; __device__ __forceinline__ float bfhi(unsigned w) { return __uint_as_float(w & 0xffff0000u); }
;     __device__ __forceinline__ void operator()(f32x4 (&acc)[2][2][4][2], const Unit& u, int wr, int wc, int fr, int fq) const {
;         const int row0 = u.pm * BM + wr * 64 + fr, col0 = u.pn * BM + wc * 32 + 8 * fq;
; #pragma unroll
;         for (int ai = 0; ai < 2; ++ai) {
;             f32x4 r[4][2][2];
; #pragma unroll
;             for (int m = 0; m < 4; ++m)
; #pragma unroll
;                 for (int bj = 0; bj < 2; ++bj) { const size_t o = (size_t)(row0 + ai * HALF + m * 16) * DM + col0 + bj * HALF;
;                     if (RB) { const u32x4 w = *(const u32x4*)((const bf16_t*)res + o); r[m][bj][0] = (f32x4){bflo(w.x), bfhi(w.x), bflo(w.y), bfhi(w.y)}; r[m][bj][1] = (f32x4){bflo(w.z), bfhi(w.z), bflo(w.w), bfhi(w.w)}; }
;                     else { r[m][bj][0] = __builtin_nontemporal_load((const f32x4*)((const float*)res + o)); r[m][bj][1] = __builtin_nontemporal_load((const f32x4*)((const float*)res + o + 4)); } }
; #pragma unroll
;             for (int m = 0; m < 4; ++m) { const int row = row0 + ai * HALF + m * 16; const size_t off = (size_t)row * DM + col0; float s = 0.f;
; #pragma unroll
;                 for (int bj = 0; bj < 2; ++bj) { const f32x4 v0 = acc[ai][bj][m][0] + r[m][bj][0], v1 = acc[ai][bj][m][1] + r[m][bj][1];
;                     u32x4 w; w.x = cvt_pk_bf16(v0[0], v0[1]); w.y = cvt_pk_bf16(v0[2], v0[3]); w.z = cvt_pk_bf16(v1[0], v1[1]); w.w = cvt_pk_bf16(v1[2], v1[3]);
;                     *(u32x4*)(outb + off + bj * HALF) = w;
;                     s += ((v0[0] * v0[0] + v0[1] * v0[1]) + (v0[2] * v0[2] + v0[3] * v0[3])) + ((v1[0] * v1[0] + v1[1] * v1[1]) + (v1[2] * v1[2] + v1[3] * v1[3])); }
;                 s += __shfl_xor(s, 16); s += __shfl_xor(s, 32);
;                 if (fq == 0) ssq[(size_t)row * 32 + u.pn * 4 + wc] = s; }
	v_mbcnt_lo_u32_b32 v128, -1, 0
	v_mbcnt_hi_u32_b32 v128, -1, v128
	s_lshl_b32 s9, s18, 8
	v_ashrrev_i32_e32 v210, 4, v128
	v_and_b32_e32 v128, 15, v128
	s_add_i32 s9, s9, s22
	v_readlane_b32 s11, v254, 19
	v_add_u32_e32 v194, s9, v128
	s_lshl_b32 s9, s2, 8
	s_or_b32 s9, s9, s11
	v_lshl_add_u32 v192, v210, 3, s9
	v_ashrrev_i32_e32 v193, 31, v192
	v_ashrrev_i32_e32 v195, 31, v194
	v_lshl_add_u64 v[196:197], v[192:193], 2, s[56:57]
	v_lshlrev_b64 v[128:129], 13, v[194:195]
	v_lshl_add_u64 v[128:129], v[196:197], 0, v[128:129]
	global_load_dwordx4 v[212:215], v[128:129], off nt
	global_load_dwordx4 v[216:219], v[128:129], off offset:16 nt
	global_load_dwordx4 v[220:223], v[128:129], off offset:512 nt
	global_load_dwordx4 v[224:227], v[128:129], off offset:528 nt
	v_add_u32_e32 v202, 16, v194
	v_add_u32_e32 v200, 32, v194
	v_add_u32_e32 v198, 48, v194
	v_ashrrev_i32_e32 v203, 31, v202
	v_ashrrev_i32_e32 v201, 31, v200
	v_ashrrev_i32_e32 v199, 31, v198
	v_lshlrev_b64 v[128:129], 13, v[202:203]
	v_lshlrev_b64 v[130:131], 13, v[200:201]
	v_lshlrev_b64 v[132:133], 13, v[198:199]
	v_lshl_add_u64 v[128:129], v[196:197], 0, v[128:129]
	v_lshl_add_u64 v[130:131], v[196:197], 0, v[130:131]
	v_lshl_add_u64 v[132:133], v[196:197], 0, v[132:133]
	global_load_dwordx4 v[168:171], v[128:129], off offset:16 nt
	global_load_dwordx4 v[172:175], v[128:129], off nt
	global_load_dwordx4 v[160:163], v[128:129], off offset:528 nt
	global_load_dwordx4 v[164:167], v[128:129], off offset:512 nt
	global_load_dwordx4 v[152:155], v[130:131], off offset:16 nt
	global_load_dwordx4 v[156:159], v[130:131], off nt
	global_load_dwordx4 v[144:147], v[130:131], off offset:528 nt
	global_load_dwordx4 v[148:151], v[130:131], off offset:512 nt
	global_load_dwordx4 v[136:139], v[132:133], off offset:16 nt
	global_load_dwordx4 v[140:143], v[132:133], off nt
	s_nop 0
	global_load_dwordx4 v[128:131], v[132:133], off offset:528 nt
	s_nop 0
	global_load_dwordx4 v[132:135], v[132:133], off offset:512 nt
	v_and_b32_e32 v228, 64, v209
	v_xor_b32_e32 v211, 16, v209
	v_add_u32_e32 v228, 64, v228
	v_xor_b32_e32 v229, 32, v209
	v_cmp_lt_i32_e32 vcc, v211, v228
	s_lshl_b32 s18, s2, 2
	s_ashr_i32 s19, s18, 31
	v_cndmask_b32_e32 v211, v209, v211, vcc
	v_cmp_lt_i32_e32 vcc, v229, v228
	s_waitcnt vmcnt(0)
	v_pk_add_f32 v[126:127], v[126:127], v[214:215]
	v_pk_add_f32 v[124:125], v[124:125], v[212:213]
	v_pk_add_f32 v[122:123], v[122:123], v[218:219]
	v_pk_add_f32 v[120:121], v[120:121], v[216:217]
	v_pk_add_f32 v[118:119], v[118:119], v[222:223]
	v_pk_add_f32 v[116:117], v[116:117], v[220:221]
	v_pk_add_f32 v[212:213], v[114:115], v[226:227]
	v_pk_add_f32 v[214:215], v[112:113], v[224:225]
	v_cndmask_b32_e32 v230, v209, v229, vcc
	v_cmp_eq_u32_e32 vcc, 0, v210
	v_lshlrev_b32_e32 v210, 2, v211
	v_cvt_pk_bf16_f32 v112, v124, v125
	v_cvt_pk_bf16_f32 v113, v126, v127
	v_mul_f32_e32 v114, v125, v125
	v_mul_f32_e32 v115, v127, v127
	v_mul_f32_e32 v125, v121, v121
	v_mul_f32_e32 v127, v123, v123
	v_mul_f32_e32 v211, v117, v117
	v_mul_f32_e32 v216, v119, v119
	v_mul_f32_e32 v217, v215, v215
	v_mul_f32_e32 v218, v213, v213
	v_fmac_f32_e32 v114, v124, v124
	v_fmac_f32_e32 v115, v126, v126
	v_fmac_f32_e32 v125, v120, v120
	v_fmac_f32_e32 v127, v122, v122
	v_fmac_f32_e32 v211, v116, v116
	v_fmac_f32_e32 v216, v118, v118
	v_fmac_f32_e32 v217, v214, v214
	v_fmac_f32_e32 v218, v212, v212
	v_add_f32_e32 v114, v114, v115
	v_add_f32_e32 v115, v125, v127
	v_add_f32_e32 v124, v211, v216
	v_add_f32_e32 v125, v217, v218
	v_add_f32_e32 v114, v114, v115
	v_add_f32_e32 v115, v124, v125
	v_add_f32_e32 v124, v114, v115
	ds_bpermute_b32 v125, v210, v124
	v_lshlrev_b64 v[228:229], 12, v[194:195]
	v_lshl_add_u64 v[228:229], s[6:7], 0, v[228:229]
	v_lshl_add_u64 v[228:229], v[192:193], 1, v[228:229]
	v_cvt_pk_bf16_f32 v114, v120, v121
	v_cvt_pk_bf16_f32 v115, v122, v123
	global_store_dwordx4 v[228:229], v[112:115], off
	v_lshlrev_b32_e32 v120, 2, v230
	s_waitcnt lgkmcnt(0)
	v_add_f32_e32 v112, v124, v125
	ds_bpermute_b32 v113, v120, v112
	v_cvt_pk_bf16_f32 v114, v116, v117
	v_cvt_pk_bf16_f32 v115, v118, v119
	v_cvt_pk_bf16_f32 v116, v214, v215
	v_cvt_pk_bf16_f32 v117, v212, v213
	global_store_dwordx4 v[228:229], v[114:117], off offset:256
	s_and_saveexec_b64 s[20:21], vcc
	s_cbranch_execz .LBB0_673
	v_lshlrev_b64 v[114:115], 7, v[194:195]
	v_lshl_add_u64 v[114:115], s[16:17], 0, v[114:115]
	v_lshl_add_u64 v[114:115], s[18:19], 2, v[114:115]
	s_lshl_b32 s2, s27, 2
	v_lshl_add_u64 v[114:115], v[114:115], 0, s[2:3]
	s_waitcnt lgkmcnt(0)
	v_add_f32_e32 v112, v112, v113
	global_store_dword v[114:115], v112, off

; #define PG8_STAGE(bufoff, gbase, voff) do { _Pragma("unroll") for (int _i = 0; _i < 2; ++_i) \
;         __builtin_amdgcn_global_load_lds((const unsigned*)((const char*)(gbase) + (voff)[_i]), (LAS unsigned*)(lds + (bufoff) + ldsw + _i * 8192), 16, 0, 0); } while (0)
; #define PG8_LDA(dst, b, h) do { _Pragma("unroll") for (int m = 0; m < 4; ++m) _Pragma("unroll") for (int k = 0; k < 2; ++k) dst[m][k] = *(const LAS bf16x8*)(lds + PG8_SA(b, h) + aoff + m * 2048 + k * 1024); } while (0)
; #define PG8_LDB(dst, b, h) do { _Pragma("unroll") for (int n = 0; n < 2; ++n) _Pragma("unroll") for (int k = 0; k < 2; ++k) dst[n][k] = *(const LAS bf16x8*)(lds + PG8_SB(b, h) + boff + n * 2048 + k * 1024); } while (0)
; #define PG8_MMA(ai, bj, At, Bt) do { __builtin_amdgcn_s_setprio(1); _Pragma("unroll") for (int m = 0; m < 4; ++m) _Pragma("unroll") for (int n = 0; n < 2; ++n) _Pragma("unroll") for (int k = 0; k < 2; ++k) \
;         acc[ai][bj][m][n] = __builtin_amdgcn_mfma_f32_16x16x32_bf16(Bt[n][k], At[m][k], acc[ai][bj][m][n], 0, 0, 0); __builtin_amdgcn_s_setprio(0); } while (0)
; #define PG8_WAIT_L(n) asm volatile("s_waitcnt lgkmcnt(" #n ")" ::: "memory")
; #define PG8_BAR __builtin_amdgcn_s_barrier()
; #define PG8_SCHED __builtin_amdgcn_sched_barrier(0)
; template <class Epi, bool KS0 = false>
; __device__ __forceinline__ void gemm_phase(const int WID, LAS unsigned char* lds, const Gemm g, const StaticOrder& S, const Epi& E) {
;     ...
;         for (int t = 0; t < nt; t += 2) {
;             const bool last = (t == nt - 2);
;             const char* a1 = cA + (size_t)(t + 1) * kstep;
;             const char* a2 = last ? nA : cA + (size_t)(t + 2) * kstep; const char* b2 = last ? nB : cB + (size_t)(t + 2) * kstep;
;             const char* a3 = a2 + kstep; const char* b3 = b2 + kstep;
;             PG8_LDB(B0, 0, 0); PG8_SCHED; PG8_LDA(At, 0, 0); PG8_STAGE(PG8_SA(1, 1), a1 + hstep, voffA);
;             PG8_WAIT_L(8); PG8_BAR; PG8_WAIT_L(0); PG8_MMA(0, 0, At, B0); PG8_BAR; PG8_SCHED;
;             PG8_LDB(B1, 0, 1); PG8_STAGE(PG8_SB(0, 0), b2, voffB);
;             PG8_BAR; PG8_WAIT_L(0); PG8_MMA(0, 1, At, B1); PG8_BAR;
;             PG8_LDA(At, 0, 1); PG8_STAGE(PG8_SA(0, 0), a2, voffA);
;             PG8_BAR; PG8_WAIT_L(0); PG8_MMA(1, 0, At, B0); PG8_BAR; PG8_SCHED;
.LBB0_703:
	s_add_u32 s43, s20, s42
	s_addc_u32 s53, s21, 0
	s_add_u32 s48, s43, 0x100
	s_addc_u32 s49, s53, 0
	s_and_b64 s[44:45], s[34:35], exec
	s_cselect_b32 s49, s11, s49
	s_cselect_b32 s48, s63, s48
	s_add_u32 s42, s18, s42
	s_addc_u32 s44, s19, 0
	s_add_u32 s42, s42, 0x100
	s_addc_u32 s44, s44, 0
	s_and_b64 s[34:35], s[34:35], exec
	s_cselect_b32 s51, s9, s44
	s_cselect_b32 s50, s64, s42
	s_add_u32 s52, s43, 0x10080
	s_addc_u32 s53, s53, 0
	s_add_i32 s75, s59, s26
	s_add_i32 m0, s29, 0xc000
	s_add_i32 s80, s29, 0xe000
	s_add_i32 s74, s75, 0x2000
	s_add_u32 s44, s50, 0x10000
	s_addc_u32 s45, s51, 0
	s_add_i32 s73, s60, s26
	ds_read_b128 v[146:149], v143
	ds_read_b128 v[150:153], v143 offset:1024
	ds_read_b128 v[154:157], v143 offset:2048
	ds_read_b128 v[158:161], v143 offset:3072
	s_add_i32 s71, s73, 0x2000
	s_add_i32 s70, 0, 0x18000
	s_add_u32 s42, s48, 0x10000
	s_addc_u32 s43, s49, 0
	s_add_i32 s69, s70, s26
	s_add_i32 s68, 0, 0x1c000
	s_add_i32 s67, s69, 0x2000
	s_add_u32 s34, s50, 0x10080
	s_addc_u32 s35, s51, 0
	s_add_i32 s66, s68, s26
	s_add_i32 s65, s66, 0x2000
	v_lshl_add_u64 v[140:141], s[52:53], 0, v[134:135]
	ds_read_b128 v[162:165], v144
	ds_read_b128 v[166:169], v144 offset:1024
	ds_read_b128 v[170:173], v144 offset:2048
	ds_read_b128 v[174:177], v144 offset:3072
	ds_read_b128 v[178:181], v144 offset:4096
	ds_read_b128 v[182:185], v144 offset:5120
	ds_read_b128 v[186:189], v144 offset:6144
	ds_read_b128 v[190:193], v144 offset:7168
	global_load_lds_dwordx4 v[140:141], off
	v_lshl_add_u64 v[140:141], s[52:53], 0, v[130:131]
	s_mov_b32 m0, s80
	s_nop 0
	global_load_lds_dwordx4 v[140:141], off
	s_waitcnt lgkmcnt(8)
	s_barrier
	s_waitcnt lgkmcnt(0)
	s_waitcnt lgkmcnt(0)
	v_mfma_f32_16x16x32_bf16 v[124:127], v[146:149], v[162:165], v[124:127]
	v_mfma_f32_16x16x32_bf16 v[120:123], v[154:157], v[162:165], v[120:123]
	v_mfma_f32_16x16x32_bf16 v[112:115], v[146:149], v[170:173], v[112:115]
	v_mfma_f32_16x16x32_bf16 v[104:107], v[154:157], v[170:173], v[104:107]
	v_mfma_f32_16x16x32_bf16 v[100:103], v[146:149], v[178:181], v[100:103]
	v_mfma_f32_16x16x32_bf16 v[92:95], v[154:157], v[178:181], v[92:95]
	v_mfma_f32_16x16x32_bf16 v[84:87], v[146:149], v[186:189], v[84:87]
	v_mfma_f32_16x16x32_bf16 v[76:79], v[154:157], v[186:189], v[76:79]
	v_mfma_f32_16x16x32_bf16 v[124:127], v[150:153], v[166:169], v[124:127]
	v_mfma_f32_16x16x32_bf16 v[120:123], v[158:161], v[166:169], v[120:123]
	v_mfma_f32_16x16x32_bf16 v[112:115], v[150:153], v[174:177], v[112:115]
	v_mfma_f32_16x16x32_bf16 v[104:107], v[158:161], v[174:177], v[104:107]
	v_mfma_f32_16x16x32_bf16 v[100:103], v[150:153], v[182:185], v[100:103]
	v_mfma_f32_16x16x32_bf16 v[92:95], v[158:161], v[182:185], v[92:95]
	v_mfma_f32_16x16x32_bf16 v[84:87], v[150:153], v[190:193], v[84:87]
	v_mfma_f32_16x16x32_bf16 v[76:79], v[158:161], v[190:193], v[76:79]
	s_barrier
	s_mov_b32 m0, s75
	v_lshl_add_u64 v[140:141], s[50:51], 0, v[132:133]
	ds_read_b128 v[194:197], v145
	ds_read_b128 v[198:201], v145 offset:1024
	ds_read_b128 v[210:213], v145 offset:2048
	ds_read_b128 v[214:217], v145 offset:3072
	global_load_lds_dwordx4 v[140:141], off
	v_lshl_add_u64 v[202:203], s[50:51], 0, v[128:129]
	s_mov_b32 m0, s74
	s_nop 0
	global_load_lds_dwordx4 v[202:203], off
	s_barrier
	s_waitcnt lgkmcnt(0)
	s_waitcnt lgkmcnt(0)
	v_mfma_f32_16x16x32_bf16 v[116:119], v[194:197], v[162:165], v[116:119]
	v_mfma_f32_16x16x32_bf16 v[108:111], v[210:213], v[162:165], v[108:111]
	v_mfma_f32_16x16x32_bf16 v[96:99], v[194:197], v[170:173], v[96:99]
	v_mfma_f32_16x16x32_bf16 v[88:91], v[210:213], v[170:173], v[88:91]
	v_mfma_f32_16x16x32_bf16 v[80:83], v[194:197], v[178:181], v[80:83]
	v_mfma_f32_16x16x32_bf16 v[72:75], v[210:213], v[178:181], v[72:75]
	v_mfma_f32_16x16x32_bf16 v[68:71], v[194:197], v[186:189], v[68:71]
	v_mfma_f32_16x16x32_bf16 v[64:67], v[210:213], v[186:189], v[64:67]
	v_mfma_f32_16x16x32_bf16 v[116:119], v[198:201], v[166:169], v[116:119]
	v_mfma_f32_16x16x32_bf16 v[108:111], v[214:217], v[166:169], v[108:111]
	v_mfma_f32_16x16x32_bf16 v[96:99], v[198:201], v[174:177], v[96:99]
	v_mfma_f32_16x16x32_bf16 v[88:91], v[214:217], v[174:177], v[88:91]
	v_mfma_f32_16x16x32_bf16 v[80:83], v[198:201], v[182:185], v[80:83]
	v_mfma_f32_16x16x32_bf16 v[72:75], v[214:217], v[182:185], v[72:75]
	v_mfma_f32_16x16x32_bf16 v[68:71], v[198:201], v[190:193], v[68:71]
	v_mfma_f32_16x16x32_bf16 v[64:67], v[214:217], v[190:193], v[64:67]
	s_mov_b32 m0, s29
	v_lshl_add_u64 v[206:207], s[48:49], 0, v[134:135]
	s_barrier
	ds_read_b128 v[162:165], v144 offset:16384
	ds_read_b128 v[166:169], v144 offset:17408
	ds_read_b128 v[170:173], v144 offset:18432
	ds_read_b128 v[174:177], v144 offset:19456
	ds_read_b128 v[178:181], v144 offset:20480
	ds_read_b128 v[182:185], v144 offset:21504
	ds_read_b128 v[186:189], v144 offset:22528
	ds_read_b128 v[190:193], v144 offset:23552
	global_load_lds_dwordx4 v[206:207], off
	v_lshl_add_u64 v[218:219], s[48:49], 0, v[130:131]
	s_mov_b32 m0, s54
	s_nop 0
	global_load_lds_dwordx4 v[218:219], off
	s_barrier
	s_waitcnt lgkmcnt(0)
	s_waitcnt lgkmcnt(0)
	v_mfma_f32_16x16x32_bf16 v[60:63], v[146:149], v[162:165], v[60:63]
	v_mfma_f32_16x16x32_bf16 v[56:59], v[154:157], v[162:165], v[56:59]
	v_mfma_f32_16x16x32_bf16 v[52:55], v[146:149], v[170:173], v[52:55]
	v_mfma_f32_16x16x32_bf16 v[44:47], v[154:157], v[170:173], v[44:47]
	v_mfma_f32_16x16x32_bf16 v[36:39], v[146:149], v[178:181], v[36:39]
	v_mfma_f32_16x16x32_bf16 v[28:31], v[154:157], v[178:181], v[28:31]
	v_mfma_f32_16x16x32_bf16 v[20:23], v[146:149], v[186:189], v[20:23]
	v_mfma_f32_16x16x32_bf16 v[12:15], v[154:157], v[186:189], v[12:15]
	v_mfma_f32_16x16x32_bf16 v[60:63], v[150:153], v[166:169], v[60:63]
	v_mfma_f32_16x16x32_bf16 v[56:59], v[158:161], v[166:169], v[56:59]
	v_mfma_f32_16x16x32_bf16 v[52:55], v[150:153], v[174:177], v[52:55]
	v_mfma_f32_16x16x32_bf16 v[44:47], v[158:161], v[174:177], v[44:47]
	v_mfma_f32_16x16x32_bf16 v[36:39], v[150:153], v[182:185], v[36:39]
	v_mfma_f32_16x16x32_bf16 v[28:31], v[158:161], v[182:185], v[28:31]
	v_mfma_f32_16x16x32_bf16 v[20:23], v[150:153], v[190:193], v[20:23]
	v_mfma_f32_16x16x32_bf16 v[12:15], v[158:161], v[190:193], v[12:15]
	s_barrier
; #define PG8_STAGE(bufoff, gbase, voff) do { _Pragma("unroll") for (int _i = 0; _i < 2; ++_i) \
;         __builtin_amdgcn_global_load_lds((const unsigned*)((const char*)(gbase) + (voff)[_i]), (LAS unsigned*)(lds + (bufoff) + ldsw + _i * 8192), 16, 0, 0); } while (0)
; #define PG8_LDA(dst, b, h) do { _Pragma("unroll") for (int m = 0; m < 4; ++m) _Pragma("unroll") for (int k = 0; k < 2; ++k) dst[m][k] = *(const LAS bf16x8*)(lds + PG8_SA(b, h) + aoff + m * 2048 + k * 1024); } while (0)
; #define PG8_LDB(dst, b, h) do { _Pragma("unroll") for (int n = 0; n < 2; ++n) _Pragma("unroll") for (int k = 0; k < 2; ++k) dst[n][k] = *(const LAS bf16x8*)(lds + PG8_SB(b, h) + boff + n * 2048 + k * 1024); } while (0)
; #define PG8_MMA(ai, bj, At, Bt) do { __builtin_amdgcn_s_setprio(1); _Pragma("unroll") for (int m = 0; m < 4; ++m) _Pragma("unroll") for (int n = 0; n < 2; ++n) _Pragma("unroll") for (int k = 0; k < 2; ++k) \
;         acc[ai][bj][m][n] = __builtin_amdgcn_mfma_f32_16x16x32_bf16(Bt[n][k], At[m][k], acc[ai][bj][m][n], 0, 0, 0); __builtin_amdgcn_s_setprio(0); } while (0)
; #define PG8_WAIT_V(n) asm volatile("s_waitcnt vmcnt(" #n ")" ::: "memory")
; #define PG8_WAIT_L(n) asm volatile("s_waitcnt lgkmcnt(" #n ")" ::: "memory")
; #define PG8_BAR __builtin_amdgcn_s_barrier()
; #define PG8_SCHED __builtin_amdgcn_sched_barrier(0)
; template <class Epi, bool KS0 = false>
; __device__ __forceinline__ void gemm_phase(const int WID, LAS unsigned char* lds, const Gemm g, const StaticOrder& S, const Epi& E) {
;     ...
;             PG8_STAGE(PG8_SB(0, 1), b2 + hstep, voffB);
;             PG8_WAIT_V(6); PG8_BAR; PG8_MMA(1, 1, At, B1); PG8_BAR;
;             PG8_LDB(B0, 1, 0); PG8_SCHED; PG8_LDA(At, 1, 0); PG8_STAGE(PG8_SA(0, 1), a2 + hstep, voffA);
;             PG8_WAIT_L(8); PG8_BAR; PG8_WAIT_L(0); PG8_MMA(0, 0, At, B0); PG8_BAR; PG8_SCHED;
;             PG8_LDB(B1, 1, 1); PG8_STAGE(PG8_SB(1, 0), b3, voffB);
;             PG8_BAR; PG8_WAIT_L(0); PG8_MMA(0, 1, At, B1); PG8_BAR;
	s_mov_b32 m0, s73
	v_lshl_add_u64 v[146:147], s[44:45], 0, v[132:133]
	global_load_lds_dwordx4 v[146:147], off
	v_lshl_add_u64 v[146:147], s[44:45], 0, v[128:129]
	s_mov_b32 m0, s71
	s_nop 0
	global_load_lds_dwordx4 v[146:147], off
	s_waitcnt vmcnt(6)
	s_barrier
	v_mfma_f32_16x16x32_bf16 v[48:51], v[194:197], v[162:165], v[48:51]
	v_mfma_f32_16x16x32_bf16 v[40:43], v[210:213], v[162:165], v[40:43]
	v_mfma_f32_16x16x32_bf16 v[32:35], v[194:197], v[170:173], v[32:35]
	v_mfma_f32_16x16x32_bf16 v[24:27], v[210:213], v[170:173], v[24:27]
	v_mfma_f32_16x16x32_bf16 v[16:19], v[194:197], v[178:181], v[16:19]
	v_mfma_f32_16x16x32_bf16 v[8:11], v[210:213], v[178:181], v[8:11]
	v_mfma_f32_16x16x32_bf16 v[4:7], v[194:197], v[186:189], v[4:7]
	v_mfma_f32_16x16x32_bf16 v[0:3], v[210:213], v[186:189], v[0:3]
	v_mfma_f32_16x16x32_bf16 v[48:51], v[198:201], v[166:169], v[48:51]
	v_mfma_f32_16x16x32_bf16 v[40:43], v[214:217], v[166:169], v[40:43]
	v_mfma_f32_16x16x32_bf16 v[32:35], v[198:201], v[174:177], v[32:35]
	v_mfma_f32_16x16x32_bf16 v[24:27], v[214:217], v[174:177], v[24:27]
	v_mfma_f32_16x16x32_bf16 v[16:19], v[198:201], v[182:185], v[16:19]
	v_mfma_f32_16x16x32_bf16 v[8:11], v[214:217], v[182:185], v[8:11]
	v_mfma_f32_16x16x32_bf16 v[4:7], v[198:201], v[190:193], v[4:7]
	v_mfma_f32_16x16x32_bf16 v[0:3], v[214:217], v[190:193], v[0:3]
	v_add_u32_e32 v158, s70, v142
	s_barrier
	ds_read_b128 v[146:149], v158
	ds_read_b128 v[150:153], v158 offset:1024
	ds_read_b128 v[154:157], v158 offset:2048
	ds_read_b128 v[158:161], v158 offset:3072
	s_mov_b32 m0, s55
	v_lshl_add_u64 v[194:195], s[42:43], 0, v[134:135]
	ds_read_b128 v[162:165], v144 offset:32768
	ds_read_b128 v[166:169], v144 offset:33792
	ds_read_b128 v[170:173], v144 offset:34816
	ds_read_b128 v[174:177], v144 offset:35840
	ds_read_b128 v[178:181], v144 offset:36864
	ds_read_b128 v[182:185], v144 offset:37888
	ds_read_b128 v[186:189], v144 offset:38912
	ds_read_b128 v[190:193], v144 offset:39936
	global_load_lds_dwordx4 v[194:195], off
	v_lshl_add_u64 v[194:195], s[42:43], 0, v[130:131]
	s_mov_b32 m0, s56
	s_nop 0
	global_load_lds_dwordx4 v[194:195], off
	s_waitcnt lgkmcnt(8)
	s_barrier
	s_waitcnt lgkmcnt(0)
	s_waitcnt lgkmcnt(0)
	v_mfma_f32_16x16x32_bf16 v[124:127], v[146:149], v[162:165], v[124:127]
	v_mfma_f32_16x16x32_bf16 v[120:123], v[154:157], v[162:165], v[120:123]
	v_mfma_f32_16x16x32_bf16 v[112:115], v[146:149], v[170:173], v[112:115]
	v_mfma_f32_16x16x32_bf16 v[104:107], v[154:157], v[170:173], v[104:107]
	v_mfma_f32_16x16x32_bf16 v[100:103], v[146:149], v[178:181], v[100:103]
	v_mfma_f32_16x16x32_bf16 v[92:95], v[154:157], v[178:181], v[92:95]
	v_mfma_f32_16x16x32_bf16 v[84:87], v[146:149], v[186:189], v[84:87]
	v_mfma_f32_16x16x32_bf16 v[76:79], v[154:157], v[186:189], v[76:79]
	v_mfma_f32_16x16x32_bf16 v[124:127], v[150:153], v[166:169], v[124:127]
	v_mfma_f32_16x16x32_bf16 v[120:123], v[158:161], v[166:169], v[120:123]
	v_mfma_f32_16x16x32_bf16 v[112:115], v[150:153], v[174:177], v[112:115]
	v_mfma_f32_16x16x32_bf16 v[104:107], v[158:161], v[174:177], v[104:107]
	v_mfma_f32_16x16x32_bf16 v[100:103], v[150:153], v[182:185], v[100:103]
	v_mfma_f32_16x16x32_bf16 v[92:95], v[158:161], v[182:185], v[92:95]
	v_mfma_f32_16x16x32_bf16 v[84:87], v[150:153], v[190:193], v[84:87]
	v_mfma_f32_16x16x32_bf16 v[76:79], v[158:161], v[190:193], v[76:79]
	s_barrier
	s_mov_b32 m0, s69
	v_add_u32_e32 v205, s68, v142
	v_lshl_add_u64 v[140:141], v[140:141], 0, s[2:3]
	ds_read_b128 v[194:197], v205
	ds_read_b128 v[198:201], v205 offset:1024
	ds_read_b128 v[210:213], v205 offset:2048
	ds_read_b128 v[214:217], v205 offset:3072
	global_load_lds_dwordx4 v[140:141], off
	v_lshl_add_u64 v[140:141], v[202:203], 0, s[2:3]
	s_mov_b32 m0, s67
	s_nop 0
	global_load_lds_dwordx4 v[140:141], off
	s_barrier
; __device__ __forceinline__ int lane_id_() { int l; asm volatile("v_mbcnt_lo_u32_b32 %0, -1, 0\n\tv_mbcnt_hi_u32_b32 %0, -1, %0" : "=v"(l)); return l; }
; #define PG8_STAGE(bufoff, gbase, voff) do { _Pragma("unroll") for (int _i = 0; _i < 2; ++_i) \
;         __builtin_amdgcn_global_load_lds((const unsigned*)((const char*)(gbase) + (voff)[_i]), (LAS unsigned*)(lds + (bufoff) + ldsw + _i * 8192), 16, 0, 0); } while (0)
; #define PG8_LDA(dst, b, h) do { _Pragma("unroll") for (int m = 0; m < 4; ++m) _Pragma("unroll") for (int k = 0; k < 2; ++k) dst[m][k] = *(const LAS bf16x8*)(lds + PG8_SA(b, h) + aoff + m * 2048 + k * 1024); } while (0)
; #define PG8_MMA(ai, bj, At, Bt) do { __builtin_amdgcn_s_setprio(1); _Pragma("unroll") for (int m = 0; m < 4; ++m) _Pragma("unroll") for (int n = 0; n < 2; ++n) _Pragma("unroll") for (int k = 0; k < 2; ++k) \
;         acc[ai][bj][m][n] = __builtin_amdgcn_mfma_f32_16x16x32_bf16(Bt[n][k], At[m][k], acc[ai][bj][m][n], 0, 0, 0); __builtin_amdgcn_s_setprio(0); } while (0)
; #define PG8_WAIT_V(n) asm volatile("s_waitcnt vmcnt(" #n ")" ::: "memory")
; #define PG8_WAIT_L(n) asm volatile("s_waitcnt lgkmcnt(" #n ")" ::: "memory")
; #define PG8_BAR __builtin_amdgcn_s_barrier()
; #define PG8_SCHED __builtin_amdgcn_sched_barrier(0)
; template <class Epi, bool KS0 = false>
; __device__ __forceinline__ void gemm_phase(const int WID, LAS unsigned char* lds, const Gemm g, const StaticOrder& S, const Epi& E) {
;     ...
;             PG8_BAR; PG8_WAIT_L(0); PG8_MMA(0, 1, At, B1); PG8_BAR;
;             PG8_LDA(At, 1, 1); PG8_STAGE(PG8_SA(1, 0), a3, voffA);
;             PG8_BAR; PG8_WAIT_L(0); PG8_MMA(1, 0, At, B0); PG8_BAR; PG8_SCHED;
;             PG8_STAGE(PG8_SB(1, 1), b3 + hstep, voffB);
;             PG8_WAIT_V(6); PG8_BAR; PG8_MMA(1, 1, At, B1); PG8_BAR;
;         }
;         { int fr2 = lane_id_(), fq2; fq2 = fr2 >> 4; fr2 &= 15; asm volatile("" : "+v"(fr2), "+v"(fq2)); E(acc, cur, wr, wc, fr2, fq2); }
;         if (!has_next) break;
	s_waitcnt lgkmcnt(0)
	s_waitcnt lgkmcnt(0)
	v_mfma_f32_16x16x32_bf16 v[116:119], v[194:197], v[162:165], v[116:119]
	v_mfma_f32_16x16x32_bf16 v[108:111], v[210:213], v[162:165], v[108:111]
	v_mfma_f32_16x16x32_bf16 v[96:99], v[194:197], v[170:173], v[96:99]
	v_mfma_f32_16x16x32_bf16 v[88:91], v[210:213], v[170:173], v[88:91]
	v_mfma_f32_16x16x32_bf16 v[80:83], v[194:197], v[178:181], v[80:83]
	v_mfma_f32_16x16x32_bf16 v[72:75], v[210:213], v[178:181], v[72:75]
	v_mfma_f32_16x16x32_bf16 v[68:71], v[194:197], v[186:189], v[68:71]
	v_mfma_f32_16x16x32_bf16 v[64:67], v[210:213], v[186:189], v[64:67]
	v_mfma_f32_16x16x32_bf16 v[116:119], v[198:201], v[166:169], v[116:119]
	v_mfma_f32_16x16x32_bf16 v[108:111], v[214:217], v[166:169], v[108:111]
	v_mfma_f32_16x16x32_bf16 v[96:99], v[198:201], v[174:177], v[96:99]
	v_mfma_f32_16x16x32_bf16 v[88:91], v[214:217], v[174:177], v[88:91]
	v_mfma_f32_16x16x32_bf16 v[80:83], v[198:201], v[182:185], v[80:83]
	v_mfma_f32_16x16x32_bf16 v[72:75], v[214:217], v[182:185], v[72:75]
	v_mfma_f32_16x16x32_bf16 v[68:71], v[198:201], v[190:193], v[68:71]
	v_mfma_f32_16x16x32_bf16 v[64:67], v[214:217], v[190:193], v[64:67]
	s_mov_b32 m0, s57
	v_lshl_add_u64 v[140:141], v[206:207], 0, s[2:3]
	s_barrier
	ds_read_b128 v[162:165], v144 offset:49152
	ds_read_b128 v[166:169], v144 offset:50176
	ds_read_b128 v[170:173], v144 offset:51200
	ds_read_b128 v[174:177], v144 offset:52224
	ds_read_b128 v[178:181], v144 offset:53248
	ds_read_b128 v[182:185], v144 offset:54272
	ds_read_b128 v[186:189], v144 offset:55296
	ds_read_b128 v[190:193], v144 offset:56320
	global_load_lds_dwordx4 v[140:141], off
	v_lshl_add_u64 v[140:141], v[218:219], 0, s[2:3]
	s_mov_b32 m0, s58
	s_nop 0
	global_load_lds_dwordx4 v[140:141], off
	s_barrier
	s_waitcnt lgkmcnt(0)
	s_waitcnt lgkmcnt(0)
	v_mfma_f32_16x16x32_bf16 v[60:63], v[146:149], v[162:165], v[60:63]
	v_mfma_f32_16x16x32_bf16 v[56:59], v[154:157], v[162:165], v[56:59]
	v_mfma_f32_16x16x32_bf16 v[52:55], v[146:149], v[170:173], v[52:55]
	v_mfma_f32_16x16x32_bf16 v[44:47], v[154:157], v[170:173], v[44:47]
	v_mfma_f32_16x16x32_bf16 v[36:39], v[146:149], v[178:181], v[36:39]
	v_mfma_f32_16x16x32_bf16 v[28:31], v[154:157], v[178:181], v[28:31]
	v_mfma_f32_16x16x32_bf16 v[20:23], v[146:149], v[186:189], v[20:23]
	v_mfma_f32_16x16x32_bf16 v[12:15], v[154:157], v[186:189], v[12:15]
	v_mfma_f32_16x16x32_bf16 v[60:63], v[150:153], v[166:169], v[60:63]
	v_mfma_f32_16x16x32_bf16 v[56:59], v[158:161], v[166:169], v[56:59]
	v_mfma_f32_16x16x32_bf16 v[52:55], v[150:153], v[174:177], v[52:55]
	v_mfma_f32_16x16x32_bf16 v[44:47], v[158:161], v[174:177], v[44:47]
	v_mfma_f32_16x16x32_bf16 v[36:39], v[150:153], v[182:185], v[36:39]
	v_mfma_f32_16x16x32_bf16 v[28:31], v[158:161], v[182:185], v[28:31]
	v_mfma_f32_16x16x32_bf16 v[20:23], v[150:153], v[190:193], v[20:23]
	v_mfma_f32_16x16x32_bf16 v[12:15], v[158:161], v[190:193], v[12:15]
	s_barrier
	s_mov_b32 m0, s66
	v_lshl_add_u64 v[140:141], s[34:35], 0, v[132:133]
	global_load_lds_dwordx4 v[140:141], off
	v_lshl_add_u64 v[140:141], s[34:35], 0, v[128:129]
	s_mov_b32 m0, s65
	s_nop 0
	global_load_lds_dwordx4 v[140:141], off
	s_waitcnt vmcnt(6)
	s_barrier
	v_mfma_f32_16x16x32_bf16 v[48:51], v[194:197], v[162:165], v[48:51]
	v_mfma_f32_16x16x32_bf16 v[40:43], v[210:213], v[162:165], v[40:43]
	v_mfma_f32_16x16x32_bf16 v[32:35], v[194:197], v[170:173], v[32:35]
	v_mfma_f32_16x16x32_bf16 v[24:27], v[210:213], v[170:173], v[24:27]
	v_mfma_f32_16x16x32_bf16 v[16:19], v[194:197], v[178:181], v[16:19]
	v_mfma_f32_16x16x32_bf16 v[8:11], v[210:213], v[178:181], v[8:11]
	v_mfma_f32_16x16x32_bf16 v[4:7], v[194:197], v[186:189], v[4:7]
	v_mfma_f32_16x16x32_bf16 v[0:3], v[210:213], v[186:189], v[0:3]
	v_mfma_f32_16x16x32_bf16 v[48:51], v[198:201], v[166:169], v[48:51]
	v_mfma_f32_16x16x32_bf16 v[40:43], v[214:217], v[166:169], v[40:43]
	v_mfma_f32_16x16x32_bf16 v[32:35], v[198:201], v[174:177], v[32:35]
	v_mfma_f32_16x16x32_bf16 v[24:27], v[214:217], v[174:177], v[24:27]
	v_mfma_f32_16x16x32_bf16 v[16:19], v[198:201], v[182:185], v[16:19]
	v_mfma_f32_16x16x32_bf16 v[8:11], v[214:217], v[182:185], v[8:11]
	v_mfma_f32_16x16x32_bf16 v[4:7], v[198:201], v[190:193], v[4:7]
	v_mfma_f32_16x16x32_bf16 v[0:3], v[214:217], v[190:193], v[0:3]
	s_movk_i32 s42, 0x100
	s_andn2_b64 vcc, exec, s[30:31]
	s_mov_b64 s[34:35], -1
	s_mov_b64 s[30:31], 0
	s_barrier
	s_cbranch_vccz .LBB0_703
	v_mbcnt_lo_u32_b32 v140, -1, 0
	v_mbcnt_hi_u32_b32 v140, -1, v140
	s_cmp_lt_i32 s62, 0
	v_ashrrev_i32_e32 v141, 4, v140
	v_and_b32_e32 v146, 15, v140
	s_mov_b64 s[18:19], -1
	s_cbranch_scc1 .LBB0_706
	v_readlane_b32 s9, v251, 37
	v_lshlrev_b32_e32 v147, 7, v141
	s_mov_b64 s[18:19], 0
	v_add_u32_e32 v140, s9, v146
	v_lshl_add_u32 v140, v140, 3, v147

; #define PG8_STAGE(bufoff, gbase, voff) do { _Pragma("unroll") for (int _i = 0; _i < 2; ++_i) \
;         __builtin_amdgcn_global_load_lds((const unsigned*)((const char*)(gbase) + (voff)[_i]), (LAS unsigned*)(lds + (bufoff) + ldsw + _i * 8192), 16, 0, 0); } while (0)
; #define PG8_LDA(dst, b, h) do { _Pragma("unroll") for (int m = 0; m < 4; ++m) _Pragma("unroll") for (int k = 0; k < 2; ++k) dst[m][k] = *(const LAS bf16x8*)(lds + PG8_SA(b, h) + aoff + m * 2048 + k * 1024); } while (0)
; #define PG8_LDB(dst, b, h) do { _Pragma("unroll") for (int n = 0; n < 2; ++n) _Pragma("unroll") for (int k = 0; k < 2; ++k) dst[n][k] = *(const LAS bf16x8*)(lds + PG8_SB(b, h) + boff + n * 2048 + k * 1024); } while (0)
; #define PG8_MMA(ai, bj, At, Bt) do { __builtin_amdgcn_s_setprio(1); _Pragma("unroll") for (int m = 0; m < 4; ++m) _Pragma("unroll") for (int n = 0; n < 2; ++n) _Pragma("unroll") for (int k = 0; k < 2; ++k) \
;         acc[ai][bj][m][n] = __builtin_amdgcn_mfma_f32_16x16x32_bf16(Bt[n][k], At[m][k], acc[ai][bj][m][n], 0, 0, 0); __builtin_amdgcn_s_setprio(0); } while (0)
; #define PG8_WAIT_L(n) asm volatile("s_waitcnt lgkmcnt(" #n ")" ::: "memory")
; #define PG8_BAR __builtin_amdgcn_s_barrier()
; #define PG8_SCHED __builtin_amdgcn_sched_barrier(0)
; template <class Epi, bool KS0 = false>
; __device__ __forceinline__ void gemm_phase(const int WID, LAS unsigned char* lds, const Gemm g, const StaticOrder& S, const Epi& E) {
;     ...
;         for (int t = 0; t < nt; t += 2) {
;             const bool last = (t == nt - 2);
;             const char* a1 = cA + (size_t)(t + 1) * kstep;
;             const char* a2 = last ? nA : cA + (size_t)(t + 2) * kstep; const char* b2 = last ? nB : cB + (size_t)(t + 2) * kstep;
;             const char* a3 = a2 + kstep; const char* b3 = b2 + kstep;
;             PG8_LDB(B0, 0, 0); PG8_SCHED; PG8_LDA(At, 0, 0); PG8_STAGE(PG8_SA(1, 1), a1 + hstep, voffA);
;             PG8_WAIT_L(8); PG8_BAR; PG8_WAIT_L(0); PG8_MMA(0, 0, At, B0); PG8_BAR; PG8_SCHED;
;             PG8_LDB(B1, 0, 1); PG8_STAGE(PG8_SB(0, 0), b2, voffB);
;             PG8_BAR; PG8_WAIT_L(0); PG8_MMA(0, 1, At, B1); PG8_BAR;
;             PG8_LDA(At, 0, 1); PG8_STAGE(PG8_SA(0, 0), a2, voffA);
;             PG8_BAR; PG8_WAIT_L(0); PG8_MMA(1, 0, At, B0); PG8_BAR; PG8_SCHED;
.LBB0_777:
	ds_read_b128 v[108:111], v175
	ds_read_b128 v[132:135], v175 offset:1024
	ds_read_b128 v[136:139], v175 offset:2048
	ds_read_b128 v[152:155], v175 offset:3072
	s_add_u32 s12, s2, 0xfff80080
	s_addc_u32 s13, s3, -1
	s_cmp_eq_u32 s53, 28
	s_cselect_b32 s15, s28, s13
	s_cselect_b32 s14, s29, s12
	s_cselect_b32 s13, s42, s45
	s_cselect_b32 s12, s43, s44
	v_lshl_add_u64 v[196:197], s[2:3], 0, v[144:145]
	s_add_i32 m0, s9, 0xc000
	ds_read_b128 v[156:159], v176
	ds_read_b128 v[160:163], v176 offset:1024
	ds_read_b128 v[164:167], v176 offset:2048
	ds_read_b128 v[168:171], v176 offset:3072
	ds_read_b128 v[180:183], v176 offset:4096
	ds_read_b128 v[184:187], v176 offset:5120
	ds_read_b128 v[188:191], v176 offset:6144
	ds_read_b128 v[192:195], v176 offset:7168
	global_load_lds_dwordx4 v[196:197], off
	v_lshl_add_u64 v[196:197], s[2:3], 0, v[146:147]
	s_add_i32 m0, s9, 0xe000
	s_nop 0
	global_load_lds_dwordx4 v[196:197], off
	s_waitcnt lgkmcnt(8)
	s_barrier
	s_waitcnt lgkmcnt(0)
	s_waitcnt lgkmcnt(0)
	v_mfma_f32_16x16x32_bf16 v[128:131], v[108:111], v[156:159], v[128:131]
	v_mfma_f32_16x16x32_bf16 v[124:127], v[136:139], v[156:159], v[124:127]
	v_mfma_f32_16x16x32_bf16 v[116:119], v[108:111], v[164:167], v[116:119]
	v_mfma_f32_16x16x32_bf16 v[112:115], v[136:139], v[164:167], v[112:115]
	v_mfma_f32_16x16x32_bf16 v[104:107], v[108:111], v[180:183], v[104:107]
	v_mfma_f32_16x16x32_bf16 v[96:99], v[136:139], v[180:183], v[96:99]
	v_mfma_f32_16x16x32_bf16 v[88:91], v[108:111], v[188:191], v[88:91]
	v_mfma_f32_16x16x32_bf16 v[24:27], v[136:139], v[188:191], v[24:27]
	v_mfma_f32_16x16x32_bf16 v[128:131], v[132:135], v[160:163], v[128:131]
	v_mfma_f32_16x16x32_bf16 v[124:127], v[152:155], v[160:163], v[124:127]
	v_mfma_f32_16x16x32_bf16 v[116:119], v[132:135], v[168:171], v[116:119]
	v_mfma_f32_16x16x32_bf16 v[112:115], v[152:155], v[168:171], v[112:115]
	v_mfma_f32_16x16x32_bf16 v[104:107], v[132:135], v[184:187], v[104:107]
	v_mfma_f32_16x16x32_bf16 v[96:99], v[152:155], v[184:187], v[96:99]
	v_mfma_f32_16x16x32_bf16 v[88:91], v[132:135], v[192:195], v[88:91]
	v_mfma_f32_16x16x32_bf16 v[24:27], v[152:155], v[192:195], v[24:27]
	s_barrier
	s_add_i32 s55, s63, s26
	v_lshl_add_u64 v[214:215], s[12:13], 0, v[140:141]
	s_mov_b32 m0, s55
	ds_read_b128 v[196:199], v177
	ds_read_b128 v[200:203], v177 offset:1024
	ds_read_b128 v[204:207], v177 offset:2048
	ds_read_b128 v[210:213], v177 offset:3072
	global_load_lds_dwordx4 v[214:215], off
	v_lshl_add_u64 v[216:217], s[12:13], 0, v[142:143]
	s_add_i32 m0, s55, 0x2000
	s_nop 0
	global_load_lds_dwordx4 v[216:217], off
	s_barrier
	s_waitcnt lgkmcnt(0)
	s_waitcnt lgkmcnt(0)
	v_mfma_f32_16x16x32_bf16 v[12:15], v[196:199], v[156:159], v[12:15]
	v_mfma_f32_16x16x32_bf16 v[120:123], v[204:207], v[156:159], v[120:123]
	v_mfma_f32_16x16x32_bf16 v[100:103], v[196:199], v[164:167], v[100:103]
	v_mfma_f32_16x16x32_bf16 v[92:95], v[204:207], v[164:167], v[92:95]
	v_mfma_f32_16x16x32_bf16 v[84:87], v[196:199], v[180:183], v[84:87]
	v_mfma_f32_16x16x32_bf16 v[80:83], v[204:207], v[180:183], v[80:83]
	v_mfma_f32_16x16x32_bf16 v[28:31], v[196:199], v[188:191], v[28:31]
	v_mfma_f32_16x16x32_bf16 v[20:23], v[204:207], v[188:191], v[20:23]
	v_mfma_f32_16x16x32_bf16 v[12:15], v[200:203], v[160:163], v[12:15]
	v_mfma_f32_16x16x32_bf16 v[120:123], v[210:213], v[160:163], v[120:123]
	v_mfma_f32_16x16x32_bf16 v[100:103], v[200:203], v[168:171], v[100:103]
	v_mfma_f32_16x16x32_bf16 v[92:95], v[210:213], v[168:171], v[92:95]
	v_mfma_f32_16x16x32_bf16 v[84:87], v[200:203], v[184:187], v[84:87]
	v_mfma_f32_16x16x32_bf16 v[80:83], v[210:213], v[184:187], v[80:83]
	v_mfma_f32_16x16x32_bf16 v[28:31], v[200:203], v[192:195], v[28:31]
	v_mfma_f32_16x16x32_bf16 v[20:23], v[210:213], v[192:195], v[20:23]
	s_mov_b32 m0, s9
	v_lshl_add_u64 v[218:219], s[14:15], 0, v[140:141]
	s_barrier
	ds_read_b128 v[156:159], v176 offset:16384
	ds_read_b128 v[160:163], v176 offset:17408
	ds_read_b128 v[164:167], v176 offset:18432
	ds_read_b128 v[168:171], v176 offset:19456
	ds_read_b128 v[180:183], v176 offset:20480
	ds_read_b128 v[184:187], v176 offset:21504
	ds_read_b128 v[188:191], v176 offset:22528
	ds_read_b128 v[192:195], v176 offset:23552
	global_load_lds_dwordx4 v[218:219], off
	v_lshl_add_u64 v[220:221], s[14:15], 0, v[142:143]
	s_mov_b32 m0, s11
	s_nop 0
	global_load_lds_dwordx4 v[220:221], off
	s_barrier
	s_waitcnt lgkmcnt(0)
	s_waitcnt lgkmcnt(0)
	v_mfma_f32_16x16x32_bf16 v[76:79], v[108:111], v[156:159], v[76:79]
	v_mfma_f32_16x16x32_bf16 v[72:75], v[136:139], v[156:159], v[72:75]
	v_mfma_f32_16x16x32_bf16 v[68:71], v[108:111], v[164:167], v[68:71]
	v_mfma_f32_16x16x32_bf16 v[64:67], v[136:139], v[164:167], v[64:67]
	v_mfma_f32_16x16x32_bf16 v[52:55], v[108:111], v[180:183], v[52:55]
	v_mfma_f32_16x16x32_bf16 v[48:51], v[136:139], v[180:183], v[48:51]
	v_mfma_f32_16x16x32_bf16 v[16:19], v[108:111], v[188:191], v[16:19]
	v_mfma_f32_16x16x32_bf16 v[8:11], v[136:139], v[188:191], v[8:11]
	v_mfma_f32_16x16x32_bf16 v[76:79], v[132:135], v[160:163], v[76:79]
	v_mfma_f32_16x16x32_bf16 v[72:75], v[152:155], v[160:163], v[72:75]
	v_mfma_f32_16x16x32_bf16 v[68:71], v[132:135], v[168:171], v[68:71]
	v_mfma_f32_16x16x32_bf16 v[64:67], v[152:155], v[168:171], v[64:67]
	v_mfma_f32_16x16x32_bf16 v[52:55], v[132:135], v[184:187], v[52:55]
	v_mfma_f32_16x16x32_bf16 v[48:51], v[152:155], v[184:187], v[48:51]
	v_mfma_f32_16x16x32_bf16 v[16:19], v[132:135], v[192:195], v[16:19]
	v_mfma_f32_16x16x32_bf16 v[8:11], v[152:155], v[192:195], v[8:11]
	s_barrier
; #define PG8_STAGE(bufoff, gbase, voff) do { _Pragma("unroll") for (int _i = 0; _i < 2; ++_i) \
;         __builtin_amdgcn_global_load_lds((const unsigned*)((const char*)(gbase) + (voff)[_i]), (LAS unsigned*)(lds + (bufoff) + ldsw + _i * 8192), 16, 0, 0); } while (0)
; #define PG8_LDA(dst, b, h) do { _Pragma("unroll") for (int m = 0; m < 4; ++m) _Pragma("unroll") for (int k = 0; k < 2; ++k) dst[m][k] = *(const LAS bf16x8*)(lds + PG8_SA(b, h) + aoff + m * 2048 + k * 1024); } while (0)
; #define PG8_LDB(dst, b, h) do { _Pragma("unroll") for (int n = 0; n < 2; ++n) _Pragma("unroll") for (int k = 0; k < 2; ++k) dst[n][k] = *(const LAS bf16x8*)(lds + PG8_SB(b, h) + boff + n * 2048 + k * 1024); } while (0)
; #define PG8_MMA(ai, bj, At, Bt) do { __builtin_amdgcn_s_setprio(1); _Pragma("unroll") for (int m = 0; m < 4; ++m) _Pragma("unroll") for (int n = 0; n < 2; ++n) _Pragma("unroll") for (int k = 0; k < 2; ++k) \
;         acc[ai][bj][m][n] = __builtin_amdgcn_mfma_f32_16x16x32_bf16(Bt[n][k], At[m][k], acc[ai][bj][m][n], 0, 0, 0); __builtin_amdgcn_s_setprio(0); } while (0)
; #define PG8_WAIT_V(n) asm volatile("s_waitcnt vmcnt(" #n ")" ::: "memory")
; #define PG8_WAIT_L(n) asm volatile("s_waitcnt lgkmcnt(" #n ")" ::: "memory")
; #define PG8_BAR __builtin_amdgcn_s_barrier()
; #define PG8_SCHED __builtin_amdgcn_sched_barrier(0)
; template <class Epi, bool KS0 = false>
; __device__ __forceinline__ void gemm_phase(const int WID, LAS unsigned char* lds, const Gemm g, const StaticOrder& S, const Epi& E) {
;     ...
;             PG8_STAGE(PG8_SB(0, 1), b2 + hstep, voffB);
;             PG8_WAIT_V(6); PG8_BAR; PG8_MMA(1, 1, At, B1); PG8_BAR;
;             PG8_LDB(B0, 1, 0); PG8_SCHED; PG8_LDA(At, 1, 0); PG8_STAGE(PG8_SA(0, 1), a2 + hstep, voffA);
;             PG8_WAIT_L(8); PG8_BAR; PG8_WAIT_L(0); PG8_MMA(0, 0, At, B0); PG8_BAR; PG8_SCHED;
;             PG8_LDB(B1, 1, 1); PG8_STAGE(PG8_SB(1, 0), b3, voffB);
;             PG8_BAR; PG8_WAIT_L(0); PG8_MMA(0, 1, At, B1); PG8_BAR;
;             PG8_LDA(At, 1, 1); PG8_STAGE(PG8_SA(1, 0), a3, voffA);
;             PG8_BAR; PG8_WAIT_L(0); PG8_MMA(1, 0, At, B0); PG8_BAR; PG8_SCHED;
	s_add_u32 s70, s12, 0x80000
	s_addc_u32 s71, s13, 0
	s_add_i32 s55, s64, s26
	v_lshl_add_u64 v[108:109], s[70:71], 0, v[140:141]
	s_mov_b32 m0, s55
	s_nop 0
	global_load_lds_dwordx4 v[108:109], off
	v_lshl_add_u64 v[108:109], s[70:71], 0, v[142:143]
	s_add_i32 m0, s55, 0x2000
	s_nop 0
	global_load_lds_dwordx4 v[108:109], off
	s_waitcnt vmcnt(6)
	s_barrier
	v_mfma_f32_16x16x32_bf16 v[60:63], v[196:199], v[156:159], v[60:63]
	v_mfma_f32_16x16x32_bf16 v[56:59], v[204:207], v[156:159], v[56:59]
	v_mfma_f32_16x16x32_bf16 v[44:47], v[196:199], v[164:167], v[44:47]
	v_mfma_f32_16x16x32_bf16 v[40:43], v[204:207], v[164:167], v[40:43]
	v_mfma_f32_16x16x32_bf16 v[36:39], v[196:199], v[180:183], v[36:39]
	v_mfma_f32_16x16x32_bf16 v[32:35], v[204:207], v[180:183], v[32:35]
	v_mfma_f32_16x16x32_bf16 v[4:7], v[196:199], v[188:191], v[4:7]
	v_mfma_f32_16x16x32_bf16 v[0:3], v[204:207], v[188:191], v[0:3]
	v_mfma_f32_16x16x32_bf16 v[60:63], v[200:203], v[160:163], v[60:63]
	v_mfma_f32_16x16x32_bf16 v[56:59], v[210:213], v[160:163], v[56:59]
	v_mfma_f32_16x16x32_bf16 v[44:47], v[200:203], v[168:171], v[44:47]
	v_mfma_f32_16x16x32_bf16 v[40:43], v[210:213], v[168:171], v[40:43]
	v_mfma_f32_16x16x32_bf16 v[36:39], v[200:203], v[184:187], v[36:39]
	v_mfma_f32_16x16x32_bf16 v[32:35], v[210:213], v[184:187], v[32:35]
	v_mfma_f32_16x16x32_bf16 v[4:7], v[200:203], v[192:195], v[4:7]
	v_mfma_f32_16x16x32_bf16 v[0:3], v[210:213], v[192:195], v[0:3]
	s_add_i32 s55, 0, 0x18000
	v_add_u32_e32 v152, s55, v174
	s_barrier
	ds_read_b128 v[108:111], v152
	ds_read_b128 v[132:135], v152 offset:1024
	ds_read_b128 v[136:139], v152 offset:2048
	ds_read_b128 v[152:155], v152 offset:3072
	s_add_u32 s14, s14, 0x80000
	s_addc_u32 s15, s15, 0
	s_mov_b32 m0, s18
	v_lshl_add_u64 v[196:197], s[14:15], 0, v[140:141]
	ds_read_b128 v[156:159], v176 offset:32768
	ds_read_b128 v[160:163], v176 offset:33792
	ds_read_b128 v[164:167], v176 offset:34816
	ds_read_b128 v[168:171], v176 offset:35840
	ds_read_b128 v[180:183], v176 offset:36864
	ds_read_b128 v[184:187], v176 offset:37888
	ds_read_b128 v[188:191], v176 offset:38912
	ds_read_b128 v[192:195], v176 offset:39936
	global_load_lds_dwordx4 v[196:197], off
	v_lshl_add_u64 v[196:197], s[14:15], 0, v[142:143]
	s_mov_b32 m0, s19
	s_nop 0
	global_load_lds_dwordx4 v[196:197], off
	s_waitcnt lgkmcnt(8)
	s_barrier
	s_waitcnt lgkmcnt(0)
	s_waitcnt lgkmcnt(0)
	v_mfma_f32_16x16x32_bf16 v[128:131], v[108:111], v[156:159], v[128:131]
	v_mfma_f32_16x16x32_bf16 v[124:127], v[136:139], v[156:159], v[124:127]
	v_mfma_f32_16x16x32_bf16 v[116:119], v[108:111], v[164:167], v[116:119]
	v_mfma_f32_16x16x32_bf16 v[112:115], v[136:139], v[164:167], v[112:115]
	v_mfma_f32_16x16x32_bf16 v[104:107], v[108:111], v[180:183], v[104:107]
	v_mfma_f32_16x16x32_bf16 v[96:99], v[136:139], v[180:183], v[96:99]
	v_mfma_f32_16x16x32_bf16 v[88:91], v[108:111], v[188:191], v[88:91]
	v_mfma_f32_16x16x32_bf16 v[24:27], v[136:139], v[188:191], v[24:27]
	v_mfma_f32_16x16x32_bf16 v[128:131], v[132:135], v[160:163], v[128:131]
	v_mfma_f32_16x16x32_bf16 v[124:127], v[152:155], v[160:163], v[124:127]
	v_mfma_f32_16x16x32_bf16 v[116:119], v[132:135], v[168:171], v[116:119]
	v_mfma_f32_16x16x32_bf16 v[112:115], v[152:155], v[168:171], v[112:115]
	v_mfma_f32_16x16x32_bf16 v[104:107], v[132:135], v[184:187], v[104:107]
	v_mfma_f32_16x16x32_bf16 v[96:99], v[152:155], v[184:187], v[96:99]
	v_mfma_f32_16x16x32_bf16 v[88:91], v[132:135], v[192:195], v[88:91]
	v_mfma_f32_16x16x32_bf16 v[24:27], v[152:155], v[192:195], v[24:27]
	s_barrier
	s_add_i32 s14, 0, 0x1c000
	s_add_i32 s15, s55, s26
	v_add_u32_e32 v179, s14, v174
	v_lshl_add_u64 v[214:215], v[214:215], 0, s[50:51]
	s_mov_b32 m0, s15
	ds_read_b128 v[196:199], v179
	ds_read_b128 v[200:203], v179 offset:1024
	ds_read_b128 v[204:207], v179 offset:2048
	ds_read_b128 v[210:213], v179 offset:3072
	global_load_lds_dwordx4 v[214:215], off
	v_lshl_add_u64 v[214:215], v[216:217], 0, s[50:51]
	s_add_i32 m0, s15, 0x2000
	s_nop 0
	global_load_lds_dwordx4 v[214:215], off
	s_barrier
	s_waitcnt lgkmcnt(0)
	s_waitcnt lgkmcnt(0)
	v_mfma_f32_16x16x32_bf16 v[12:15], v[196:199], v[156:159], v[12:15]
	v_mfma_f32_16x16x32_bf16 v[120:123], v[204:207], v[156:159], v[120:123]
	v_mfma_f32_16x16x32_bf16 v[100:103], v[196:199], v[164:167], v[100:103]
	v_mfma_f32_16x16x32_bf16 v[92:95], v[204:207], v[164:167], v[92:95]
	v_mfma_f32_16x16x32_bf16 v[84:87], v[196:199], v[180:183], v[84:87]
	v_mfma_f32_16x16x32_bf16 v[80:83], v[204:207], v[180:183], v[80:83]
	v_mfma_f32_16x16x32_bf16 v[28:31], v[196:199], v[188:191], v[28:31]
	v_mfma_f32_16x16x32_bf16 v[20:23], v[204:207], v[188:191], v[20:23]
	v_mfma_f32_16x16x32_bf16 v[12:15], v[200:203], v[160:163], v[12:15]
	v_mfma_f32_16x16x32_bf16 v[120:123], v[210:213], v[160:163], v[120:123]
	v_mfma_f32_16x16x32_bf16 v[100:103], v[200:203], v[168:171], v[100:103]
	v_mfma_f32_16x16x32_bf16 v[92:95], v[210:213], v[168:171], v[92:95]
	v_mfma_f32_16x16x32_bf16 v[84:87], v[200:203], v[184:187], v[84:87]
	v_mfma_f32_16x16x32_bf16 v[80:83], v[210:213], v[184:187], v[80:83]
	v_mfma_f32_16x16x32_bf16 v[28:31], v[200:203], v[192:195], v[28:31]
	v_mfma_f32_16x16x32_bf16 v[20:23], v[210:213], v[192:195], v[20:23]
	s_mov_b32 m0, s61
	v_lshl_add_u64 v[214:215], v[218:219], 0, s[50:51]
	s_barrier
	ds_read_b128 v[156:159], v176 offset:49152
	ds_read_b128 v[160:163], v176 offset:50176
	ds_read_b128 v[164:167], v176 offset:51200
	ds_read_b128 v[168:171], v176 offset:52224
	ds_read_b128 v[180:183], v176 offset:53248
	ds_read_b128 v[184:187], v176 offset:54272
	ds_read_b128 v[188:191], v176 offset:55296
	ds_read_b128 v[192:195], v176 offset:56320
	global_load_lds_dwordx4 v[214:215], off
	v_lshl_add_u64 v[214:215], v[220:221], 0, s[50:51]
	s_mov_b32 m0, s62
	s_nop 0
	global_load_lds_dwordx4 v[214:215], off
	s_barrier
; #define LAS __attribute__((address_space(3)))
; __device__ __forceinline__ int lane_id_() { int l; asm volatile("v_mbcnt_lo_u32_b32 %0, -1, 0\n\tv_mbcnt_hi_u32_b32 %0, -1, %0" : "=v"(l)); return l; }
; #define PG8_STAGE(bufoff, gbase, voff) do { _Pragma("unroll") for (int _i = 0; _i < 2; ++_i) \
;         __builtin_amdgcn_global_load_lds((const unsigned*)((const char*)(gbase) + (voff)[_i]), (LAS unsigned*)(lds + (bufoff) + ldsw + _i * 8192), 16, 0, 0); } while (0)
; #define PG8_MMA(ai, bj, At, Bt) do { __builtin_amdgcn_s_setprio(1); _Pragma("unroll") for (int m = 0; m < 4; ++m) _Pragma("unroll") for (int n = 0; n < 2; ++n) _Pragma("unroll") for (int k = 0; k < 2; ++k) \
;         acc[ai][bj][m][n] = __builtin_amdgcn_mfma_f32_16x16x32_bf16(Bt[n][k], At[m][k], acc[ai][bj][m][n], 0, 0, 0); __builtin_amdgcn_s_setprio(0); } while (0)
; template <class Epi, bool KS0 = false>
; __device__ __forceinline__ void gemm_phase(const int WID, LAS unsigned char* lds, const Gemm g, const StaticOrder& S, const Epi& E) {
;     ...
;             PG8_BAR; PG8_WAIT_L(0); PG8_MMA(1, 0, At, B0); PG8_BAR; PG8_SCHED;
;             PG8_STAGE(PG8_SB(1, 1), b3 + hstep, voffB);
;             PG8_WAIT_V(6); PG8_BAR; PG8_MMA(1, 1, At, B1); PG8_BAR;
;         }
;         { int fr2 = lane_id_(), fq2; fq2 = fr2 >> 4; fr2 &= 15; asm volatile("" : "+v"(fr2), "+v"(fq2)); E(acc, cur, wr, wc, fr2, fq2); }
;     __device__ __forceinline__ void operator()(f32x4 (&acc)[2][2][4][2], const Unit& u, int wr, int wc, int fr, int fq) const {
;         const int rowt = u.pm * BM + wr * 64 + fr, cl0 = wc * 32 + 4 * fq, wv = wr * 4 + wc, ln = fq * 16 + fr;
;         float cwr[4];
; #pragma unroll
;         for (int i = 0; i < 4; ++i) { const float* srcp = (i < 3) ? (cw + (size_t)i * FF2) : cb; cwr[i] = srcp[(ln >> 5) * FF + u.pn * HALF + wc * 32 + (ln & 31)]; }
;         {
;             LAS float* myr = rsl + wv * 128; LAS int* mypm = (LAS int*)(rsl + 1024) + wv;
;             if (__builtin_amdgcn_readfirstlane(*mypm) != u.pm) {
; #pragma unroll
;                 for (int ai = 0; ai < 2; ++ai)
; #pragma unroll
;                     for (int m = 0; m < 4; ++m) { const float r_ = row_rstd(ssq_in, rowt + ai * HALF + m * 16, fq); if (fq == 0) myr[(ai * 4 + m) * 16 + fr] = r_; }
;                 if (fq == 0 && fr == 0) *mypm = u.pm;
;                 asm volatile("s_waitcnt lgkmcnt(0)" ::: "memory");
	s_waitcnt lgkmcnt(0)
	s_waitcnt lgkmcnt(0)
	v_mfma_f32_16x16x32_bf16 v[76:79], v[108:111], v[156:159], v[76:79]
	v_mfma_f32_16x16x32_bf16 v[72:75], v[136:139], v[156:159], v[72:75]
	v_mfma_f32_16x16x32_bf16 v[68:71], v[108:111], v[164:167], v[68:71]
	v_mfma_f32_16x16x32_bf16 v[64:67], v[136:139], v[164:167], v[64:67]
	v_mfma_f32_16x16x32_bf16 v[52:55], v[108:111], v[180:183], v[52:55]
	v_mfma_f32_16x16x32_bf16 v[48:51], v[136:139], v[180:183], v[48:51]
	v_mfma_f32_16x16x32_bf16 v[16:19], v[108:111], v[188:191], v[16:19]
	v_mfma_f32_16x16x32_bf16 v[8:11], v[136:139], v[188:191], v[8:11]
	v_mfma_f32_16x16x32_bf16 v[76:79], v[132:135], v[160:163], v[76:79]
	v_mfma_f32_16x16x32_bf16 v[72:75], v[152:155], v[160:163], v[72:75]
	v_mfma_f32_16x16x32_bf16 v[68:71], v[132:135], v[168:171], v[68:71]
	v_mfma_f32_16x16x32_bf16 v[64:67], v[152:155], v[168:171], v[64:67]
	v_mfma_f32_16x16x32_bf16 v[52:55], v[132:135], v[184:187], v[52:55]
	v_mfma_f32_16x16x32_bf16 v[48:51], v[152:155], v[184:187], v[48:51]
	v_mfma_f32_16x16x32_bf16 v[16:19], v[132:135], v[192:195], v[16:19]
	v_mfma_f32_16x16x32_bf16 v[8:11], v[152:155], v[192:195], v[8:11]
	s_barrier
	s_add_u32 s12, s12, 0x80080
	s_addc_u32 s13, s13, 0
	s_add_i32 s14, s14, s26
	v_lshl_add_u64 v[108:109], s[12:13], 0, v[140:141]
	s_mov_b32 m0, s14
	s_nop 0
	global_load_lds_dwordx4 v[108:109], off
	v_lshl_add_u64 v[108:109], s[12:13], 0, v[142:143]
	s_add_i32 m0, s14, 0x2000
	s_nop 0
	global_load_lds_dwordx4 v[108:109], off
	s_waitcnt vmcnt(6)
	s_barrier
	v_mfma_f32_16x16x32_bf16 v[60:63], v[196:199], v[156:159], v[60:63]
	v_mfma_f32_16x16x32_bf16 v[56:59], v[204:207], v[156:159], v[56:59]
	v_mfma_f32_16x16x32_bf16 v[44:47], v[196:199], v[164:167], v[44:47]
	v_mfma_f32_16x16x32_bf16 v[40:43], v[204:207], v[164:167], v[40:43]
	v_mfma_f32_16x16x32_bf16 v[36:39], v[196:199], v[180:183], v[36:39]
	v_mfma_f32_16x16x32_bf16 v[32:35], v[204:207], v[180:183], v[32:35]
	v_mfma_f32_16x16x32_bf16 v[4:7], v[196:199], v[188:191], v[4:7]
	v_mfma_f32_16x16x32_bf16 v[0:3], v[204:207], v[188:191], v[0:3]
	v_mfma_f32_16x16x32_bf16 v[60:63], v[200:203], v[160:163], v[60:63]
	v_mfma_f32_16x16x32_bf16 v[56:59], v[210:213], v[160:163], v[56:59]
	v_mfma_f32_16x16x32_bf16 v[44:47], v[200:203], v[168:171], v[44:47]
	v_mfma_f32_16x16x32_bf16 v[40:43], v[210:213], v[168:171], v[40:43]
	v_mfma_f32_16x16x32_bf16 v[36:39], v[200:203], v[184:187], v[36:39]
	v_mfma_f32_16x16x32_bf16 v[32:35], v[210:213], v[184:187], v[32:35]
	v_mfma_f32_16x16x32_bf16 v[4:7], v[200:203], v[192:195], v[4:7]
	v_mfma_f32_16x16x32_bf16 v[0:3], v[210:213], v[192:195], v[0:3]
	s_add_i32 s53, s53, 2
	s_add_u32 s2, s2, 0x100
	s_addc_u32 s3, s3, 0
	s_add_u32 s44, s44, 0x100
	s_addc_u32 s45, s45, 0
	s_cmp_gt_u32 s53, 29
	s_barrier
	s_cbranch_scc0 .LBB0_777
	v_mbcnt_lo_u32_b32 v108, -1, 0
	v_mbcnt_hi_u32_b32 v108, -1, v108
	s_movk_i32 s3, 0x1600
	v_ashrrev_i32_e32 v132, 4, v108
	v_and_b32_e32 v179, 15, v108
	s_lshl_b32 s12, s8, 7
	v_lshl_add_u32 v164, v132, 4, v179
	v_lshrrev_b32_e32 v108, 5, v164
	v_mul_lo_u32 v108, v108, s3
	v_add_u32_e32 v108, s12, v108
	v_and_b32_e32 v109, 31, v164
	v_readlane_b32 s3, v254, 19
	s_lshl_b32 s2, s10, 8
	s_add_i32 s2, s2, s22
	v_or3_b32 v108, v108, v109, s3
	v_ashrrev_i32_e32 v109, 31, v108
	v_lshlrev_b64 v[108:109], 2, v[108:109]
	v_lshl_add_u64 v[110:111], s[76:77], 0, v[108:109]
	global_load_dword v165, v[110:111], off
	v_lshl_add_u64 v[110:111], s[34:35], 0, v[108:109]
	global_load_dword v166, v[110:111], off
	v_lshl_add_u64 v[110:111], s[48:49], 0, v[108:109]
	v_lshl_add_u64 v[108:109], s[78:79], 0, v[108:109]
	global_load_dword v167, v[110:111], off
	global_load_dword v168, v[108:109], off
	v_mov_b32_e32 v108, s25
	ds_read_b32 v108, v108
	v_add_u32_e32 v152, s2, v179
	v_lshl_add_u32 v155, v179, 2, s21
	s_waitcnt lgkmcnt(0)
	v_readfirstlane_b32 s2, v108
	s_cmp_eq_u32 s2, s10
	s_cbranch_scc1 .LBB0_798
	v_lshlrev_b32_e32 v108, 3, v132
	v_ashrrev_i32_e32 v109, 31, v108
	v_ashrrev_i32_e32 v153, 31, v152
	v_lshl_add_u64 v[108:109], v[108:109], 2, s[16:17]
	v_lshlrev_b64 v[110:111], 7, v[152:153]
	v_lshl_add_u64 v[110:111], v[108:109], 0, v[110:111]
	global_load_dwordx4 v[134:137], v[110:111], off
	global_load_dwordx4 v[156:159], v[110:111], off offset:16
	v_and_b32_e32 v138, 64, v209
	v_xor_b32_e32 v133, 16, v209
	v_add_u32_e32 v138, 64, v138
	v_cmp_lt_i32_e32 vcc, v133, v138
	v_cmp_eq_u32_e64 s[42:43], 0, v132
	s_waitcnt vmcnt(0)
	v_add_f32_e32 v134, v134, v135
	v_add_f32_e32 v135, v136, v137
	v_add_f32_e32 v136, v156, v157
	v_add_f32_e32 v137, v158, v159
	v_cndmask_b32_e32 v133, v209, v133, vcc
	v_add_f32_e32 v134, v134, v135
	v_add_f32_e32 v135, v136, v137
	v_lshlrev_b32_e32 v133, 2, v133
	v_add_f32_e32 v135, v134, v135
	ds_bpermute_b32 v136, v133, v135
	v_xor_b32_e32 v134, 32, v209
	v_cmp_lt_i32_e32 vcc, v134, v138
	s_waitcnt lgkmcnt(0)
	v_add_f32_e32 v135, v135, v136
	v_cndmask_b32_e32 v134, v209, v134, vcc
	v_lshlrev_b32_e32 v134, 2, v134
	ds_bpermute_b32 v136, v134, v135
	s_and_saveexec_b64 s[2:3], s[42:43]
	s_cbranch_execz .LBB0_781
	s_waitcnt lgkmcnt(0)
	v_add_f32_e32 v135, v135, v136
	v_fmamk_f32 v135, v135, 0x3a000000, v178
	v_mul_f32_e32 v136, 0x4b800000, v135
	v_cmp_gt_f32_e32 vcc, s65, v135
	s_nop 1
	v_cndmask_b32_e32 v135, v135, v136, vcc
	v_rsq_f32_e32 v135, v135
	s_nop 0
	v_mul_f32_e32 v136, 0x45800000, v135
	v_cndmask_b32_e32 v135, v135, v136, vcc
	ds_write_b32 v155, v135

; #define PG8_STAGE(bufoff, gbase, voff) do { _Pragma("unroll") for (int _i = 0; _i < 2; ++_i) \
;         __builtin_amdgcn_global_load_lds((const unsigned*)((const char*)(gbase) + (voff)[_i]), (LAS unsigned*)(lds + (bufoff) + ldsw + _i * 8192), 16, 0, 0); } while (0)
; #define PG8_LDA(dst, b, h) do { _Pragma("unroll") for (int m = 0; m < 4; ++m) _Pragma("unroll") for (int k = 0; k < 2; ++k) dst[m][k] = *(const LAS bf16x8*)(lds + PG8_SA(b, h) + aoff + m * 2048 + k * 1024); } while (0)
; #define PG8_LDB(dst, b, h) do { _Pragma("unroll") for (int n = 0; n < 2; ++n) _Pragma("unroll") for (int k = 0; k < 2; ++k) dst[n][k] = *(const LAS bf16x8*)(lds + PG8_SB(b, h) + boff + n * 2048 + k * 1024); } while (0)
; #define PG8_MMA(ai, bj, At, Bt) do { __builtin_amdgcn_s_setprio(1); _Pragma("unroll") for (int m = 0; m < 4; ++m) _Pragma("unroll") for (int n = 0; n < 2; ++n) _Pragma("unroll") for (int k = 0; k < 2; ++k) \
;         acc[ai][bj][m][n] = __builtin_amdgcn_mfma_f32_16x16x32_bf16(Bt[n][k], At[m][k], acc[ai][bj][m][n], 0, 0, 0); __builtin_amdgcn_s_setprio(0); } while (0)
; #define PG8_WAIT_L(n) asm volatile("s_waitcnt lgkmcnt(" #n ")" ::: "memory")
; #define PG8_BAR __builtin_amdgcn_s_barrier()
; #define PG8_SCHED __builtin_amdgcn_sched_barrier(0)
; template <class Epi, bool KS0 = false>
; __device__ __forceinline__ void gemm_phase(const int WID, LAS unsigned char* lds, const Gemm g, const StaticOrder& S, const Epi& E) {
;     ...
;         for (int t = 0; t < nt; t += 2) {
;             const bool last = (t == nt - 2);
;             const char* a1 = cA + (size_t)(t + 1) * kstep;
;             const char* a2 = last ? nA : cA + (size_t)(t + 2) * kstep; const char* b2 = last ? nB : cB + (size_t)(t + 2) * kstep;
;             const char* a3 = a2 + kstep; const char* b3 = b2 + kstep;
;             PG8_LDB(B0, 0, 0); PG8_SCHED; PG8_LDA(At, 0, 0); PG8_STAGE(PG8_SA(1, 1), a1 + hstep, voffA);
;             PG8_WAIT_L(8); PG8_BAR; PG8_WAIT_L(0); PG8_MMA(0, 0, At, B0); PG8_BAR; PG8_SCHED;
;             PG8_LDB(B1, 0, 1); PG8_STAGE(PG8_SB(0, 0), b2, voffB);
;             PG8_BAR; PG8_WAIT_L(0); PG8_MMA(0, 1, At, B1); PG8_BAR;
;             PG8_LDA(At, 0, 1); PG8_STAGE(PG8_SA(0, 0), a2, voffA);
;             PG8_BAR; PG8_WAIT_L(0); PG8_MMA(1, 0, At, B0); PG8_BAR; PG8_SCHED;
.LBB0_914:
	ds_read_b128 v[128:131], v187
	ds_read_b128 v[132:135], v187 offset:1024
	ds_read_b128 v[136:139], v187 offset:2048
	ds_read_b128 v[140:143], v187 offset:3072
	s_add_u32 s18, s2, 0x100
	s_addc_u32 s19, s3, 0
	s_cmpk_eq_i32 s42, 0x54
	s_cselect_b32 s29, s13, s19
	s_cselect_b32 s28, s12, s18
	s_cselect_b32 s21, s15, s41
	s_cselect_b32 s20, s14, s40
	v_lshl_add_u64 v[184:185], s[2:3], 0, v[160:161]
	s_add_i32 m0, s25, 0xc000
	ds_read_b128 v[144:147], v188
	ds_read_b128 v[148:151], v188 offset:1024
	ds_read_b128 v[168:171], v188 offset:2048
	ds_read_b128 v[172:175], v188 offset:3072
	ds_read_b128 v[176:179], v188 offset:4096
	ds_read_b128 v[180:183], v188 offset:5120
	ds_read_b128 v[190:193], v188 offset:6144
	ds_read_b128 v[194:197], v188 offset:7168
	global_load_lds_dwordx4 v[184:185], off
	v_lshl_add_u64 v[184:185], s[2:3], 0, v[162:163]
	s_add_i32 m0, s25, 0xe000
	s_nop 0
	global_load_lds_dwordx4 v[184:185], off
	s_waitcnt lgkmcnt(8)
	s_barrier
	s_waitcnt lgkmcnt(0)
	s_waitcnt lgkmcnt(0)
	v_mfma_f32_16x16x32_bf16 v[124:127], v[128:131], v[144:147], v[124:127]
	v_mfma_f32_16x16x32_bf16 v[120:123], v[136:139], v[144:147], v[120:123]
	v_mfma_f32_16x16x32_bf16 v[108:111], v[128:131], v[168:171], v[108:111]
	v_mfma_f32_16x16x32_bf16 v[104:107], v[136:139], v[168:171], v[104:107]
	v_mfma_f32_16x16x32_bf16 v[92:95], v[128:131], v[176:179], v[92:95]
	v_mfma_f32_16x16x32_bf16 v[88:91], v[136:139], v[176:179], v[88:91]
	v_mfma_f32_16x16x32_bf16 v[76:79], v[128:131], v[190:193], v[76:79]
	v_mfma_f32_16x16x32_bf16 v[72:75], v[136:139], v[190:193], v[72:75]
	v_mfma_f32_16x16x32_bf16 v[124:127], v[132:135], v[148:151], v[124:127]
	v_mfma_f32_16x16x32_bf16 v[120:123], v[140:143], v[148:151], v[120:123]
	v_mfma_f32_16x16x32_bf16 v[108:111], v[132:135], v[172:175], v[108:111]
	v_mfma_f32_16x16x32_bf16 v[104:107], v[140:143], v[172:175], v[104:107]
	v_mfma_f32_16x16x32_bf16 v[92:95], v[132:135], v[180:183], v[92:95]
	v_mfma_f32_16x16x32_bf16 v[88:91], v[140:143], v[180:183], v[88:91]
	v_mfma_f32_16x16x32_bf16 v[76:79], v[132:135], v[194:197], v[76:79]
	v_mfma_f32_16x16x32_bf16 v[72:75], v[140:143], v[194:197], v[72:75]
	s_barrier
	s_add_i32 s2, s47, s26
	v_lshl_add_u64 v[184:185], s[20:21], 0, v[154:155]
	s_mov_b32 m0, s2
	ds_read_b128 v[198:201], v189
	ds_read_b128 v[202:205], v189 offset:1024
	ds_read_b128 v[210:213], v189 offset:2048
	ds_read_b128 v[214:217], v189 offset:3072
	global_load_lds_dwordx4 v[184:185], off
	v_lshl_add_u64 v[206:207], s[20:21], 0, v[158:159]
	s_add_i32 m0, s2, 0x2000
	s_nop 0
	global_load_lds_dwordx4 v[206:207], off
	s_barrier
	s_waitcnt lgkmcnt(0)
	s_waitcnt lgkmcnt(0)
	v_mfma_f32_16x16x32_bf16 v[116:119], v[198:201], v[144:147], v[116:119]
	v_mfma_f32_16x16x32_bf16 v[112:115], v[210:213], v[144:147], v[112:115]
	v_mfma_f32_16x16x32_bf16 v[100:103], v[198:201], v[168:171], v[100:103]
	v_mfma_f32_16x16x32_bf16 v[96:99], v[210:213], v[168:171], v[96:99]
	v_mfma_f32_16x16x32_bf16 v[84:87], v[198:201], v[176:179], v[84:87]
	v_mfma_f32_16x16x32_bf16 v[80:83], v[210:213], v[176:179], v[80:83]
	v_mfma_f32_16x16x32_bf16 v[68:71], v[198:201], v[190:193], v[68:71]
	v_mfma_f32_16x16x32_bf16 v[64:67], v[210:213], v[190:193], v[64:67]
	v_mfma_f32_16x16x32_bf16 v[116:119], v[202:205], v[148:151], v[116:119]
	v_mfma_f32_16x16x32_bf16 v[112:115], v[214:217], v[148:151], v[112:115]
	v_mfma_f32_16x16x32_bf16 v[100:103], v[202:205], v[172:175], v[100:103]
	v_mfma_f32_16x16x32_bf16 v[96:99], v[214:217], v[172:175], v[96:99]
	v_mfma_f32_16x16x32_bf16 v[84:87], v[202:205], v[180:183], v[84:87]
	v_mfma_f32_16x16x32_bf16 v[80:83], v[214:217], v[180:183], v[80:83]
	v_mfma_f32_16x16x32_bf16 v[68:71], v[202:205], v[194:197], v[68:71]
	v_mfma_f32_16x16x32_bf16 v[64:67], v[214:217], v[194:197], v[64:67]
	s_mov_b32 m0, s25
	v_lshl_add_u64 v[218:219], s[28:29], 0, v[152:153]
	s_barrier
	ds_read_b128 v[144:147], v188 offset:16384
	ds_read_b128 v[148:151], v188 offset:17408
	ds_read_b128 v[168:171], v188 offset:18432
	ds_read_b128 v[172:175], v188 offset:19456
	ds_read_b128 v[176:179], v188 offset:20480
	ds_read_b128 v[180:183], v188 offset:21504
	ds_read_b128 v[190:193], v188 offset:22528
	ds_read_b128 v[194:197], v188 offset:23552
	global_load_lds_dwordx4 v[218:219], off
	v_lshl_add_u64 v[220:221], s[28:29], 0, v[156:157]
	s_mov_b32 m0, s30
	s_nop 0
	global_load_lds_dwordx4 v[220:221], off
	s_barrier
	s_waitcnt lgkmcnt(0)
	s_waitcnt lgkmcnt(0)
	v_mfma_f32_16x16x32_bf16 v[60:63], v[128:131], v[144:147], v[60:63]
	v_mfma_f32_16x16x32_bf16 v[56:59], v[136:139], v[144:147], v[56:59]
	v_mfma_f32_16x16x32_bf16 v[44:47], v[128:131], v[168:171], v[44:47]
	v_mfma_f32_16x16x32_bf16 v[40:43], v[136:139], v[168:171], v[40:43]
	v_mfma_f32_16x16x32_bf16 v[28:31], v[128:131], v[176:179], v[28:31]
	v_mfma_f32_16x16x32_bf16 v[24:27], v[136:139], v[176:179], v[24:27]
	v_mfma_f32_16x16x32_bf16 v[12:15], v[128:131], v[190:193], v[12:15]
	v_mfma_f32_16x16x32_bf16 v[8:11], v[136:139], v[190:193], v[8:11]
	v_mfma_f32_16x16x32_bf16 v[60:63], v[132:135], v[148:151], v[60:63]
	v_mfma_f32_16x16x32_bf16 v[56:59], v[140:143], v[148:151], v[56:59]
	v_mfma_f32_16x16x32_bf16 v[44:47], v[132:135], v[172:175], v[44:47]
	v_mfma_f32_16x16x32_bf16 v[40:43], v[140:143], v[172:175], v[40:43]
	v_mfma_f32_16x16x32_bf16 v[28:31], v[132:135], v[180:183], v[28:31]
	v_mfma_f32_16x16x32_bf16 v[24:27], v[140:143], v[180:183], v[24:27]
	v_mfma_f32_16x16x32_bf16 v[12:15], v[132:135], v[194:197], v[12:15]
	v_mfma_f32_16x16x32_bf16 v[8:11], v[140:143], v[194:197], v[8:11]
	s_barrier
; #define PG8_STAGE(bufoff, gbase, voff) do { _Pragma("unroll") for (int _i = 0; _i < 2; ++_i) \
;         __builtin_amdgcn_global_load_lds((const unsigned*)((const char*)(gbase) + (voff)[_i]), (LAS unsigned*)(lds + (bufoff) + ldsw + _i * 8192), 16, 0, 0); } while (0)
; #define PG8_LDA(dst, b, h) do { _Pragma("unroll") for (int m = 0; m < 4; ++m) _Pragma("unroll") for (int k = 0; k < 2; ++k) dst[m][k] = *(const LAS bf16x8*)(lds + PG8_SA(b, h) + aoff + m * 2048 + k * 1024); } while (0)
; #define PG8_LDB(dst, b, h) do { _Pragma("unroll") for (int n = 0; n < 2; ++n) _Pragma("unroll") for (int k = 0; k < 2; ++k) dst[n][k] = *(const LAS bf16x8*)(lds + PG8_SB(b, h) + boff + n * 2048 + k * 1024); } while (0)
; #define PG8_MMA(ai, bj, At, Bt) do { __builtin_amdgcn_s_setprio(1); _Pragma("unroll") for (int m = 0; m < 4; ++m) _Pragma("unroll") for (int n = 0; n < 2; ++n) _Pragma("unroll") for (int k = 0; k < 2; ++k) \
;         acc[ai][bj][m][n] = __builtin_amdgcn_mfma_f32_16x16x32_bf16(Bt[n][k], At[m][k], acc[ai][bj][m][n], 0, 0, 0); __builtin_amdgcn_s_setprio(0); } while (0)
; #define PG8_WAIT_V(n) asm volatile("s_waitcnt vmcnt(" #n ")" ::: "memory")
; #define PG8_WAIT_L(n) asm volatile("s_waitcnt lgkmcnt(" #n ")" ::: "memory")
; #define PG8_BAR __builtin_amdgcn_s_barrier()
; #define PG8_SCHED __builtin_amdgcn_sched_barrier(0)
; template <class Epi, bool KS0 = false>
; __device__ __forceinline__ void gemm_phase(const int WID, LAS unsigned char* lds, const Gemm g, const StaticOrder& S, const Epi& E) {
;     ...
;             PG8_STAGE(PG8_SB(0, 1), b2 + hstep, voffB);
;             PG8_WAIT_V(6); PG8_BAR; PG8_MMA(1, 1, At, B1); PG8_BAR;
;             PG8_LDB(B0, 1, 0); PG8_SCHED; PG8_LDA(At, 1, 0); PG8_STAGE(PG8_SA(0, 1), a2 + hstep, voffA);
;             PG8_WAIT_L(8); PG8_BAR; PG8_WAIT_L(0); PG8_MMA(0, 0, At, B0); PG8_BAR; PG8_SCHED;
;             PG8_LDB(B1, 1, 1); PG8_STAGE(PG8_SB(1, 0), b3, voffB);
;             PG8_BAR; PG8_WAIT_L(0); PG8_MMA(0, 1, At, B1); PG8_BAR;
;             PG8_LDA(At, 1, 1); PG8_STAGE(PG8_SA(1, 0), a3, voffA);
;             PG8_BAR; PG8_WAIT_L(0); PG8_MMA(1, 0, At, B0); PG8_BAR; PG8_SCHED;
	s_add_u32 s2, s20, 0x160000
	s_addc_u32 s3, s21, 0
	s_add_i32 s43, s48, s26
	v_lshl_add_u64 v[128:129], s[2:3], 0, v[154:155]
	s_mov_b32 m0, s43
	s_nop 0
	global_load_lds_dwordx4 v[128:129], off
	v_lshl_add_u64 v[128:129], s[2:3], 0, v[158:159]
	s_add_i32 m0, s43, 0x2000
	s_nop 0
	global_load_lds_dwordx4 v[128:129], off
	s_waitcnt vmcnt(6)
	s_barrier
	v_mfma_f32_16x16x32_bf16 v[52:55], v[198:201], v[144:147], v[52:55]
	v_mfma_f32_16x16x32_bf16 v[48:51], v[210:213], v[144:147], v[48:51]
	v_mfma_f32_16x16x32_bf16 v[36:39], v[198:201], v[168:171], v[36:39]
	v_mfma_f32_16x16x32_bf16 v[32:35], v[210:213], v[168:171], v[32:35]
	v_mfma_f32_16x16x32_bf16 v[20:23], v[198:201], v[176:179], v[20:23]
	v_mfma_f32_16x16x32_bf16 v[16:19], v[210:213], v[176:179], v[16:19]
	v_mfma_f32_16x16x32_bf16 v[4:7], v[198:201], v[190:193], v[4:7]
	v_mfma_f32_16x16x32_bf16 v[0:3], v[210:213], v[190:193], v[0:3]
	v_mfma_f32_16x16x32_bf16 v[52:55], v[202:205], v[148:151], v[52:55]
	v_mfma_f32_16x16x32_bf16 v[48:51], v[214:217], v[148:151], v[48:51]
	v_mfma_f32_16x16x32_bf16 v[36:39], v[202:205], v[172:175], v[36:39]
	v_mfma_f32_16x16x32_bf16 v[32:35], v[214:217], v[172:175], v[32:35]
	v_mfma_f32_16x16x32_bf16 v[20:23], v[202:205], v[180:183], v[20:23]
	v_mfma_f32_16x16x32_bf16 v[16:19], v[214:217], v[180:183], v[16:19]
	v_mfma_f32_16x16x32_bf16 v[4:7], v[202:205], v[194:197], v[4:7]
	v_mfma_f32_16x16x32_bf16 v[0:3], v[214:217], v[194:197], v[0:3]
	s_add_i32 s43, 0, 0x18000
	v_add_u32_e32 v140, s43, v186
	s_barrier
	ds_read_b128 v[128:131], v140
	ds_read_b128 v[132:135], v140 offset:1024
	ds_read_b128 v[136:139], v140 offset:2048
	ds_read_b128 v[140:143], v140 offset:3072
	s_add_u32 s2, s28, 0x160000
	s_addc_u32 s3, s29, 0
	s_mov_b32 m0, s31
	v_lshl_add_u64 v[198:199], s[2:3], 0, v[152:153]
	ds_read_b128 v[144:147], v188 offset:32768
	ds_read_b128 v[148:151], v188 offset:33792
	ds_read_b128 v[168:171], v188 offset:34816
	ds_read_b128 v[172:175], v188 offset:35840
	ds_read_b128 v[176:179], v188 offset:36864
	ds_read_b128 v[180:183], v188 offset:37888
	ds_read_b128 v[190:193], v188 offset:38912
	ds_read_b128 v[194:197], v188 offset:39936
	global_load_lds_dwordx4 v[198:199], off
	v_lshl_add_u64 v[198:199], s[2:3], 0, v[156:157]
	s_mov_b32 m0, s44
	s_nop 0
	global_load_lds_dwordx4 v[198:199], off
	s_waitcnt lgkmcnt(8)
	s_barrier
	s_waitcnt lgkmcnt(0)
	s_waitcnt lgkmcnt(0)
	v_mfma_f32_16x16x32_bf16 v[124:127], v[128:131], v[144:147], v[124:127]
	v_mfma_f32_16x16x32_bf16 v[120:123], v[136:139], v[144:147], v[120:123]
	v_mfma_f32_16x16x32_bf16 v[108:111], v[128:131], v[168:171], v[108:111]
	v_mfma_f32_16x16x32_bf16 v[104:107], v[136:139], v[168:171], v[104:107]
	v_mfma_f32_16x16x32_bf16 v[92:95], v[128:131], v[176:179], v[92:95]
	v_mfma_f32_16x16x32_bf16 v[88:91], v[136:139], v[176:179], v[88:91]
	v_mfma_f32_16x16x32_bf16 v[76:79], v[128:131], v[190:193], v[76:79]
	v_mfma_f32_16x16x32_bf16 v[72:75], v[136:139], v[190:193], v[72:75]
	v_mfma_f32_16x16x32_bf16 v[124:127], v[132:135], v[148:151], v[124:127]
	v_mfma_f32_16x16x32_bf16 v[120:123], v[140:143], v[148:151], v[120:123]
	v_mfma_f32_16x16x32_bf16 v[108:111], v[132:135], v[172:175], v[108:111]
	v_mfma_f32_16x16x32_bf16 v[104:107], v[140:143], v[172:175], v[104:107]
	v_mfma_f32_16x16x32_bf16 v[92:95], v[132:135], v[180:183], v[92:95]
	v_mfma_f32_16x16x32_bf16 v[88:91], v[140:143], v[180:183], v[88:91]
	v_mfma_f32_16x16x32_bf16 v[76:79], v[132:135], v[194:197], v[76:79]
	v_mfma_f32_16x16x32_bf16 v[72:75], v[140:143], v[194:197], v[72:75]
	s_barrier
	s_add_i32 s28, 0, 0x1c000
	s_add_i32 s2, s43, s26
	v_add_u32_e32 v208, s28, v186
	v_lshl_add_u64 v[184:185], v[184:185], 0, s[10:11]
	s_mov_b32 m0, s2
	ds_read_b128 v[198:201], v208
	ds_read_b128 v[202:205], v208 offset:1024
	ds_read_b128 v[210:213], v208 offset:2048
	ds_read_b128 v[214:217], v208 offset:3072
	global_load_lds_dwordx4 v[184:185], off
	v_lshl_add_u64 v[184:185], v[206:207], 0, s[10:11]
	s_add_i32 m0, s2, 0x2000
	s_nop 0
	global_load_lds_dwordx4 v[184:185], off
	s_barrier
	s_waitcnt lgkmcnt(0)
	s_waitcnt lgkmcnt(0)
	v_mfma_f32_16x16x32_bf16 v[116:119], v[198:201], v[144:147], v[116:119]
	v_mfma_f32_16x16x32_bf16 v[112:115], v[210:213], v[144:147], v[112:115]
	v_mfma_f32_16x16x32_bf16 v[100:103], v[198:201], v[168:171], v[100:103]
	v_mfma_f32_16x16x32_bf16 v[96:99], v[210:213], v[168:171], v[96:99]
	v_mfma_f32_16x16x32_bf16 v[84:87], v[198:201], v[176:179], v[84:87]
	v_mfma_f32_16x16x32_bf16 v[80:83], v[210:213], v[176:179], v[80:83]
	v_mfma_f32_16x16x32_bf16 v[68:71], v[198:201], v[190:193], v[68:71]
	v_mfma_f32_16x16x32_bf16 v[64:67], v[210:213], v[190:193], v[64:67]
	v_mfma_f32_16x16x32_bf16 v[116:119], v[202:205], v[148:151], v[116:119]
	v_mfma_f32_16x16x32_bf16 v[112:115], v[214:217], v[148:151], v[112:115]
	v_mfma_f32_16x16x32_bf16 v[100:103], v[202:205], v[172:175], v[100:103]
	v_mfma_f32_16x16x32_bf16 v[96:99], v[214:217], v[172:175], v[96:99]
	v_mfma_f32_16x16x32_bf16 v[84:87], v[202:205], v[180:183], v[84:87]
	v_mfma_f32_16x16x32_bf16 v[80:83], v[214:217], v[180:183], v[80:83]
	v_mfma_f32_16x16x32_bf16 v[68:71], v[202:205], v[194:197], v[68:71]
	v_mfma_f32_16x16x32_bf16 v[64:67], v[214:217], v[194:197], v[64:67]
	s_mov_b32 m0, s45
	v_lshl_add_u64 v[184:185], v[218:219], 0, s[10:11]
	s_barrier
	ds_read_b128 v[144:147], v188 offset:49152
	ds_read_b128 v[148:151], v188 offset:50176
	ds_read_b128 v[168:171], v188 offset:51200
	ds_read_b128 v[172:175], v188 offset:52224
	ds_read_b128 v[176:179], v188 offset:53248
	ds_read_b128 v[180:183], v188 offset:54272
	ds_read_b128 v[190:193], v188 offset:55296
	ds_read_b128 v[194:197], v188 offset:56320
	global_load_lds_dwordx4 v[184:185], off
	v_lshl_add_u64 v[184:185], v[220:221], 0, s[10:11]
	s_mov_b32 m0, s46
	s_nop 0
	global_load_lds_dwordx4 v[184:185], off
	s_barrier
; #define PG8_STAGE(bufoff, gbase, voff) do { _Pragma("unroll") for (int _i = 0; _i < 2; ++_i) \
;         __builtin_amdgcn_global_load_lds((const unsigned*)((const char*)(gbase) + (voff)[_i]), (LAS unsigned*)(lds + (bufoff) + ldsw + _i * 8192), 16, 0, 0); } while (0)
; #define PG8_LDA(dst, b, h) do { _Pragma("unroll") for (int m = 0; m < 4; ++m) _Pragma("unroll") for (int k = 0; k < 2; ++k) dst[m][k] = *(const LAS bf16x8*)(lds + PG8_SA(b, h) + aoff + m * 2048 + k * 1024); } while (0)
; #define PG8_MMA(ai, bj, At, Bt) do { __builtin_amdgcn_s_setprio(1); _Pragma("unroll") for (int m = 0; m < 4; ++m) _Pragma("unroll") for (int n = 0; n < 2; ++n) _Pragma("unroll") for (int k = 0; k < 2; ++k) \
;         acc[ai][bj][m][n] = __builtin_amdgcn_mfma_f32_16x16x32_bf16(Bt[n][k], At[m][k], acc[ai][bj][m][n], 0, 0, 0); __builtin_amdgcn_s_setprio(0); } while (0)
; #define PG8_WAIT_V(n) asm volatile("s_waitcnt vmcnt(" #n ")" ::: "memory")
; #define PG8_WAIT_L(n) asm volatile("s_waitcnt lgkmcnt(" #n ")" ::: "memory")
; #define PG8_BAR __builtin_amdgcn_s_barrier()
; #define PG8_SCHED __builtin_amdgcn_sched_barrier(0)
; template <class Epi, bool KS0 = false>
; __device__ __forceinline__ void gemm_phase(const int WID, LAS unsigned char* lds, const Gemm g, const StaticOrder& S, const Epi& E) {
;     ...
;             PG8_LDA(At, 1, 1); PG8_STAGE(PG8_SA(1, 0), a3, voffA);
;             PG8_BAR; PG8_WAIT_L(0); PG8_MMA(1, 0, At, B0); PG8_BAR; PG8_SCHED;
;             PG8_STAGE(PG8_SB(1, 1), b3 + hstep, voffB);
;             PG8_WAIT_V(6); PG8_BAR; PG8_MMA(1, 1, At, B1); PG8_BAR;
;         }
	s_waitcnt lgkmcnt(0)
	s_waitcnt lgkmcnt(0)
	v_mfma_f32_16x16x32_bf16 v[60:63], v[128:131], v[144:147], v[60:63]
	v_mfma_f32_16x16x32_bf16 v[56:59], v[136:139], v[144:147], v[56:59]
	v_mfma_f32_16x16x32_bf16 v[44:47], v[128:131], v[168:171], v[44:47]
	v_mfma_f32_16x16x32_bf16 v[40:43], v[136:139], v[168:171], v[40:43]
	v_mfma_f32_16x16x32_bf16 v[28:31], v[128:131], v[176:179], v[28:31]
	v_mfma_f32_16x16x32_bf16 v[24:27], v[136:139], v[176:179], v[24:27]
	v_mfma_f32_16x16x32_bf16 v[12:15], v[128:131], v[190:193], v[12:15]
	v_mfma_f32_16x16x32_bf16 v[8:11], v[136:139], v[190:193], v[8:11]
	v_mfma_f32_16x16x32_bf16 v[60:63], v[132:135], v[148:151], v[60:63]
	v_mfma_f32_16x16x32_bf16 v[56:59], v[140:143], v[148:151], v[56:59]
	v_mfma_f32_16x16x32_bf16 v[44:47], v[132:135], v[172:175], v[44:47]
	v_mfma_f32_16x16x32_bf16 v[40:43], v[140:143], v[172:175], v[40:43]
	v_mfma_f32_16x16x32_bf16 v[28:31], v[132:135], v[180:183], v[28:31]
	v_mfma_f32_16x16x32_bf16 v[24:27], v[140:143], v[180:183], v[24:27]
	v_mfma_f32_16x16x32_bf16 v[12:15], v[132:135], v[194:197], v[12:15]
	v_mfma_f32_16x16x32_bf16 v[8:11], v[140:143], v[194:197], v[8:11]
	s_barrier
	s_add_u32 s2, s20, 0x160080
	s_addc_u32 s3, s21, 0
	s_add_i32 s20, s28, s26
	v_lshl_add_u64 v[128:129], s[2:3], 0, v[154:155]
	s_mov_b32 m0, s20
	s_nop 0
	global_load_lds_dwordx4 v[128:129], off
	v_lshl_add_u64 v[128:129], s[2:3], 0, v[158:159]
	s_add_i32 m0, s20, 0x2000
	s_nop 0
	global_load_lds_dwordx4 v[128:129], off
	s_waitcnt vmcnt(6)
	s_barrier
	v_mfma_f32_16x16x32_bf16 v[52:55], v[198:201], v[144:147], v[52:55]
	v_mfma_f32_16x16x32_bf16 v[48:51], v[210:213], v[144:147], v[48:51]
	v_mfma_f32_16x16x32_bf16 v[36:39], v[198:201], v[168:171], v[36:39]
	v_mfma_f32_16x16x32_bf16 v[32:35], v[210:213], v[168:171], v[32:35]
	v_mfma_f32_16x16x32_bf16 v[20:23], v[198:201], v[176:179], v[20:23]
	v_mfma_f32_16x16x32_bf16 v[16:19], v[210:213], v[176:179], v[16:19]
	v_mfma_f32_16x16x32_bf16 v[4:7], v[198:201], v[190:193], v[4:7]
	v_mfma_f32_16x16x32_bf16 v[0:3], v[210:213], v[190:193], v[0:3]
	v_mfma_f32_16x16x32_bf16 v[52:55], v[202:205], v[148:151], v[52:55]
	v_mfma_f32_16x16x32_bf16 v[48:51], v[214:217], v[148:151], v[48:51]
	v_mfma_f32_16x16x32_bf16 v[36:39], v[202:205], v[172:175], v[36:39]
	v_mfma_f32_16x16x32_bf16 v[32:35], v[214:217], v[172:175], v[32:35]
	v_mfma_f32_16x16x32_bf16 v[20:23], v[202:205], v[180:183], v[20:23]
	v_mfma_f32_16x16x32_bf16 v[16:19], v[214:217], v[180:183], v[16:19]
	v_mfma_f32_16x16x32_bf16 v[4:7], v[202:205], v[194:197], v[4:7]
	v_mfma_f32_16x16x32_bf16 v[0:3], v[214:217], v[194:197], v[0:3]
	s_add_i32 s42, s42, 2
	s_add_u32 s40, s40, 0x100
	s_addc_u32 s41, s41, 0
	s_cmpk_gt_u32 s42, 0x55
	s_mov_b64 s[2:3], s[18:19]
	s_barrier
	s_cbranch_scc0 .LBB0_914
; __device__ __forceinline__ unsigned cvt_pk_bf16(float lo, float hi) { unsigned r; asm volatile("v_cvt_pk_bf16_f32 %0, %1, %2" : "=v"(r) : "v"(lo), "v"(hi)); return r; }
; __device__ __forceinline__ float bflo(unsigned w) { return __uint_as_float(w << 16); }
; __device__ __forceinline__ float bfhi(unsigned w) { return __uint_as_float(w & 0xffff0000u); }
;     __device__ __forceinline__ void operator()(f32x4 (&acc)[2][2][4][2], const Unit& u, int wr, int wc, int fr, int fq) const {
;         const int row0 = u.pm * BM + wr * 64 + fr, col0 = u.pn * BM + wc * 32 + 8 * fq;
; #pragma unroll
;         for (int ai = 0; ai < 2; ++ai) {
;             f32x4 r[4][2][2];
; #pragma unroll
;             for (int m = 0; m < 4; ++m)
; #pragma unroll
;                 for (int bj = 0; bj < 2; ++bj) { const size_t o = (size_t)(row0 + ai * HALF + m * 16) * DM + col0 + bj * HALF;
;                     if (RB) { const u32x4 w = *(const u32x4*)((const bf16_t*)res + o); r[m][bj][0] = (f32x4){bflo(w.x), bfhi(w.x), bflo(w.y), bfhi(w.y)}; r[m][bj][1] = (f32x4){bflo(w.z), bfhi(w.z), bflo(w.w), bfhi(w.w)}; }
;                     else { r[m][bj][0] = __builtin_nontemporal_load((const f32x4*)((const float*)res + o)); r[m][bj][1] = __builtin_nontemporal_load((const f32x4*)((const float*)res + o + 4)); } }
; #pragma unroll
;             for (int m = 0; m < 4; ++m) { const int row = row0 + ai * HALF + m * 16; const size_t off = (size_t)row * DM + col0; float s = 0.f;
; #pragma unroll
;                 for (int bj = 0; bj < 2; ++bj) { const f32x4 v0 = acc[ai][bj][m][0] + r[m][bj][0], v1 = acc[ai][bj][m][1] + r[m][bj][1];
;                     u32x4 w; w.x = cvt_pk_bf16(v0[0], v0[1]); w.y = cvt_pk_bf16(v0[2], v0[3]); w.z = cvt_pk_bf16(v1[0], v1[1]); w.w = cvt_pk_bf16(v1[2], v1[3]);
;                     *(u32x4*)(outb + off + bj * HALF) = w;
;                     s += ((v0[0] * v0[0] + v0[1] * v0[1]) + (v0[2] * v0[2] + v0[3] * v0[3])) + ((v1[0] * v1[0] + v1[1] * v1[1]) + (v1[2] * v1[2] + v1[3] * v1[3])); }
;                 s += __shfl_xor(s, 16); s += __shfl_xor(s, 32);
;                 if (fq == 0) ssq[(size_t)row * 32 + u.pn * 4 + wc] = s; }
;             asm volatile("" ::: "memory"); }
;     }
	v_mbcnt_lo_u32_b32 v128, -1, 0
	v_mbcnt_hi_u32_b32 v128, -1, v128
	s_lshl_b32 s2, s52, 8
	v_ashrrev_i32_e32 v129, 4, v128
	v_and_b32_e32 v128, 15, v128
	s_add_i32 s2, s2, s22
	v_readlane_b32 s3, v254, 19
	v_add_u32_e32 v172, s2, v128
	s_lshl_b32 s2, s8, 8
	s_or_b32 s2, s2, s3
	v_lshl_add_u32 v168, v129, 3, s2
	v_ashrrev_i32_e32 v169, 31, v168
	v_lshlrev_b64 v[190:191], 1, v[168:169]
	v_ashrrev_i32_e32 v173, 31, v172
	v_lshl_add_u64 v[170:171], s[6:7], 0, v[190:191]
	v_lshlrev_b64 v[192:193], 12, v[172:173]
	v_lshl_add_u64 v[132:133], v[170:171], 0, v[192:193]
	v_cmp_eq_u32_e32 vcc, 0, v129
	global_load_dwordx4 v[128:131], v[132:133], off
	v_add_u32_e32 v182, 16, v172
	v_ashrrev_i32_e32 v183, 31, v182
	v_add_u32_e32 v178, 32, v172
	v_lshlrev_b64 v[184:185], 12, v[182:183]
	v_ashrrev_i32_e32 v179, 31, v178
	v_add_u32_e32 v174, 48, v172
	v_lshlrev_b64 v[180:181], 12, v[178:179]
	v_ashrrev_i32_e32 v175, 31, v174
	v_lshlrev_b64 v[176:177], 12, v[174:175]
	v_lshl_add_u64 v[192:193], s[6:7], 0, v[192:193]
	v_lshl_add_u64 v[190:191], v[192:193], 0, v[190:191]
	s_lshl_b32 s18, s8, 2
	s_ashr_i32 s19, s18, 31
	s_waitcnt vmcnt(0)
	v_lshlrev_b32_e32 v194, 16, v128
	v_and_b32_e32 v195, 0xffff0000, v128
	v_lshlrev_b32_e32 v196, 16, v129
	v_and_b32_e32 v197, 0xffff0000, v129
	v_lshlrev_b32_e32 v198, 16, v130
	v_and_b32_e32 v199, 0xffff0000, v130
	v_lshlrev_b32_e32 v200, 16, v131
	v_and_b32_e32 v201, 0xffff0000, v131
	global_load_dwordx4 v[128:131], v[132:133], off offset:256
	v_pk_add_f32 v[126:127], v[126:127], v[196:197]
	v_pk_add_f32 v[124:125], v[124:125], v[194:195]
	v_pk_add_f32 v[196:197], v[120:121], v[198:199]
	v_pk_add_f32 v[194:195], v[122:123], v[200:201]
	s_waitcnt vmcnt(0)
	v_lshlrev_b32_e32 v202, 16, v128
	v_and_b32_e32 v203, 0xffff0000, v128
	v_lshlrev_b32_e32 v204, 16, v129
	v_and_b32_e32 v205, 0xffff0000, v129
	v_lshl_add_u64 v[128:129], v[170:171], 0, v[184:185]
	global_load_dwordx4 v[148:151], v[128:129], off
	global_load_dwordx4 v[144:147], v[128:129], off offset:256
	v_lshl_add_u64 v[128:129], v[170:171], 0, v[180:181]
	global_load_dwordx4 v[140:143], v[128:129], off
	global_load_dwordx4 v[136:139], v[128:129], off offset:256
	v_lshl_add_u64 v[128:129], v[170:171], 0, v[176:177]
	v_lshlrev_b32_e32 v206, 16, v130
	v_and_b32_e32 v207, 0xffff0000, v130
	v_lshlrev_b32_e32 v210, 16, v131
	v_and_b32_e32 v211, 0xffff0000, v131
	global_load_dwordx4 v[132:135], v[128:129], off
	s_nop 0
	global_load_dwordx4 v[128:131], v[128:129], off offset:256
	v_cvt_pk_bf16_f32 v120, v124, v125
	v_cvt_pk_bf16_f32 v121, v126, v127
	v_cvt_pk_bf16_f32 v122, v196, v197
	v_cvt_pk_bf16_f32 v123, v194, v195
	global_store_dwordx4 v[190:191], v[120:123], off
	v_pk_add_f32 v[118:119], v[118:119], v[204:205]
	v_pk_add_f32 v[116:117], v[116:117], v[202:203]
	v_mul_f32_e32 v120, v125, v125
	v_mul_f32_e32 v121, v127, v127
	v_fmac_f32_e32 v120, v124, v124
	v_fmac_f32_e32 v121, v126, v126
	v_add_f32_e32 v120, v120, v121
	v_mul_f32_e32 v121, v197, v197
	v_mul_f32_e32 v122, v195, v195
	v_fmac_f32_e32 v121, v196, v196
	v_fmac_f32_e32 v122, v194, v194
	v_add_f32_e32 v121, v121, v122
	v_pk_add_f32 v[122:123], v[112:113], v[206:207]
	v_cvt_pk_bf16_f32 v112, v116, v117
	v_cvt_pk_bf16_f32 v113, v118, v119
	v_add_f32_e32 v124, v120, v121
	v_pk_add_f32 v[120:121], v[114:115], v[210:211]
	v_cvt_pk_bf16_f32 v114, v122, v123
	s_nop 0
	v_cvt_pk_bf16_f32 v115, v120, v121
	global_store_dwordx4 v[190:191], v[112:115], off offset:256
	s_nop 1
	v_mul_f32_e32 v112, v117, v117
	v_mul_f32_e32 v113, v119, v119
	v_fmac_f32_e32 v112, v116, v116
	v_fmac_f32_e32 v113, v118, v118
	v_add_f32_e32 v112, v112, v113
	v_mul_f32_e32 v113, v123, v123
	v_mul_f32_e32 v114, v121, v121
	v_fmac_f32_e32 v113, v122, v122
	v_fmac_f32_e32 v114, v120, v120
	v_add_f32_e32 v113, v113, v114
	v_add_f32_e32 v112, v112, v113
	v_and_b32_e32 v114, 64, v209
	v_add_f32_e32 v113, v124, v112
	v_xor_b32_e32 v112, 16, v209
	v_add_u32_e32 v115, 64, v114
	v_cmp_lt_i32_e64 s[2:3], v112, v115
	s_nop 1
	v_cndmask_b32_e64 v112, v209, v112, s[2:3]
	v_lshlrev_b32_e32 v112, 2, v112
	ds_bpermute_b32 v114, v112, v113
	s_waitcnt lgkmcnt(0)
	v_add_f32_e32 v114, v113, v114
	v_xor_b32_e32 v113, 32, v209
	v_cmp_lt_i32_e64 s[2:3], v113, v115
	s_nop 1
	v_cndmask_b32_e64 v113, v209, v113, s[2:3]
	v_lshlrev_b32_e32 v113, 2, v113
	ds_bpermute_b32 v115, v113, v114
	s_and_saveexec_b64 s[2:3], vcc
	s_cbranch_execz .LBB0_917
	v_lshlrev_b64 v[116:117], 7, v[172:173]
	v_lshl_add_u64 v[116:117], s[16:17], 0, v[116:117]
	v_lshl_add_u64 v[116:117], s[18:19], 2, v[116:117]
	s_lshl_b32 s8, s27, 2
	v_lshl_add_u64 v[116:117], v[116:117], 0, s[8:9]
	s_waitcnt lgkmcnt(0)
	v_add_f32_e32 v114, v114, v115
	global_store_dword v[116:117], v114, off

; #define PG8_STAGE(bufoff, gbase, voff) do { _Pragma("unroll") for (int _i = 0; _i < 2; ++_i) \
;         __builtin_amdgcn_global_load_lds((const unsigned*)((const char*)(gbase) + (voff)[_i]), (LAS unsigned*)(lds + (bufoff) + ldsw + _i * 8192), 16, 0, 0); } while (0)
; #define PG8_LDA(dst, b, h) do { _Pragma("unroll") for (int m = 0; m < 4; ++m) _Pragma("unroll") for (int k = 0; k < 2; ++k) dst[m][k] = *(const LAS bf16x8*)(lds + PG8_SA(b, h) + aoff + m * 2048 + k * 1024); } while (0)
; #define PG8_LDB(dst, b, h) do { _Pragma("unroll") for (int n = 0; n < 2; ++n) _Pragma("unroll") for (int k = 0; k < 2; ++k) dst[n][k] = *(const LAS bf16x8*)(lds + PG8_SB(b, h) + boff + n * 2048 + k * 1024); } while (0)
; #define PG8_MMA(ai, bj, At, Bt) do { __builtin_amdgcn_s_setprio(1); _Pragma("unroll") for (int m = 0; m < 4; ++m) _Pragma("unroll") for (int n = 0; n < 2; ++n) _Pragma("unroll") for (int k = 0; k < 2; ++k) \
;         acc[ai][bj][m][n] = __builtin_amdgcn_mfma_f32_16x16x32_bf16(Bt[n][k], At[m][k], acc[ai][bj][m][n], 0, 0, 0); __builtin_amdgcn_s_setprio(0); } while (0)
; #define PG8_WAIT_L(n) asm volatile("s_waitcnt lgkmcnt(" #n ")" ::: "memory")
; #define PG8_BAR __builtin_amdgcn_s_barrier()
; #define PG8_SCHED __builtin_amdgcn_sched_barrier(0)
; template <class Epi, bool KS0 = false>
; __device__ __forceinline__ void gemm_phase(const int WID, LAS unsigned char* lds, const Gemm g, const StaticOrder& S, const Epi& E) {
;     ...
;         for (int t = 0; t < nt; t += 2) {
;             const bool last = (t == nt - 2);
;             const char* a1 = cA + (size_t)(t + 1) * kstep;
;             const char* a2 = last ? nA : cA + (size_t)(t + 2) * kstep; const char* b2 = last ? nB : cB + (size_t)(t + 2) * kstep;
;             const char* a3 = a2 + kstep; const char* b3 = b2 + kstep;
;             PG8_LDB(B0, 0, 0); PG8_SCHED; PG8_LDA(At, 0, 0); PG8_STAGE(PG8_SA(1, 1), a1 + hstep, voffA);
;             PG8_WAIT_L(8); PG8_BAR; PG8_WAIT_L(0); PG8_MMA(0, 0, At, B0); PG8_BAR; PG8_SCHED;
;             PG8_LDB(B1, 0, 1); PG8_STAGE(PG8_SB(0, 0), b2, voffB);
;             PG8_BAR; PG8_WAIT_L(0); PG8_MMA(0, 1, At, B1); PG8_BAR;
;             PG8_LDA(At, 0, 1); PG8_STAGE(PG8_SA(0, 0), a2, voffA);
;             PG8_BAR; PG8_WAIT_L(0); PG8_MMA(1, 0, At, B0); PG8_BAR; PG8_SCHED;
.LBB0_1006:
	ds_read_b128 v[104:107], v246
	ds_read_b128 v[108:111], v246 offset:1024
	ds_read_b128 v[112:115], v246 offset:2048
	ds_read_b128 v[120:123], v246 offset:3072
	s_add_u32 s10, s8, 0xfff80080
	s_addc_u32 s11, s9, -1
	s_cmp_eq_u32 s43, 28
	s_cselect_b32 s13, s3, s11
	s_cselect_b32 s12, s14, s10
	s_cselect_b32 s11, s15, s41
	s_cselect_b32 s10, s36, s37
	v_lshl_add_u64 v[176:177], s[8:9], 0, v[200:201]
	s_add_i32 m0, s18, 0xc000
	ds_read_b128 v[136:139], v247
	ds_read_b128 v[144:147], v247 offset:1024
	ds_read_b128 v[148:151], v247 offset:2048
	ds_read_b128 v[156:159], v247 offset:3072
	ds_read_b128 v[160:163], v247 offset:4096
	ds_read_b128 v[164:167], v247 offset:5120
	ds_read_b128 v[168:171], v247 offset:6144
	ds_read_b128 v[172:175], v247 offset:7168
	global_load_lds_dwordx4 v[176:177], off
	v_lshl_add_u64 v[176:177], s[8:9], 0, v[202:203]
	s_add_i32 m0, s18, 0xe000
	s_nop 0
	global_load_lds_dwordx4 v[176:177], off
	s_waitcnt lgkmcnt(8)
	s_barrier
	s_waitcnt lgkmcnt(0)
	s_waitcnt lgkmcnt(0)
	v_mfma_f32_16x16x32_bf16 v[152:155], v[104:107], v[136:139], v[152:155]
	v_mfma_f32_16x16x32_bf16 v[140:143], v[112:115], v[136:139], v[140:143]
	v_mfma_f32_16x16x32_bf16 v[124:127], v[104:107], v[148:151], v[124:127]
	v_mfma_f32_16x16x32_bf16 v[116:119], v[112:115], v[148:151], v[116:119]
	v_mfma_f32_16x16x32_bf16 v[92:95], v[104:107], v[160:163], v[92:95]
	v_mfma_f32_16x16x32_bf16 v[88:91], v[112:115], v[160:163], v[88:91]
	v_mfma_f32_16x16x32_bf16 v[76:79], v[104:107], v[168:171], v[76:79]
	v_mfma_f32_16x16x32_bf16 v[72:75], v[112:115], v[168:171], v[72:75]
	v_mfma_f32_16x16x32_bf16 v[152:155], v[108:111], v[144:147], v[152:155]
	v_mfma_f32_16x16x32_bf16 v[140:143], v[120:123], v[144:147], v[140:143]
	v_mfma_f32_16x16x32_bf16 v[124:127], v[108:111], v[156:159], v[124:127]
	v_mfma_f32_16x16x32_bf16 v[116:119], v[120:123], v[156:159], v[116:119]
	v_mfma_f32_16x16x32_bf16 v[92:95], v[108:111], v[164:167], v[92:95]
	v_mfma_f32_16x16x32_bf16 v[88:91], v[120:123], v[164:167], v[88:91]
	v_mfma_f32_16x16x32_bf16 v[76:79], v[108:111], v[172:175], v[76:79]
	v_mfma_f32_16x16x32_bf16 v[72:75], v[120:123], v[172:175], v[72:75]
	s_barrier
	s_add_i32 s48, s50, s26
	v_lshl_add_u64 v[210:211], s[10:11], 0, v[194:195]
	s_mov_b32 m0, s48
	ds_read_b128 v[176:179], v248
	ds_read_b128 v[180:183], v248 offset:1024
	ds_read_b128 v[184:187], v248 offset:2048
	ds_read_b128 v[188:191], v248 offset:3072
	global_load_lds_dwordx4 v[210:211], off
	v_lshl_add_u64 v[212:213], s[10:11], 0, v[198:199]
	s_add_i32 m0, s48, 0x2000
	s_nop 0
	global_load_lds_dwordx4 v[212:213], off
	s_barrier
	s_waitcnt lgkmcnt(0)
	s_waitcnt lgkmcnt(0)
	v_mfma_f32_16x16x32_bf16 v[132:135], v[176:179], v[136:139], v[132:135]
	v_mfma_f32_16x16x32_bf16 v[128:131], v[184:187], v[136:139], v[128:131]
	v_mfma_f32_16x16x32_bf16 v[100:103], v[176:179], v[148:151], v[100:103]
	v_mfma_f32_16x16x32_bf16 v[96:99], v[184:187], v[148:151], v[96:99]
	v_mfma_f32_16x16x32_bf16 v[84:87], v[176:179], v[160:163], v[84:87]
	v_mfma_f32_16x16x32_bf16 v[80:83], v[184:187], v[160:163], v[80:83]
	v_mfma_f32_16x16x32_bf16 v[68:71], v[176:179], v[168:171], v[68:71]
	v_mfma_f32_16x16x32_bf16 v[64:67], v[184:187], v[168:171], v[64:67]
	v_mfma_f32_16x16x32_bf16 v[132:135], v[180:183], v[144:147], v[132:135]
	v_mfma_f32_16x16x32_bf16 v[128:131], v[188:191], v[144:147], v[128:131]
	v_mfma_f32_16x16x32_bf16 v[100:103], v[180:183], v[156:159], v[100:103]
	v_mfma_f32_16x16x32_bf16 v[96:99], v[188:191], v[156:159], v[96:99]
	v_mfma_f32_16x16x32_bf16 v[84:87], v[180:183], v[164:167], v[84:87]
	v_mfma_f32_16x16x32_bf16 v[80:83], v[188:191], v[164:167], v[80:83]
	v_mfma_f32_16x16x32_bf16 v[68:71], v[180:183], v[172:175], v[68:71]
	v_mfma_f32_16x16x32_bf16 v[64:67], v[188:191], v[172:175], v[64:67]
	s_mov_b32 m0, s18
	v_lshl_add_u64 v[214:215], s[12:13], 0, v[192:193]
	s_barrier
	ds_read_b128 v[136:139], v247 offset:16384
	ds_read_b128 v[144:147], v247 offset:17408
	ds_read_b128 v[148:151], v247 offset:18432
	ds_read_b128 v[156:159], v247 offset:19456
	ds_read_b128 v[160:163], v247 offset:20480
	ds_read_b128 v[164:167], v247 offset:21504
	ds_read_b128 v[168:171], v247 offset:22528
	ds_read_b128 v[172:175], v247 offset:23552
	global_load_lds_dwordx4 v[214:215], off
	v_lshl_add_u64 v[216:217], s[12:13], 0, v[196:197]
	s_mov_b32 m0, s19
	s_nop 0
	global_load_lds_dwordx4 v[216:217], off
	s_barrier
	s_waitcnt lgkmcnt(0)
	s_waitcnt lgkmcnt(0)
	v_mfma_f32_16x16x32_bf16 v[60:63], v[104:107], v[136:139], v[60:63]
	v_mfma_f32_16x16x32_bf16 v[56:59], v[112:115], v[136:139], v[56:59]
	v_mfma_f32_16x16x32_bf16 v[44:47], v[104:107], v[148:151], v[44:47]
	v_mfma_f32_16x16x32_bf16 v[40:43], v[112:115], v[148:151], v[40:43]
	v_mfma_f32_16x16x32_bf16 v[28:31], v[104:107], v[160:163], v[28:31]
	v_mfma_f32_16x16x32_bf16 v[24:27], v[112:115], v[160:163], v[24:27]
	v_mfma_f32_16x16x32_bf16 v[12:15], v[104:107], v[168:171], v[12:15]
	v_mfma_f32_16x16x32_bf16 v[8:11], v[112:115], v[168:171], v[8:11]
	v_mfma_f32_16x16x32_bf16 v[60:63], v[108:111], v[144:147], v[60:63]
	v_mfma_f32_16x16x32_bf16 v[56:59], v[120:123], v[144:147], v[56:59]
	v_mfma_f32_16x16x32_bf16 v[44:47], v[108:111], v[156:159], v[44:47]
	v_mfma_f32_16x16x32_bf16 v[40:43], v[120:123], v[156:159], v[40:43]
	v_mfma_f32_16x16x32_bf16 v[28:31], v[108:111], v[164:167], v[28:31]
	v_mfma_f32_16x16x32_bf16 v[24:27], v[120:123], v[164:167], v[24:27]
	v_mfma_f32_16x16x32_bf16 v[12:15], v[108:111], v[172:175], v[12:15]
	v_mfma_f32_16x16x32_bf16 v[8:11], v[120:123], v[172:175], v[8:11]
	s_barrier
; #define PG8_STAGE(bufoff, gbase, voff) do { _Pragma("unroll") for (int _i = 0; _i < 2; ++_i) \
;         __builtin_amdgcn_global_load_lds((const unsigned*)((const char*)(gbase) + (voff)[_i]), (LAS unsigned*)(lds + (bufoff) + ldsw + _i * 8192), 16, 0, 0); } while (0)
; #define PG8_LDA(dst, b, h) do { _Pragma("unroll") for (int m = 0; m < 4; ++m) _Pragma("unroll") for (int k = 0; k < 2; ++k) dst[m][k] = *(const LAS bf16x8*)(lds + PG8_SA(b, h) + aoff + m * 2048 + k * 1024); } while (0)
; #define PG8_LDB(dst, b, h) do { _Pragma("unroll") for (int n = 0; n < 2; ++n) _Pragma("unroll") for (int k = 0; k < 2; ++k) dst[n][k] = *(const LAS bf16x8*)(lds + PG8_SB(b, h) + boff + n * 2048 + k * 1024); } while (0)
; #define PG8_MMA(ai, bj, At, Bt) do { __builtin_amdgcn_s_setprio(1); _Pragma("unroll") for (int m = 0; m < 4; ++m) _Pragma("unroll") for (int n = 0; n < 2; ++n) _Pragma("unroll") for (int k = 0; k < 2; ++k) \
;         acc[ai][bj][m][n] = __builtin_amdgcn_mfma_f32_16x16x32_bf16(Bt[n][k], At[m][k], acc[ai][bj][m][n], 0, 0, 0); __builtin_amdgcn_s_setprio(0); } while (0)
; #define PG8_WAIT_V(n) asm volatile("s_waitcnt vmcnt(" #n ")" ::: "memory")
; #define PG8_WAIT_L(n) asm volatile("s_waitcnt lgkmcnt(" #n ")" ::: "memory")
; #define PG8_BAR __builtin_amdgcn_s_barrier()
; #define PG8_SCHED __builtin_amdgcn_sched_barrier(0)
; template <class Epi, bool KS0 = false>
; __device__ __forceinline__ void gemm_phase(const int WID, LAS unsigned char* lds, const Gemm g, const StaticOrder& S, const Epi& E) {
;     ...
;             PG8_STAGE(PG8_SB(0, 1), b2 + hstep, voffB);
;             PG8_WAIT_V(6); PG8_BAR; PG8_MMA(1, 1, At, B1); PG8_BAR;
;             PG8_LDB(B0, 1, 0); PG8_SCHED; PG8_LDA(At, 1, 0); PG8_STAGE(PG8_SA(0, 1), a2 + hstep, voffA);
;             PG8_WAIT_L(8); PG8_BAR; PG8_WAIT_L(0); PG8_MMA(0, 0, At, B0); PG8_BAR; PG8_SCHED;
;             PG8_LDB(B1, 1, 1); PG8_STAGE(PG8_SB(1, 0), b3, voffB);
;             PG8_BAR; PG8_WAIT_L(0); PG8_MMA(0, 1, At, B1); PG8_BAR;
;             PG8_LDA(At, 1, 1); PG8_STAGE(PG8_SA(1, 0), a3, voffA);
	s_add_u32 s48, s10, 0x80000
	s_addc_u32 s49, s11, 0
	s_add_i32 s54, s51, s26
	v_lshl_add_u64 v[104:105], s[48:49], 0, v[194:195]
	s_mov_b32 m0, s54
	s_nop 0
	global_load_lds_dwordx4 v[104:105], off
	v_lshl_add_u64 v[104:105], s[48:49], 0, v[198:199]
	s_add_i32 m0, s54, 0x2000
	s_nop 0
	global_load_lds_dwordx4 v[104:105], off
	s_waitcnt vmcnt(6)
	s_barrier
	v_mfma_f32_16x16x32_bf16 v[52:55], v[176:179], v[136:139], v[52:55]
	v_mfma_f32_16x16x32_bf16 v[48:51], v[184:187], v[136:139], v[48:51]
	v_mfma_f32_16x16x32_bf16 v[36:39], v[176:179], v[148:151], v[36:39]
	v_mfma_f32_16x16x32_bf16 v[32:35], v[184:187], v[148:151], v[32:35]
	v_mfma_f32_16x16x32_bf16 v[20:23], v[176:179], v[160:163], v[20:23]
	v_mfma_f32_16x16x32_bf16 v[16:19], v[184:187], v[160:163], v[16:19]
	v_mfma_f32_16x16x32_bf16 v[4:7], v[176:179], v[168:171], v[4:7]
	v_mfma_f32_16x16x32_bf16 v[0:3], v[184:187], v[168:171], v[0:3]
	v_mfma_f32_16x16x32_bf16 v[52:55], v[180:183], v[144:147], v[52:55]
	v_mfma_f32_16x16x32_bf16 v[48:51], v[188:191], v[144:147], v[48:51]
	v_mfma_f32_16x16x32_bf16 v[36:39], v[180:183], v[156:159], v[36:39]
	v_mfma_f32_16x16x32_bf16 v[32:35], v[188:191], v[156:159], v[32:35]
	v_mfma_f32_16x16x32_bf16 v[20:23], v[180:183], v[164:167], v[20:23]
	v_mfma_f32_16x16x32_bf16 v[16:19], v[188:191], v[164:167], v[16:19]
	v_mfma_f32_16x16x32_bf16 v[4:7], v[180:183], v[172:175], v[4:7]
	v_mfma_f32_16x16x32_bf16 v[0:3], v[188:191], v[172:175], v[0:3]
	s_add_i32 s48, 0, 0x18000
	v_add_u32_e32 v120, s48, v245
	s_barrier
	ds_read_b128 v[104:107], v120
	ds_read_b128 v[108:111], v120 offset:1024
	ds_read_b128 v[112:115], v120 offset:2048
	ds_read_b128 v[120:123], v120 offset:3072
	s_add_u32 s12, s12, 0x80000
	s_addc_u32 s13, s13, 0
	s_mov_b32 m0, s20
	v_lshl_add_u64 v[176:177], s[12:13], 0, v[192:193]
	ds_read_b128 v[136:139], v247 offset:32768
	ds_read_b128 v[144:147], v247 offset:33792
	ds_read_b128 v[148:151], v247 offset:34816
	ds_read_b128 v[156:159], v247 offset:35840
	ds_read_b128 v[160:163], v247 offset:36864
	ds_read_b128 v[164:167], v247 offset:37888
	ds_read_b128 v[168:171], v247 offset:38912
	ds_read_b128 v[172:175], v247 offset:39936
	global_load_lds_dwordx4 v[176:177], off
	v_lshl_add_u64 v[176:177], s[12:13], 0, v[196:197]
	s_mov_b32 m0, s21
	s_nop 0
	global_load_lds_dwordx4 v[176:177], off
	s_waitcnt lgkmcnt(8)
	s_barrier
	s_waitcnt lgkmcnt(0)
	s_waitcnt lgkmcnt(0)
	v_mfma_f32_16x16x32_bf16 v[152:155], v[104:107], v[136:139], v[152:155]
	v_mfma_f32_16x16x32_bf16 v[140:143], v[112:115], v[136:139], v[140:143]
	v_mfma_f32_16x16x32_bf16 v[124:127], v[104:107], v[148:151], v[124:127]
	v_mfma_f32_16x16x32_bf16 v[116:119], v[112:115], v[148:151], v[116:119]
	v_mfma_f32_16x16x32_bf16 v[92:95], v[104:107], v[160:163], v[92:95]
	v_mfma_f32_16x16x32_bf16 v[88:91], v[112:115], v[160:163], v[88:91]
	v_mfma_f32_16x16x32_bf16 v[76:79], v[104:107], v[168:171], v[76:79]
	v_mfma_f32_16x16x32_bf16 v[72:75], v[112:115], v[168:171], v[72:75]
	v_mfma_f32_16x16x32_bf16 v[152:155], v[108:111], v[144:147], v[152:155]
	v_mfma_f32_16x16x32_bf16 v[140:143], v[120:123], v[144:147], v[140:143]
	v_mfma_f32_16x16x32_bf16 v[124:127], v[108:111], v[156:159], v[124:127]
	v_mfma_f32_16x16x32_bf16 v[116:119], v[120:123], v[156:159], v[116:119]
	v_mfma_f32_16x16x32_bf16 v[92:95], v[108:111], v[164:167], v[92:95]
	v_mfma_f32_16x16x32_bf16 v[88:91], v[120:123], v[164:167], v[88:91]
	v_mfma_f32_16x16x32_bf16 v[76:79], v[108:111], v[172:175], v[76:79]
	v_mfma_f32_16x16x32_bf16 v[72:75], v[120:123], v[172:175], v[72:75]
	s_barrier
	s_add_i32 s12, 0, 0x1c000
	s_add_i32 s13, s48, s26
	v_add_u32_e32 v188, s12, v245
	v_lshl_add_u64 v[210:211], v[210:211], 0, s[30:31]
	s_mov_b32 m0, s13
	ds_read_b128 v[176:179], v188
	ds_read_b128 v[180:183], v188 offset:1024
	ds_read_b128 v[184:187], v188 offset:2048
	ds_read_b128 v[188:191], v188 offset:3072
	global_load_lds_dwordx4 v[210:211], off
	v_lshl_add_u64 v[210:211], v[212:213], 0, s[30:31]
	s_add_i32 m0, s13, 0x2000
	s_nop 0
	global_load_lds_dwordx4 v[210:211], off
	s_barrier
	s_waitcnt lgkmcnt(0)
	s_waitcnt lgkmcnt(0)
	v_mfma_f32_16x16x32_bf16 v[132:135], v[176:179], v[136:139], v[132:135]
	v_mfma_f32_16x16x32_bf16 v[128:131], v[184:187], v[136:139], v[128:131]
	v_mfma_f32_16x16x32_bf16 v[100:103], v[176:179], v[148:151], v[100:103]
	v_mfma_f32_16x16x32_bf16 v[96:99], v[184:187], v[148:151], v[96:99]
	v_mfma_f32_16x16x32_bf16 v[84:87], v[176:179], v[160:163], v[84:87]
	v_mfma_f32_16x16x32_bf16 v[80:83], v[184:187], v[160:163], v[80:83]
	v_mfma_f32_16x16x32_bf16 v[68:71], v[176:179], v[168:171], v[68:71]
	v_mfma_f32_16x16x32_bf16 v[64:67], v[184:187], v[168:171], v[64:67]
	v_mfma_f32_16x16x32_bf16 v[132:135], v[180:183], v[144:147], v[132:135]
	v_mfma_f32_16x16x32_bf16 v[128:131], v[188:191], v[144:147], v[128:131]
	v_mfma_f32_16x16x32_bf16 v[100:103], v[180:183], v[156:159], v[100:103]
	v_mfma_f32_16x16x32_bf16 v[96:99], v[188:191], v[156:159], v[96:99]
	v_mfma_f32_16x16x32_bf16 v[84:87], v[180:183], v[164:167], v[84:87]
	v_mfma_f32_16x16x32_bf16 v[80:83], v[188:191], v[164:167], v[80:83]
	v_mfma_f32_16x16x32_bf16 v[68:71], v[180:183], v[172:175], v[68:71]
	v_mfma_f32_16x16x32_bf16 v[64:67], v[188:191], v[172:175], v[64:67]
	s_mov_b32 m0, s25
	v_lshl_add_u64 v[210:211], v[214:215], 0, s[30:31]
	s_barrier
	ds_read_b128 v[136:139], v247 offset:49152
	ds_read_b128 v[144:147], v247 offset:50176
	ds_read_b128 v[148:151], v247 offset:51200
	ds_read_b128 v[156:159], v247 offset:52224
	ds_read_b128 v[160:163], v247 offset:53248
	ds_read_b128 v[164:167], v247 offset:54272
	ds_read_b128 v[168:171], v247 offset:55296
	ds_read_b128 v[172:175], v247 offset:56320
	global_load_lds_dwordx4 v[210:211], off
	v_lshl_add_u64 v[210:211], v[216:217], 0, s[30:31]
	s_mov_b32 m0, s39
	s_nop 0
	global_load_lds_dwordx4 v[210:211], off
	s_barrier
; #define PG8_STAGE(bufoff, gbase, voff) do { _Pragma("unroll") for (int _i = 0; _i < 2; ++_i) \
;         __builtin_amdgcn_global_load_lds((const unsigned*)((const char*)(gbase) + (voff)[_i]), (LAS unsigned*)(lds + (bufoff) + ldsw + _i * 8192), 16, 0, 0); } while (0)
; #define PG8_MMA(ai, bj, At, Bt) do { __builtin_amdgcn_s_setprio(1); _Pragma("unroll") for (int m = 0; m < 4; ++m) _Pragma("unroll") for (int n = 0; n < 2; ++n) _Pragma("unroll") for (int k = 0; k < 2; ++k) \
;         acc[ai][bj][m][n] = __builtin_amdgcn_mfma_f32_16x16x32_bf16(Bt[n][k], At[m][k], acc[ai][bj][m][n], 0, 0, 0); __builtin_amdgcn_s_setprio(0); } while (0)
; #define PG8_WAIT_V(n) asm volatile("s_waitcnt vmcnt(" #n ")" ::: "memory")
; #define PG8_WAIT_L(n) asm volatile("s_waitcnt lgkmcnt(" #n ")" ::: "memory")
; #define PG8_BAR __builtin_amdgcn_s_barrier()
; #define PG8_SCHED __builtin_amdgcn_sched_barrier(0)
; template <class Epi, bool KS0 = false>
; __device__ __forceinline__ void gemm_phase(const int WID, LAS unsigned char* lds, const Gemm g, const StaticOrder& S, const Epi& E) {
;     ...
;             PG8_BAR; PG8_WAIT_L(0); PG8_MMA(1, 0, At, B0); PG8_BAR; PG8_SCHED;
;             PG8_STAGE(PG8_SB(1, 1), b3 + hstep, voffB);
;             PG8_WAIT_V(6); PG8_BAR; PG8_MMA(1, 1, At, B1); PG8_BAR;
;         }
;     __device__ __forceinline__ void operator()(f32x4 (&acc)[2][2][4][2], const Unit& u, int wr, int wc, int fr, int fq) const {
;         const int row0 = u.pm * BM + wr * 64 + fr, col0 = u.pn * BM + wc * 32 + 8 * fq;
;         const bf16_t* ppf = pp + ((size_t)(u.pm * (DM / 256) + u.pn) << 16) + (size_t)((((wr * 4 + wc) * 16) * 64 + fq * 16 + fr) << 3);
; #pragma unroll
;         for (int ai = 0; ai < 2; ++ai) {
;             u32x4 hw[4][2], pw[4][2]; float rstd[4];
; #pragma unroll
;             for (int m = 0; m < 4; ++m) { const int row = row0 + ai * HALF + m * 16;
; #pragma unroll
;                 for (int bj = 0; bj < 2; ++bj) { const size_t o = (size_t)row * DM + col0 + bj * HALF; hw[m][bj] = *(const u32x4*)(hb + o); pw[m][bj] = *(const u32x4*)(ppf + (((ai * 4 + m) * 2 + bj) << 9)); }
;                 rstd[m] = row_rstd(ssq_in, row, fq); }
	s_waitcnt lgkmcnt(0)
	s_waitcnt lgkmcnt(0)
	v_mfma_f32_16x16x32_bf16 v[60:63], v[104:107], v[136:139], v[60:63]
	v_mfma_f32_16x16x32_bf16 v[56:59], v[112:115], v[136:139], v[56:59]
	v_mfma_f32_16x16x32_bf16 v[44:47], v[104:107], v[148:151], v[44:47]
	v_mfma_f32_16x16x32_bf16 v[40:43], v[112:115], v[148:151], v[40:43]
	v_mfma_f32_16x16x32_bf16 v[28:31], v[104:107], v[160:163], v[28:31]
	v_mfma_f32_16x16x32_bf16 v[24:27], v[112:115], v[160:163], v[24:27]
	v_mfma_f32_16x16x32_bf16 v[12:15], v[104:107], v[168:171], v[12:15]
	v_mfma_f32_16x16x32_bf16 v[8:11], v[112:115], v[168:171], v[8:11]
	v_mfma_f32_16x16x32_bf16 v[60:63], v[108:111], v[144:147], v[60:63]
	v_mfma_f32_16x16x32_bf16 v[56:59], v[120:123], v[144:147], v[56:59]
	v_mfma_f32_16x16x32_bf16 v[44:47], v[108:111], v[156:159], v[44:47]
	v_mfma_f32_16x16x32_bf16 v[40:43], v[120:123], v[156:159], v[40:43]
	v_mfma_f32_16x16x32_bf16 v[28:31], v[108:111], v[164:167], v[28:31]
	v_mfma_f32_16x16x32_bf16 v[24:27], v[120:123], v[164:167], v[24:27]
	v_mfma_f32_16x16x32_bf16 v[12:15], v[108:111], v[172:175], v[12:15]
	v_mfma_f32_16x16x32_bf16 v[8:11], v[120:123], v[172:175], v[8:11]
	s_barrier
	s_add_u32 s10, s10, 0x80080
	s_addc_u32 s11, s11, 0
	s_add_i32 s12, s12, s26
	v_lshl_add_u64 v[104:105], s[10:11], 0, v[194:195]
	s_mov_b32 m0, s12
	s_nop 0
	global_load_lds_dwordx4 v[104:105], off
	v_lshl_add_u64 v[104:105], s[10:11], 0, v[198:199]
	s_add_i32 m0, s12, 0x2000
	s_nop 0
	global_load_lds_dwordx4 v[104:105], off
	s_waitcnt vmcnt(6)
	s_barrier
	v_mfma_f32_16x16x32_bf16 v[52:55], v[176:179], v[136:139], v[52:55]
	v_mfma_f32_16x16x32_bf16 v[48:51], v[184:187], v[136:139], v[48:51]
	v_mfma_f32_16x16x32_bf16 v[36:39], v[176:179], v[148:151], v[36:39]
	v_mfma_f32_16x16x32_bf16 v[32:35], v[184:187], v[148:151], v[32:35]
	v_mfma_f32_16x16x32_bf16 v[20:23], v[176:179], v[160:163], v[20:23]
	v_mfma_f32_16x16x32_bf16 v[16:19], v[184:187], v[160:163], v[16:19]
	v_mfma_f32_16x16x32_bf16 v[4:7], v[176:179], v[168:171], v[4:7]
	v_mfma_f32_16x16x32_bf16 v[0:3], v[184:187], v[168:171], v[0:3]
	v_mfma_f32_16x16x32_bf16 v[52:55], v[180:183], v[144:147], v[52:55]
	v_mfma_f32_16x16x32_bf16 v[48:51], v[188:191], v[144:147], v[48:51]
	v_mfma_f32_16x16x32_bf16 v[36:39], v[180:183], v[156:159], v[36:39]
	v_mfma_f32_16x16x32_bf16 v[32:35], v[188:191], v[156:159], v[32:35]
	v_mfma_f32_16x16x32_bf16 v[20:23], v[180:183], v[164:167], v[20:23]
	v_mfma_f32_16x16x32_bf16 v[16:19], v[188:191], v[164:167], v[16:19]
	v_mfma_f32_16x16x32_bf16 v[4:7], v[180:183], v[172:175], v[4:7]
	v_mfma_f32_16x16x32_bf16 v[0:3], v[188:191], v[172:175], v[0:3]
	s_add_i32 s43, s43, 2
	s_add_u32 s8, s8, 0x100
	s_addc_u32 s9, s9, 0
	s_add_u32 s37, s37, 0x100
	s_addc_u32 s41, s41, 0
	s_cmp_gt_u32 s43, 29
	s_barrier
	s_cbranch_scc0 .LBB0_1006
	s_lshl_b32 s3, s4, 8
	v_mbcnt_lo_u32_b32 v104, -1, 0
	v_mbcnt_hi_u32_b32 v104, -1, v104
	s_add_i32 s3, s3, s22
	v_ashrrev_i32_e32 v108, 4, v104
	v_and_b32_e32 v109, 15, v104
	v_readlane_b32 s8, v254, 19
	v_add_u32_e32 v212, s3, v109
	v_lshlrev_b32_e32 v104, 3, v108
	v_ashrrev_i32_e32 v105, 31, v104
	v_ashrrev_i32_e32 v213, 31, v212
	v_add_u32_e32 v160, 16, v212
	v_lshl_add_u64 v[214:215], v[104:105], 2, s[16:17]
	v_lshlrev_b64 v[236:237], 7, v[212:213]
	v_ashrrev_i32_e32 v161, 31, v160
	v_lshl_add_u64 v[106:107], v[214:215], 0, v[236:237]
	v_lshlrev_b64 v[228:229], 7, v[160:161]
	global_load_dwordx4 v[136:139], v[106:107], off
	global_load_dwordx4 v[144:147], v[106:107], off offset:16
	v_lshl_add_u64 v[106:107], v[214:215], 0, v[228:229]
	global_load_dwordx4 v[148:151], v[106:107], off
	global_load_dwordx4 v[156:159], v[106:107], off offset:16
	v_and_b32_e32 v106, 64, v209
	v_xor_b32_e32 v105, 16, v209
	v_add_u32_e32 v106, 64, v106
	v_add_u32_e32 v162, 32, v212
	v_xor_b32_e32 v107, 32, v209
	v_cmp_lt_i32_e32 vcc, v105, v106
	v_ashrrev_i32_e32 v163, 31, v162
	v_lshlrev_b64 v[222:223], 7, v[162:163]
	v_cndmask_b32_e32 v105, v209, v105, vcc
	v_cmp_lt_i32_e32 vcc, v107, v106
	v_add_u32_e32 v226, 48, v212
	s_lshl_b32 s3, s2, 8
	v_cndmask_b32_e32 v110, v209, v107, vcc
	v_lshl_add_u64 v[106:107], v[214:215], 0, v[222:223]
	v_ashrrev_i32_e32 v227, 31, v226
	s_or_b32 s3, s3, s8
	global_load_dwordx4 v[112:115], v[106:107], off
	global_load_dwordx4 v[120:123], v[106:107], off offset:16
	v_lshlrev_b64 v[220:221], 7, v[226:227]
	v_lshlrev_b32_e32 v250, 2, v105
	v_add_u32_e32 v210, s3, v104
	v_lshl_add_u64 v[104:105], v[214:215], 0, v[220:221]
	v_add_u32_e32 v164, s55, v109
	v_lshlrev_b32_e32 v165, 7, v108
	v_lshlrev_b32_e32 v249, 2, v110
	v_cmp_eq_u32_e64 s[36:37], 0, v108
	global_load_dwordx4 v[108:111], v[104:105], off
	s_nop 0
	global_load_dwordx4 v[104:107], v[104:105], off offset:16
	s_lshl_b32 s4, s4, 3
	s_add_i32 s8, s4, s2
	s_ashr_i32 s9, s8, 31
	s_lshl_b64 s[8:9], s[8:9], 17
	v_ashrrev_i32_e32 v211, 31, v210
	s_add_u32 s8, s23, s8
	v_lshl_add_u32 v164, v164, 3, v165
	v_lshlrev_b64 v[240:241], 1, v[210:211]
	s_addc_u32 s9, s24, s9
	v_ashrrev_i32_e32 v165, 31, v164
	v_lshlrev_b64 v[238:239], 12, v[212:213]
	v_lshl_add_u64 v[216:217], s[6:7], 0, v[240:241]
	v_lshl_add_u64 v[218:219], v[164:165], 1, s[8:9]
	v_lshl_add_u64 v[164:165], v[216:217], 0, v[238:239]
	global_load_dwordx4 v[184:187], v[218:219], off
	global_load_dwordx4 v[188:191], v[164:165], off
	global_load_dwordx4 v[176:179], v[218:219], off offset:1024
	s_lshl_b32 s48, s2, 2
	v_lshlrev_b64 v[234:235], 12, v[160:161]
	v_lshlrev_b64 v[224:225], 12, v[162:163]
	v_lshlrev_b64 v[226:227], 12, v[226:227]
	s_ashr_i32 s49, s48, 31
	s_waitcnt vmcnt(0)
; __device__ __forceinline__ float bflo(unsigned w) { return __uint_as_float(w << 16); }
; __device__ __forceinline__ float bfhi(unsigned w) { return __uint_as_float(w & 0xffff0000u); }
; __device__ __forceinline__ float sigmoidf_(float x) { return __builtin_amdgcn_rcpf(1.0f + __expf(-x)); }
; __device__ __forceinline__ float row_rstd(const float* ssq, int row, int fq) {
;     const f32x4 a = *(const f32x4*)(ssq + (size_t)row * 32 + 8 * fq), b = *(const f32x4*)(ssq + (size_t)row * 32 + 8 * fq + 4);
;     float t = ((a[0] + a[1]) + (a[2] + a[3])) + ((b[0] + b[1]) + (b[2] + b[3]));
;     t += __shfl_xor(t, 16); t += __shfl_xor(t, 32);
;     return rsqrtf(t * (1.0f / 2048.0f) + EPS);
;     __device__ __forceinline__ void operator()(f32x4 (&acc)[2][2][4][2], const Unit& u, int wr, int wc, int fr, int fq) const {
;     ...
;             for (int m = 0; m < 4; ++m) { const int row = row0 + ai * HALF + m * 16; const size_t off = (size_t)row * DM + col0; float s = 0.f;
; #pragma unroll
;                 for (int bj = 0; bj < 2; ++bj) { const f32x4 z0 = acc[ai][bj][m][0] * rstd[m], z1 = acc[ai][bj][m][1] * rstd[m]; const u32x4 h2 = hw[m][bj], p2 = pw[m][bj]; f32x4 v0, v1;
;                     v0[0] = bflo(h2.x) + sigmoidf_(z0[0]) * bflo(p2.x); v0[1] = bfhi(h2.x) + sigmoidf_(z0[1]) * bfhi(p2.x);
;                     v0[2] = bflo(h2.y) + sigmoidf_(z0[2]) * bflo(p2.y); v0[3] = bfhi(h2.y) + sigmoidf_(z0[3]) * bfhi(p2.y);
;                     v1[0] = bflo(h2.z) + sigmoidf_(z1[0]) * bflo(p2.z); v1[1] = bfhi(h2.z) + sigmoidf_(z1[1]) * bfhi(p2.z);
;                     v1[2] = bflo(h2.w) + sigmoidf_(z1[2]) * bflo(p2.w); v1[3] = bfhi(h2.w) + sigmoidf_(z1[3]) * bfhi(p2.w);
	v_mov_b32_e32 v166, v136
	v_mov_b32_e32 v167, v144
	v_mov_b32_e32 v144, v137
	v_mov_b32_e32 v136, v138
	v_mov_b32_e32 v137, v146
	v_mov_b32_e32 v146, v139
	v_pk_add_f32 v[138:139], v[166:167], v[144:145]
	v_pk_add_f32 v[136:137], v[136:137], v[146:147]
	v_mov_b32_e32 v144, v148
	v_mov_b32_e32 v145, v156
	v_mov_b32_e32 v156, v149
	v_mov_b32_e32 v146, v150
	v_mov_b32_e32 v147, v158
	v_mov_b32_e32 v158, v151
	v_pk_add_f32 v[136:137], v[138:139], v[136:137]
	v_pk_add_f32 v[138:139], v[144:145], v[156:157]
	v_pk_add_f32 v[144:145], v[146:147], v[158:159]
	v_lshl_add_u64 v[150:151], v[216:217], 0, v[234:235]
	v_pk_add_f32 v[138:139], v[138:139], v[144:145]
	v_mov_b32_e32 v145, v136
	v_mov_b32_e32 v144, v138
	v_mov_b32_e32 v136, v139
	v_pk_add_f32 v[136:137], v[144:145], v[136:137]
	ds_bpermute_b32 v139, v250, v137
	ds_bpermute_b32 v138, v250, v136
	v_mov_b32_e32 v232, v112
	v_mov_b32_e32 v233, v120
	v_mov_b32_e32 v120, v113
	v_pk_add_f32 v[112:113], v[232:233], v[120:121]
	s_waitcnt lgkmcnt(0)
	v_pk_add_f32 v[146:147], v[136:137], v[138:139]
	global_load_dwordx4 v[168:171], v[218:219], off offset:2048
	global_load_dwordx4 v[136:139], v[218:219], off offset:3072
	global_load_dwordx4 v[180:183], v[164:165], off offset:256
	ds_bpermute_b32 v149, v249, v147
	ds_bpermute_b32 v148, v249, v146
	v_mov_b32_e32 v120, v114
	v_mov_b32_e32 v121, v122
	v_mov_b32_e32 v122, v115
	v_pk_add_f32 v[114:115], v[120:121], v[122:123]
	s_waitcnt lgkmcnt(0)
	v_pk_add_f32 v[146:147], v[146:147], v[148:149]
	v_mov_b32_e32 v120, v108
	v_pk_fma_f32 v[242:243], v[146:147], s[38:39], v[208:209] op_sel_hi:[1,0,0]
	v_mov_b32_e32 v121, v104
	v_mul_f32_e32 v146, 0x4b800000, v243
	v_cmp_gt_f32_e64 s[2:3], s52, v243
	v_mov_b32_e32 v104, v109
	v_mov_b32_e32 v108, v110
	v_cndmask_b32_e64 v146, v243, v146, s[2:3]
	v_rsq_f32_e32 v146, v146
	v_mov_b32_e32 v109, v106
	v_mov_b32_e32 v106, v111
	v_pk_add_f32 v[104:105], v[120:121], v[104:105]
	v_mul_f32_e32 v147, 0x45800000, v146
	v_cndmask_b32_e64 v244, v146, v147, s[2:3]
	v_pk_add_f32 v[106:107], v[108:109], v[106:107]
	v_pk_mul_f32 v[152:153], v[152:153], v[244:245] op_sel_hi:[1,0]
	s_movk_i32 s2, 0x1000
	v_pk_add_f32 v[112:113], v[112:113], v[114:115]
	v_pk_add_f32 v[104:105], v[104:105], v[106:107]
	v_mul_f32_e32 v152, 0xbfb8aa3b, v152
	v_lshl_add_u64 v[144:145], v[216:217], 0, v[224:225]
	v_add_co_u32_e64 v230, s[2:3], s2, v218
	v_lshl_add_u64 v[114:115], v[216:217], 0, v[226:227]
	v_mov_b32_e32 v106, v104
	v_mov_b32_e32 v107, v112
	v_mov_b32_e32 v112, v105
	v_exp_f32_e32 v152, v152
	v_mul_f32_e32 v153, 0xbfb8aa3b, v153
	global_load_dwordx4 v[172:175], v[150:151], off
	global_load_dwordx4 v[156:159], v[150:151], off offset:256
	v_addc_co_u32_e64 v231, s[2:3], 0, v219, s[2:3]
	global_load_dwordx4 v[160:163], v[144:145], off
	s_nop 0
	global_load_dwordx4 v[144:147], v[144:145], off offset:256
	s_nop 0
	global_load_dwordx4 v[164:167], v[230:231], off
	global_load_dwordx4 v[148:151], v[230:231], off offset:1024
	v_pk_add_f32 v[232:233], v[106:107], v[112:113]
	global_load_dwordx4 v[120:123], v[114:115], off
	global_load_dwordx4 v[108:111], v[114:115], off offset:256
	s_nop 0
	global_load_dwordx4 v[112:115], v[230:231], off offset:2048
	global_load_dwordx4 v[104:107], v[230:231], off offset:3072
	v_exp_f32_e32 v153, v153
	v_add_f32_e32 v152, 1.0, v152
	v_rcp_f32_e32 v152, v152
	v_lshlrev_b32_e32 v213, 16, v188
	v_add_f32_e32 v153, 1.0, v153
	v_rcp_f32_e32 v153, v153
	v_lshlrev_b32_e32 v243, 16, v184
	v_pk_mul_f32 v[154:155], v[154:155], v[244:245] op_sel_hi:[1,0]
	v_fmac_f32_e32 v213, v152, v243
	v_and_b32_e32 v152, 0xffff0000, v188
	v_and_b32_e32 v184, 0xffff0000, v184
	v_fmac_f32_e32 v152, v153, v184
	v_mul_f32_e32 v153, 0xbfb8aa3b, v154
	v_pk_mul_f32 v[140:141], v[140:141], v[244:245] op_sel_hi:[1,0]
	v_exp_f32_e32 v153, v153
	v_mul_f32_e32 v155, 0xbfb8aa3b, v155
	v_exp_f32_e32 v155, v155
	v_mul_f32_e32 v140, 0xbfb8aa3b, v140
	v_exp_f32_e32 v140, v140
	v_mul_f32_e32 v141, 0xbfb8aa3b, v141
	v_exp_f32_e32 v141, v141
	v_add_f32_e32 v153, 1.0, v153
	v_rcp_f32_e32 v153, v153
	v_add_f32_e32 v155, 1.0, v155
	v_rcp_f32_e32 v155, v155
	v_add_f32_e32 v140, 1.0, v140
	v_rcp_f32_e32 v140, v140
	v_add_f32_e32 v141, 1.0, v141
	v_lshlrev_b32_e32 v154, 16, v189
	v_lshlrev_b32_e32 v184, 16, v185
	v_rcp_f32_e32 v141, v141
	v_fmac_f32_e32 v154, v153, v184
	v_and_b32_e32 v153, 0xffff0000, v189
	v_and_b32_e32 v184, 0xffff0000, v185
	v_fmac_f32_e32 v153, v155, v184
	v_lshlrev_b32_e32 v155, 16, v190
	v_lshlrev_b32_e32 v184, 16, v186
	v_pk_mul_f32 v[142:143], v[142:143], v[244:245] op_sel_hi:[1,0]
	v_fmac_f32_e32 v155, v140, v184
	v_and_b32_e32 v184, 0xffff0000, v190
	v_and_b32_e32 v140, 0xffff0000, v186
	v_fmac_f32_e32 v184, v141, v140
	v_mul_f32_e32 v140, 0xbfb8aa3b, v142
	v_exp_f32_e32 v140, v140
	v_mul_f32_e32 v141, 0xbfb8aa3b, v143
	v_exp_f32_e32 v141, v141
	v_pk_mul_f32 v[132:133], v[132:133], v[244:245] op_sel_hi:[1,0]
	v_add_f32_e32 v140, 1.0, v140
	v_rcp_f32_e32 v140, v140
	v_add_f32_e32 v141, 1.0, v141
	v_rcp_f32_e32 v141, v141
	v_mul_f32_e32 v132, 0xbfb8aa3b, v132
	v_exp_f32_e32 v132, v132
	v_mul_f32_e32 v133, 0xbfb8aa3b, v133
	v_lshlrev_b32_e32 v185, 16, v191
	v_lshlrev_b32_e32 v142, 16, v187
	v_exp_f32_e32 v133, v133
	v_fmac_f32_e32 v185, v140, v142
	v_and_b32_e32 v186, 0xffff0000, v191
	v_and_b32_e32 v140, 0xffff0000, v187
	v_fmac_f32_e32 v186, v141, v140
	v_cvt_pk_bf16_f32 v140, v213, v152
	v_cvt_pk_bf16_f32 v141, v154, v153
	v_mul_f32_e32 v152, v152, v152
	v_mul_f32_e32 v153, v153, v153
	v_fmac_f32_e32 v152, v213, v213
	v_fmac_f32_e32 v153, v154, v154
	v_add_f32_e32 v132, 1.0, v132
	v_add_f32_e32 v152, v152, v153
	v_mul_f32_e32 v153, v184, v184
	v_mul_f32_e32 v154, v186, v186
	v_rcp_f32_e32 v132, v132
	v_add_f32_e32 v133, 1.0, v133
	v_fmac_f32_e32 v153, v155, v155
	v_fmac_f32_e32 v154, v185, v185
	v_rcp_f32_e32 v133, v133
	v_add_f32_e32 v153, v153, v154
	v_add_f32_e32 v152, v152, v153
	s_waitcnt vmcnt(10)
; __device__ __forceinline__ unsigned cvt_pk_bf16(float lo, float hi) { unsigned r; asm volatile("v_cvt_pk_bf16_f32 %0, %1, %2" : "=v"(r) : "v"(lo), "v"(hi)); return r; }
; __device__ __forceinline__ float bflo(unsigned w) { return __uint_as_float(w << 16); }
; __device__ __forceinline__ float bfhi(unsigned w) { return __uint_as_float(w & 0xffff0000u); }
; __device__ __forceinline__ float sigmoidf_(float x) { return __builtin_amdgcn_rcpf(1.0f + __expf(-x)); }
;     __device__ __forceinline__ void operator()(f32x4 (&acc)[2][2][4][2], const Unit& u, int wr, int wc, int fr, int fq) const {
;     ...
;                 for (int bj = 0; bj < 2; ++bj) { const f32x4 z0 = acc[ai][bj][m][0] * rstd[m], z1 = acc[ai][bj][m][1] * rstd[m]; const u32x4 h2 = hw[m][bj], p2 = pw[m][bj]; f32x4 v0, v1;
;                     v0[0] = bflo(h2.x) + sigmoidf_(z0[0]) * bflo(p2.x); v0[1] = bfhi(h2.x) + sigmoidf_(z0[1]) * bfhi(p2.x);
;                     v0[2] = bflo(h2.y) + sigmoidf_(z0[2]) * bflo(p2.y); v0[3] = bfhi(h2.y) + sigmoidf_(z0[3]) * bfhi(p2.y);
;                     v1[0] = bflo(h2.z) + sigmoidf_(z1[0]) * bflo(p2.z); v1[1] = bfhi(h2.z) + sigmoidf_(z1[1]) * bfhi(p2.z);
;                     v1[2] = bflo(h2.w) + sigmoidf_(z1[2]) * bflo(p2.w); v1[3] = bfhi(h2.w) + sigmoidf_(z1[3]) * bfhi(p2.w);
;                     u32x4 w; w.x = cvt_pk_bf16(v0[0], v0[1]); w.y = cvt_pk_bf16(v0[2], v0[3]); w.z = cvt_pk_bf16(v1[0], v1[1]); w.w = cvt_pk_bf16(v1[2], v1[3]);
;                     *(u32x4*)(out + off + bj * HALF) = w;
;                     s += ((v0[0] * v0[0] + v0[1] * v0[1]) + (v0[2] * v0[2] + v0[3] * v0[3])) + ((v1[0] * v1[0] + v1[1] * v1[1]) + (v1[2] * v1[2] + v1[3] * v1[3])); }
;                 s += __shfl_xor(s, 16); s += __shfl_xor(s, 32);
;                 if (fq == 0) ssq[(size_t)row * 32 + u.pn * 4 + wc] = s; }
	v_lshlrev_b32_e32 v153, 16, v180
	v_lshlrev_b32_e32 v154, 16, v176
	v_pk_mul_f32 v[134:135], v[134:135], v[244:245] op_sel_hi:[1,0]
	v_fmac_f32_e32 v153, v132, v154
	v_and_b32_e32 v132, 0xffff0000, v180
	v_and_b32_e32 v154, 0xffff0000, v176
	v_fmac_f32_e32 v132, v133, v154
	v_mul_f32_e32 v133, 0xbfb8aa3b, v134
	v_pk_mul_f32 v[128:129], v[128:129], v[244:245] op_sel_hi:[1,0]
	v_exp_f32_e32 v133, v133
	v_mul_f32_e32 v134, 0xbfb8aa3b, v135
	v_exp_f32_e32 v134, v134
	v_mul_f32_e32 v128, 0xbfb8aa3b, v128
	v_exp_f32_e32 v128, v128
	v_mul_f32_e32 v129, 0xbfb8aa3b, v129
	v_exp_f32_e32 v129, v129
	v_add_f32_e32 v133, 1.0, v133
	v_rcp_f32_e32 v133, v133
	v_add_f32_e32 v134, 1.0, v134
	v_rcp_f32_e32 v134, v134
	v_add_f32_e32 v128, 1.0, v128
	v_rcp_f32_e32 v128, v128
	v_add_f32_e32 v129, 1.0, v129
	v_lshlrev_b32_e32 v154, 16, v181
	v_lshlrev_b32_e32 v135, 16, v177
	v_rcp_f32_e32 v129, v129
	v_fmac_f32_e32 v154, v133, v135
	v_and_b32_e32 v133, 0xffff0000, v181
	v_and_b32_e32 v135, 0xffff0000, v177
	v_cvt_pk_bf16_f32 v142, v155, v184
	v_fmac_f32_e32 v133, v134, v135
	v_lshlrev_b32_e32 v155, 16, v182
	v_lshlrev_b32_e32 v134, 16, v178
	v_pk_mul_f32 v[130:131], v[130:131], v[244:245] op_sel_hi:[1,0]
	v_fmac_f32_e32 v155, v128, v134
	v_and_b32_e32 v176, 0xffff0000, v182
	v_and_b32_e32 v128, 0xffff0000, v178
	v_fmac_f32_e32 v176, v129, v128
	v_mul_f32_e32 v128, 0xbfb8aa3b, v130
	v_exp_f32_e32 v128, v128
	v_mul_f32_e32 v129, 0xbfb8aa3b, v131
	v_exp_f32_e32 v129, v129
	v_lshlrev_b32_e32 v177, 16, v183
	v_add_f32_e32 v128, 1.0, v128
	v_rcp_f32_e32 v128, v128
	v_add_f32_e32 v129, 1.0, v129
	v_rcp_f32_e32 v129, v129
	v_lshlrev_b32_e32 v130, 16, v179
	v_fmac_f32_e32 v177, v128, v130
	v_and_b32_e32 v178, 0xffff0000, v183
	v_and_b32_e32 v128, 0xffff0000, v179
	v_fmac_f32_e32 v178, v129, v128
	v_mul_f32_e32 v128, v132, v132
	v_mul_f32_e32 v129, v133, v133
	v_fmac_f32_e32 v128, v153, v153
	v_fmac_f32_e32 v129, v154, v154
	v_add_f32_e32 v128, v128, v129
	v_mul_f32_e32 v129, v176, v176
	v_mul_f32_e32 v130, v178, v178
	v_fmac_f32_e32 v129, v155, v155
	v_fmac_f32_e32 v130, v177, v177
	v_add_f32_e32 v129, v129, v130
	v_add_f32_e32 v128, v128, v129
	v_add_f32_e32 v131, v152, v128
	ds_bpermute_b32 v253, v250, v233
	ds_bpermute_b32 v252, v250, v232
	ds_bpermute_b32 v152, v250, v131
	v_lshl_add_u64 v[128:129], s[0:1], 0, v[238:239]
	v_lshl_add_u64 v[134:135], v[128:129], 0, v[240:241]
	v_cmp_gt_f32_e32 vcc, s52, v242
	s_waitcnt lgkmcnt(1)
	v_pk_add_f32 v[230:231], v[232:233], v[252:253]
	s_waitcnt lgkmcnt(0)
	v_add_f32_e32 v128, v131, v152
	ds_bpermute_b32 v233, v249, v231
	ds_bpermute_b32 v232, v249, v230
	ds_bpermute_b32 v129, v249, v128
	v_cvt_pk_bf16_f32 v143, v185, v186
	global_store_dwordx4 v[134:135], v[140:143], off
	v_cvt_pk_bf16_f32 v130, v153, v132
	v_cvt_pk_bf16_f32 v131, v154, v133
	v_cvt_pk_bf16_f32 v132, v155, v176
	v_cvt_pk_bf16_f32 v133, v177, v178
	global_store_dwordx4 v[134:135], v[130:133], off offset:256
	s_and_saveexec_b64 s[2:3], s[36:37]
	s_cbranch_execz .LBB0_1009
	v_lshl_add_u64 v[130:131], s[28:29], 0, v[236:237]
	v_lshl_add_u64 v[130:131], s[48:49], 2, v[130:131]
	s_lshl_b32 s4, s27, 2
	v_lshl_add_u64 v[130:131], v[130:131], 0, s[4:5]
	s_waitcnt lgkmcnt(0)
	v_add_f32_e32 v128, v128, v129
	global_store_dword v[130:131], v128, off
